# c19 + fused-LN row statistics: lane^16 / lane^32 butterflies through v_permlane16_swap / v_permlane32_swap instead of ds_bpermute round trips (96 sites)
# speedup vs baseline: 1.0052x; 1.0018x over previous
;     __device__ __forceinline__ void fused(AccT& acc, const Unit& u, int wr, int wc, int fr_in, int fq_in, LAS unsigned char* lds, int wid, int lane_in) const {
;     ...
;         const int col0 = u.pn * BM + wc * 32 + 8 * fq;
;         {
;             u32x4 xr[2][4][2];
; #pragma unroll
;             for (int ai = 0; ai < 2; ++ai)
; #pragma unroll
;                 for (int m = 0; m < 4; ++m) { const int rowi = u.pm * BM + ai * HALF + wr * 64 + m * 16 + fr;
; #pragma unroll
;                     for (int bj = 0; bj < 2; ++bj) xr[ai][m][bj] = *(const u32x4*)((const char*)XinB + blk_off(rowi, col0 + bj * HALF, D, false)); }
.LBB0_1051:
	s_lshl_b32 s0, s49, 5
	s_lshl_b32 s1, s16, 8
	v_and_b32_e32 v218, 63, v146
	v_bfe_u32 v215, v146, 4, 2
	s_or_b32 s0, s1, s0
	s_waitcnt vmcnt(0)
	s_barrier
	s_lshl_b32 s24, s48, 8
	v_lshl_add_u32 v214, v215, 3, s0
	v_add_u32_e32 v217, s71, v1
	v_ashrrev_i32_e32 v132, 6, v214
	v_add_u32_e32 v140, s24, v217
	v_ashrrev_i32_e32 v133, 31, v132
	v_lshlrev_b32_e32 v130, 1, v214
	v_lshlrev_b64 v[208:209], 14, v[132:133]
	v_ashrrev_i32_e32 v132, 7, v140
	v_bfe_u32 v193, v214, 5, 1
	v_and_b32_e32 v216, 48, v130
	v_ashrrev_i32_e32 v133, 31, v132
	v_lshrrev_b32_e32 v130, 3, v217
	v_lshlrev_b64 v[212:213], 19, v[132:133]
	v_and_or_b32 v130, v130, 14, v193
	v_lshlrev_b32_e32 v132, 6, v217
	v_lshlrev_b32_e32 v133, 2, v217
	v_readlane_b32 s0, v255, 9
	v_add_u32_e32 v136, 0x80, v214
	v_and_or_b32 v132, v132, s84, v216
	v_lshlrev_b32_e32 v130, 10, v130
	v_and_b32_e32 v133, 32, v133
	v_readlane_b32 s1, v255, 10
	v_ashrrev_i32_e32 v136, 6, v136
	v_bitop3_b32 v130, v132, v130, v133 bitop3:0xde
	v_lshl_add_u64 v[132:133], s[0:1], 0, v[212:213]
	v_ashrrev_i32_e32 v137, 31, v136
	v_lshl_add_u64 v[132:133], v[132:133], 0, v[130:131]
	v_lshlrev_b64 v[206:207], 14, v[136:137]
	v_lshl_add_u64 v[134:135], v[132:133], 0, v[208:209]
	v_lshl_add_u64 v[136:137], v[132:133], 0, v[206:207]
	v_add_u32_e32 v138, 16, v140
	global_load_dwordx4 v[132:135], v[134:135], off
	s_nop 0
	global_load_dwordx4 v[194:197], v[136:137], off
	v_ashrrev_i32_e32 v136, 7, v138
	v_lshrrev_b32_e32 v139, 3, v138
	v_ashrrev_i32_e32 v137, 31, v136
	v_and_or_b32 v139, v139, 14, v193
	v_lshlrev_b32_e32 v141, 6, v138
	v_lshlrev_b32_e32 v138, 2, v138
	v_lshlrev_b64 v[136:137], 19, v[136:137]
	v_and_or_b32 v141, v141, s84, v216
	v_lshlrev_b32_e32 v139, 10, v139
	v_and_b32_e32 v138, 32, v138
	v_bitop3_b32 v138, v141, v139, v138 bitop3:0xde
	v_mov_b32_e32 v139, v131
	v_lshl_add_u64 v[136:137], s[0:1], 0, v[136:137]
	v_lshl_add_u64 v[136:137], v[136:137], 0, v[138:139]
	v_lshl_add_u64 v[138:139], v[136:137], 0, v[208:209]
	v_lshl_add_u64 v[136:137], v[136:137], 0, v[206:207]
	global_load_dwordx4 v[220:223], v[138:139], off
	global_load_dwordx4 v[188:191], v[136:137], off
	v_add_u32_e32 v138, 32, v140
	v_ashrrev_i32_e32 v136, 7, v138
	v_lshrrev_b32_e32 v139, 3, v138
	v_ashrrev_i32_e32 v137, 31, v136
	v_and_or_b32 v139, v139, 14, v193
	v_lshlrev_b32_e32 v141, 6, v138
	v_lshlrev_b32_e32 v138, 2, v138
	v_lshlrev_b64 v[136:137], 19, v[136:137]
	v_and_or_b32 v141, v141, s84, v216
	v_lshlrev_b32_e32 v139, 10, v139
	v_and_b32_e32 v138, 32, v138
	v_bitop3_b32 v138, v141, v139, v138 bitop3:0xde
	v_mov_b32_e32 v139, v131
	v_lshl_add_u64 v[136:137], s[0:1], 0, v[136:137]
	v_lshl_add_u64 v[136:137], v[136:137], 0, v[138:139]
	v_lshl_add_u64 v[138:139], v[136:137], 0, v[208:209]
	v_lshl_add_u64 v[136:137], v[136:137], 0, v[206:207]
	global_load_dwordx4 v[184:187], v[138:139], off
	global_load_dwordx4 v[180:183], v[136:137], off
	v_add_u32_e32 v138, 48, v140
	v_ashrrev_i32_e32 v136, 7, v138
	v_lshrrev_b32_e32 v139, 3, v138
	v_ashrrev_i32_e32 v137, 31, v136
	v_and_or_b32 v139, v139, 14, v193
	v_lshlrev_b32_e32 v141, 6, v138
	v_lshlrev_b32_e32 v138, 2, v138
	v_lshlrev_b64 v[136:137], 19, v[136:137]
	v_and_or_b32 v141, v141, s84, v216
	v_lshlrev_b32_e32 v139, 10, v139
	v_and_b32_e32 v138, 32, v138
	v_bitop3_b32 v138, v141, v139, v138 bitop3:0xde
	v_mov_b32_e32 v139, v131
	v_lshl_add_u64 v[136:137], s[0:1], 0, v[136:137]
	v_lshl_add_u64 v[136:137], v[136:137], 0, v[138:139]
	v_lshl_add_u64 v[138:139], v[136:137], 0, v[208:209]
	v_lshl_add_u64 v[136:137], v[136:137], 0, v[206:207]
	global_load_dwordx4 v[176:179], v[138:139], off
	global_load_dwordx4 v[172:175], v[136:137], off
	v_add_u32_e32 v136, 0x80, v140
	v_ashrrev_i32_e32 v136, 7, v136
	v_ashrrev_i32_e32 v137, 31, v136
	v_lshlrev_b64 v[210:211], 19, v[136:137]
	v_lshl_add_u64 v[136:137], s[0:1], 0, v[210:211]
	v_lshl_add_u64 v[136:137], v[136:137], 0, v[130:131]
	v_lshl_add_u64 v[138:139], v[136:137], 0, v[208:209]
	v_lshl_add_u64 v[136:137], v[136:137], 0, v[206:207]
	global_load_dwordx4 v[168:171], v[138:139], off
	global_load_dwordx4 v[164:167], v[136:137], off
	v_add_u32_e32 v138, 0x90, v140
	v_ashrrev_i32_e32 v136, 7, v138
	v_lshrrev_b32_e32 v139, 3, v138
	v_ashrrev_i32_e32 v137, 31, v136
	v_and_or_b32 v139, v139, 14, v193
	v_lshlrev_b32_e32 v141, 6, v138
	v_lshlrev_b32_e32 v138, 2, v138
	v_lshlrev_b64 v[136:137], 19, v[136:137]
	v_and_or_b32 v141, v141, s84, v216
	v_lshlrev_b32_e32 v139, 10, v139
	v_and_b32_e32 v138, 32, v138
	v_bitop3_b32 v138, v141, v139, v138 bitop3:0xde
	v_mov_b32_e32 v139, v131
	v_lshl_add_u64 v[136:137], s[0:1], 0, v[136:137]
	v_lshl_add_u64 v[136:137], v[136:137], 0, v[138:139]
	v_lshl_add_u64 v[138:139], v[136:137], 0, v[208:209]
	v_lshl_add_u64 v[136:137], v[136:137], 0, v[206:207]
	global_load_dwordx4 v[160:163], v[138:139], off
	global_load_dwordx4 v[156:159], v[136:137], off
	v_add_u32_e32 v138, 0xa0, v140
	v_ashrrev_i32_e32 v136, 7, v138
	v_lshrrev_b32_e32 v139, 3, v138
	v_ashrrev_i32_e32 v137, 31, v136
	v_and_or_b32 v139, v139, 14, v193
	v_lshlrev_b32_e32 v141, 6, v138
	v_lshlrev_b32_e32 v138, 2, v138
	v_lshlrev_b64 v[136:137], 19, v[136:137]
	v_and_or_b32 v141, v141, s84, v216
	v_lshlrev_b32_e32 v139, 10, v139
	v_and_b32_e32 v138, 32, v138
	v_bitop3_b32 v138, v141, v139, v138 bitop3:0xde
	v_mov_b32_e32 v139, v131
	v_lshl_add_u64 v[136:137], s[0:1], 0, v[136:137]
	v_lshl_add_u64 v[136:137], v[136:137], 0, v[138:139]
	v_lshl_add_u64 v[138:139], v[136:137], 0, v[208:209]
	v_lshl_add_u64 v[136:137], v[136:137], 0, v[206:207]
	global_load_dwordx4 v[152:155], v[138:139], off
	global_load_dwordx4 v[148:151], v[136:137], off
	v_add_u32_e32 v138, 0xb0, v140
	v_ashrrev_i32_e32 v136, 7, v138
	v_lshrrev_b32_e32 v139, 3, v138
	v_ashrrev_i32_e32 v137, 31, v136
	v_and_or_b32 v139, v139, 14, v193
	v_lshlrev_b32_e32 v140, 6, v138
	v_lshlrev_b32_e32 v138, 2, v138
	v_lshlrev_b64 v[136:137], 19, v[136:137]
	v_and_or_b32 v140, v140, s84, v216
	v_lshlrev_b32_e32 v139, 10, v139
	v_and_b32_e32 v138, 32, v138
	v_bitop3_b32 v138, v140, v139, v138 bitop3:0xde
	v_mov_b32_e32 v139, v131
	v_lshl_add_u64 v[136:137], s[0:1], 0, v[136:137]
	v_lshl_add_u64 v[136:137], v[136:137], 0, v[138:139]
	v_lshl_add_u64 v[138:139], v[136:137], 0, v[208:209]
	v_lshl_add_u64 v[136:137], v[136:137], 0, v[206:207]
	global_load_dwordx4 v[144:147], v[138:139], off
	global_load_dwordx4 v[140:143], v[136:137], off
	s_waitcnt vmcnt(0)
; __device__ __forceinline__ float bflo(unsigned w) { return __uint_as_float(w << 16); }
; __device__ __forceinline__ float bfhi(unsigned w) { return __uint_as_float(w & 0xffff0000u); }
;     __device__ __forceinline__ void fused(AccT& acc, const Unit& u, int wr, int wc, int fr_in, int fq_in, LAS unsigned char* lds, int wid, int lane_in) const {
;     ...
; #pragma unroll
;             for (int ai = 0; ai < 2; ++ai)
; #pragma unroll
;                 for (int m = 0; m < 4; ++m)
; #pragma unroll
;                     for (int bj = 0; bj < 2; ++bj) { const u32x4 w = xr[ai][m][bj];
;                         acc[ai][bj][m][0] += (f32x4){bflo(w.x), bfhi(w.x), bflo(w.y), bfhi(w.y)} * alpha; acc[ai][bj][m][1] += (f32x4){bflo(w.z), bfhi(w.z), bflo(w.w), bfhi(w.w)} * alpha;
;                         asm volatile("" : "+v"(acc[ai][bj][m][0]), "+v"(acc[ai][bj][m][1])); }
	v_lshlrev_b32_e32 v136, 16, v132
	v_and_b32_e32 v137, 0xffff0000, v132
	v_lshlrev_b32_e32 v132, 16, v133
	v_and_b32_e32 v133, 0xffff0000, v133
	s_mov_b32 s0, 0x3fd744fd
	v_pk_fma_f32 v[138:139], v[132:133], s[0:1], v[128:129] op_sel_hi:[1,0,1]
	v_pk_fma_f32 v[136:137], v[136:137], s[0:1], v[126:127] op_sel_hi:[1,0,1]
	v_lshlrev_b32_e32 v126, 16, v134
	v_and_b32_e32 v127, 0xffff0000, v134
	v_lshlrev_b32_e32 v128, 16, v135
	v_and_b32_e32 v129, 0xffff0000, v135
	v_pk_fma_f32 v[134:135], v[128:129], s[0:1], v[124:125] op_sel_hi:[1,0,1]
	v_pk_fma_f32 v[132:133], v[126:127], s[0:1], v[122:123] op_sel_hi:[1,0,1]
	v_lshlrev_b32_e32 v122, 16, v194
	v_and_b32_e32 v123, 0xffff0000, v194
	v_lshlrev_b32_e32 v124, 16, v195
	v_and_b32_e32 v125, 0xffff0000, v195
	v_pk_fma_f32 v[128:129], v[124:125], s[0:1], v[116:117] op_sel_hi:[1,0,1]
	v_pk_fma_f32 v[126:127], v[122:123], s[0:1], v[114:115] op_sel_hi:[1,0,1]
	v_lshlrev_b32_e32 v114, 16, v196
	v_and_b32_e32 v115, 0xffff0000, v196
	v_lshlrev_b32_e32 v116, 16, v197
	v_and_b32_e32 v117, 0xffff0000, v197
	v_pk_fma_f32 v[124:125], v[116:117], s[0:1], v[108:109] op_sel_hi:[1,0,1]
	v_pk_fma_f32 v[122:123], v[114:115], s[0:1], v[106:107] op_sel_hi:[1,0,1]
	v_lshlrev_b32_e32 v114, 16, v222
	v_and_b32_e32 v115, 0xffff0000, v222
	v_lshlrev_b32_e32 v116, 16, v223
	v_and_b32_e32 v117, 0xffff0000, v223
	v_pk_fma_f32 v[112:113], v[116:117], s[0:1], v[112:113] op_sel_hi:[1,0,1]
	v_pk_fma_f32 v[110:111], v[114:115], s[0:1], v[110:111] op_sel_hi:[1,0,1]
	v_lshlrev_b32_e32 v114, 16, v188
	v_and_b32_e32 v115, 0xffff0000, v188
	v_lshlrev_b32_e32 v116, 16, v189
	v_and_b32_e32 v117, 0xffff0000, v189
	v_lshlrev_b32_e32 v106, 16, v220
	v_and_b32_e32 v107, 0xffff0000, v220
	v_lshlrev_b32_e32 v108, 16, v221
	v_and_b32_e32 v109, 0xffff0000, v221
	v_pk_fma_f32 v[116:117], v[116:117], s[0:1], v[100:101] op_sel_hi:[1,0,1]
	v_pk_fma_f32 v[114:115], v[114:115], s[0:1], v[98:99] op_sel_hi:[1,0,1]
	v_lshlrev_b32_e32 v98, 16, v190
	v_and_b32_e32 v99, 0xffff0000, v190
	v_lshlrev_b32_e32 v100, 16, v191
	v_and_b32_e32 v101, 0xffff0000, v191
	v_pk_fma_f32 v[108:109], v[108:109], s[0:1], v[120:121] op_sel_hi:[1,0,1]
	v_pk_fma_f32 v[106:107], v[106:107], s[0:1], v[118:119] op_sel_hi:[1,0,1]
	v_pk_fma_f32 v[120:121], v[100:101], s[0:1], v[92:93] op_sel_hi:[1,0,1]
	v_pk_fma_f32 v[118:119], v[98:99], s[0:1], v[90:91] op_sel_hi:[1,0,1]
	v_lshlrev_b32_e32 v98, 16, v186
	v_and_b32_e32 v99, 0xffff0000, v186
	v_lshlrev_b32_e32 v100, 16, v187
	v_and_b32_e32 v101, 0xffff0000, v187
	v_pk_fma_f32 v[96:97], v[100:101], s[0:1], v[96:97] op_sel_hi:[1,0,1]
	v_pk_fma_f32 v[94:95], v[98:99], s[0:1], v[94:95] op_sel_hi:[1,0,1]
	v_lshlrev_b32_e32 v98, 16, v180
	v_and_b32_e32 v99, 0xffff0000, v180
	v_lshlrev_b32_e32 v100, 16, v181
	v_and_b32_e32 v101, 0xffff0000, v181
	v_lshlrev_b32_e32 v90, 16, v184
	v_and_b32_e32 v91, 0xffff0000, v184
	v_lshlrev_b32_e32 v92, 16, v185
	v_and_b32_e32 v93, 0xffff0000, v185
	v_pk_fma_f32 v[100:101], v[100:101], s[0:1], v[84:85] op_sel_hi:[1,0,1]
	v_pk_fma_f32 v[98:99], v[98:99], s[0:1], v[82:83] op_sel_hi:[1,0,1]
	v_lshlrev_b32_e32 v82, 16, v182
	v_and_b32_e32 v83, 0xffff0000, v182
	v_lshlrev_b32_e32 v84, 16, v183
	v_and_b32_e32 v85, 0xffff0000, v183
	v_pk_fma_f32 v[92:93], v[92:93], s[0:1], v[104:105] op_sel_hi:[1,0,1]
	v_pk_fma_f32 v[90:91], v[90:91], s[0:1], v[102:103] op_sel_hi:[1,0,1]
	v_pk_fma_f32 v[104:105], v[84:85], s[0:1], v[76:77] op_sel_hi:[1,0,1]
	v_pk_fma_f32 v[102:103], v[82:83], s[0:1], v[74:75] op_sel_hi:[1,0,1]
	v_lshlrev_b32_e32 v82, 16, v178
	v_and_b32_e32 v83, 0xffff0000, v178
	v_lshlrev_b32_e32 v84, 16, v179
	v_and_b32_e32 v85, 0xffff0000, v179
	v_pk_fma_f32 v[80:81], v[84:85], s[0:1], v[80:81] op_sel_hi:[1,0,1]
	v_pk_fma_f32 v[78:79], v[82:83], s[0:1], v[78:79] op_sel_hi:[1,0,1]
	v_lshlrev_b32_e32 v82, 16, v172
	v_and_b32_e32 v83, 0xffff0000, v172
	v_lshlrev_b32_e32 v84, 16, v173
	v_and_b32_e32 v85, 0xffff0000, v173
	v_pk_fma_f32 v[72:73], v[84:85], s[0:1], v[72:73] op_sel_hi:[1,0,1]
	v_pk_fma_f32 v[70:71], v[82:83], s[0:1], v[70:71] op_sel_hi:[1,0,1]
	v_lshlrev_b32_e32 v82, 16, v174
	v_and_b32_e32 v83, 0xffff0000, v174
	v_lshlrev_b32_e32 v84, 16, v175
	v_and_b32_e32 v85, 0xffff0000, v175
	v_pk_fma_f32 v[68:69], v[84:85], s[0:1], v[68:69] op_sel_hi:[1,0,1]
	v_pk_fma_f32 v[66:67], v[82:83], s[0:1], v[66:67] op_sel_hi:[1,0,1]
	v_lshlrev_b32_e32 v82, 16, v168
	v_and_b32_e32 v83, 0xffff0000, v168
	v_lshlrev_b32_e32 v84, 16, v169
	v_and_b32_e32 v85, 0xffff0000, v169
	v_pk_fma_f32 v[64:65], v[84:85], s[0:1], v[64:65] op_sel_hi:[1,0,1]
	v_pk_fma_f32 v[62:63], v[82:83], s[0:1], v[62:63] op_sel_hi:[1,0,1]
	v_lshlrev_b32_e32 v82, 16, v170
	v_and_b32_e32 v83, 0xffff0000, v170
	v_lshlrev_b32_e32 v84, 16, v171
	v_and_b32_e32 v85, 0xffff0000, v171
	v_pk_fma_f32 v[60:61], v[84:85], s[0:1], v[60:61] op_sel_hi:[1,0,1]
	v_pk_fma_f32 v[58:59], v[82:83], s[0:1], v[58:59] op_sel_hi:[1,0,1]
	v_lshlrev_b32_e32 v82, 16, v164
	v_and_b32_e32 v83, 0xffff0000, v164
	v_lshlrev_b32_e32 v84, 16, v165
	v_and_b32_e32 v85, 0xffff0000, v165
	v_lshlrev_b32_e32 v74, 16, v176
	v_and_b32_e32 v75, 0xffff0000, v176
	v_lshlrev_b32_e32 v76, 16, v177
	v_and_b32_e32 v77, 0xffff0000, v177
	v_pk_fma_f32 v[84:85], v[84:85], s[0:1], v[52:53] op_sel_hi:[1,0,1]
	v_pk_fma_f32 v[82:83], v[82:83], s[0:1], v[50:51] op_sel_hi:[1,0,1]
	v_lshlrev_b32_e32 v50, 16, v166
	v_and_b32_e32 v51, 0xffff0000, v166
	v_lshlrev_b32_e32 v52, 16, v167
	v_and_b32_e32 v53, 0xffff0000, v167
	v_pk_fma_f32 v[76:77], v[76:77], s[0:1], v[88:89] op_sel_hi:[1,0,1]
	v_pk_fma_f32 v[74:75], v[74:75], s[0:1], v[86:87] op_sel_hi:[1,0,1]
	v_pk_fma_f32 v[88:89], v[52:53], s[0:1], v[44:45] op_sel_hi:[1,0,1]
; __device__ __forceinline__ float bflo(unsigned w) { return __uint_as_float(w << 16); }
; __device__ __forceinline__ float bfhi(unsigned w) { return __uint_as_float(w & 0xffff0000u); }
; __device__ __forceinline__ float shfl_lane(float v, int srclane) { return __int_as_float(__builtin_amdgcn_ds_bpermute(srclane << 2, __float_as_int(v))); }
;     __device__ __forceinline__ void fused(AccT& acc, const Unit& u, int wr, int wc, int fr_in, int fq_in, LAS unsigned char* lds, int wid, int lane_in) const {
;     ...
;                         acc[ai][bj][m][0] += (f32x4){bflo(w.x), bfhi(w.x), bflo(w.y), bfhi(w.y)} * alpha; acc[ai][bj][m][1] += (f32x4){bflo(w.z), bfhi(w.z), bflo(w.w), bfhi(w.w)} * alpha;
;                         asm volatile("" : "+v"(acc[ai][bj][m][0]), "+v"(acc[ai][bj][m][1])); }
;             asm volatile("" ::: "memory");
;         }
; #pragma unroll
;         for (int ai = 0; ai < 2; ++ai)
; #pragma unroll
;             for (int m = 0; m < 4; ++m) {
;                 float s = 0.f;
; #pragma unroll
;                 for (int bj = 0; bj < 2; ++bj)
; #pragma unroll
;                     for (int n = 0; n < 2; ++n) { const f32x4 x = acc[ai][bj][m][n]; s += (x[0] + x[1]) + (x[2] + x[3]); }
;                 s += shfl_lane(s, lane ^ 16); s += shfl_lane(s, lane ^ 32);
;                 const float mw = s * (1.0f / 64.0f); float q = 0.f;
; #pragma unroll
;                 for (int bj = 0; bj < 2; ++bj)
; #pragma unroll
;                     for (int n = 0; n < 2; ++n) { const f32x4 d = acc[ai][bj][m][n] - mw; q += (d[0] * d[0] + d[1] * d[1]) + (d[2] * d[2] + d[3] * d[3]); }
;                 q += shfl_lane(q, lane ^ 16); q += shfl_lane(q, lane ^ 32);
;                 if (fq == 0) P[(ai * HALF + wr * 64 + m * 16 + fr) * 4 + wc] = (f32x2){mw, q};
	v_pk_fma_f32 v[86:87], v[50:51], s[0:1], v[42:43] op_sel_hi:[1,0,1]
	v_lshlrev_b32_e32 v50, 16, v162
	v_and_b32_e32 v51, 0xffff0000, v162
	v_lshlrev_b32_e32 v52, 16, v163
	v_and_b32_e32 v53, 0xffff0000, v163
	v_pk_fma_f32 v[48:49], v[52:53], s[0:1], v[48:49] op_sel_hi:[1,0,1]
	v_pk_fma_f32 v[46:47], v[50:51], s[0:1], v[46:47] op_sel_hi:[1,0,1]
	v_lshlrev_b32_e32 v50, 16, v156
	v_and_b32_e32 v51, 0xffff0000, v156
	v_lshlrev_b32_e32 v52, 16, v157
	v_and_b32_e32 v53, 0xffff0000, v157
	v_lshlrev_b32_e32 v42, 16, v160
	v_and_b32_e32 v43, 0xffff0000, v160
	v_lshlrev_b32_e32 v44, 16, v161
	v_and_b32_e32 v45, 0xffff0000, v161
	v_pk_fma_f32 v[52:53], v[52:53], s[0:1], v[36:37] op_sel_hi:[1,0,1]
	v_pk_fma_f32 v[50:51], v[50:51], s[0:1], v[34:35] op_sel_hi:[1,0,1]
	v_lshlrev_b32_e32 v34, 16, v158
	v_and_b32_e32 v35, 0xffff0000, v158
	v_lshlrev_b32_e32 v36, 16, v159
	v_and_b32_e32 v37, 0xffff0000, v159
	v_pk_fma_f32 v[44:45], v[44:45], s[0:1], v[56:57] op_sel_hi:[1,0,1]
	v_pk_fma_f32 v[42:43], v[42:43], s[0:1], v[54:55] op_sel_hi:[1,0,1]
	v_pk_fma_f32 v[56:57], v[36:37], s[0:1], v[28:29] op_sel_hi:[1,0,1]
	v_pk_fma_f32 v[54:55], v[34:35], s[0:1], v[26:27] op_sel_hi:[1,0,1]
	v_lshlrev_b32_e32 v34, 16, v154
	v_and_b32_e32 v35, 0xffff0000, v154
	v_lshlrev_b32_e32 v36, 16, v155
	v_and_b32_e32 v37, 0xffff0000, v155
	v_lshlrev_b32_e32 v26, 16, v152
	v_and_b32_e32 v27, 0xffff0000, v152
	v_lshlrev_b32_e32 v28, 16, v153
	v_and_b32_e32 v29, 0xffff0000, v153
	v_pk_fma_f32 v[32:33], v[36:37], s[0:1], v[32:33] op_sel_hi:[1,0,1]
	v_pk_fma_f32 v[30:31], v[34:35], s[0:1], v[30:31] op_sel_hi:[1,0,1]
	v_lshlrev_b32_e32 v34, 16, v148
	v_and_b32_e32 v35, 0xffff0000, v148
	v_lshlrev_b32_e32 v36, 16, v149
	v_and_b32_e32 v37, 0xffff0000, v149
	v_pk_fma_f32 v[28:29], v[28:29], s[0:1], v[40:41] op_sel_hi:[1,0,1]
	v_pk_fma_f32 v[26:27], v[26:27], s[0:1], v[38:39] op_sel_hi:[1,0,1]
	v_pk_fma_f32 v[20:21], v[36:37], s[0:1], v[20:21] op_sel_hi:[1,0,1]
	v_pk_fma_f32 v[18:19], v[34:35], s[0:1], v[18:19] op_sel_hi:[1,0,1]
	v_lshlrev_b32_e32 v34, 16, v150
	v_and_b32_e32 v35, 0xffff0000, v150
	v_lshlrev_b32_e32 v36, 16, v151
	v_and_b32_e32 v37, 0xffff0000, v151
	v_mov_b32_e32 v38, v137
	v_mov_b32_e32 v39, v138
	v_mov_b32_e32 v40, v136
	v_mov_b32_e32 v41, v139
	v_pk_fma_f32 v[36:37], v[36:37], s[0:1], v[12:13] op_sel_hi:[1,0,1]
	v_pk_fma_f32 v[34:35], v[34:35], s[0:1], v[10:11] op_sel_hi:[1,0,1]
	v_lshlrev_b32_e32 v10, 16, v144
	v_and_b32_e32 v11, 0xffff0000, v144
	v_lshlrev_b32_e32 v12, 16, v145
	v_and_b32_e32 v13, 0xffff0000, v145
	v_pk_add_f32 v[38:39], v[38:39], v[40:41]
	v_mov_b32_e32 v40, v133
	v_mov_b32_e32 v41, v134
	v_mov_b32_e32 v144, v132
	v_mov_b32_e32 v145, v135
	v_pk_add_f32 v[40:41], v[40:41], v[144:145]
	v_add_f32_e32 v38, v38, v39
	v_pk_add_f32 v[40:41], v[40:41], v[40:41] op_sel_hi:[0,1]
	v_pk_fma_f32 v[12:13], v[12:13], s[0:1], v[24:25] op_sel_hi:[1,0,1]
	v_pk_fma_f32 v[10:11], v[10:11], s[0:1], v[22:23] op_sel_hi:[1,0,1]
	v_lshlrev_b32_e32 v22, 16, v146
	v_and_b32_e32 v23, 0xffff0000, v146
	v_lshlrev_b32_e32 v24, 16, v147
	v_and_b32_e32 v25, 0xffff0000, v147
	v_add_f32_e32 v39, 0, v38
	v_add_f32_e32 v145, v126, v127
	v_add_f32_e32 v147, v128, v129
	v_mov_b32_e32 v144, v122
	v_mov_b32_e32 v146, v123
	v_mov_b32_e32 v40, v124
	v_mov_b32_e32 v38, v125
	v_pk_add_f32 v[144:145], v[144:145], v[146:147]
	v_pk_add_f32 v[38:39], v[40:41], v[38:39]
	v_pk_fma_f32 v[14:15], v[22:23], s[0:1], v[14:15] op_sel_hi:[1,0,1]
	v_lshlrev_b32_e32 v23, 2, v218
	v_pk_add_f32 v[38:39], v[144:145], v[38:39]
	v_xor_b32_e32 v22, 64, v23
	v_add_f32_e32 v40, v38, v39
	v_mov_b32_e32 v41, v40
	s_nop 1
	v_permlane16_swap_b32_e32 v40, v41
	s_nop 0
	v_xor_b32_e32 v23, 0x80, v23
	v_pk_fma_f32 v[16:17], v[24:25], s[0:1], v[16:17] op_sel_hi:[1,0,1]
	v_lshlrev_b32_e32 v24, 16, v140
	v_and_b32_e32 v25, 0xffff0000, v140
	s_waitcnt lgkmcnt(0)
	v_add_f32_e32 v41, v40, v41
	v_mov_b32_e32 v140, v41
	s_nop 1
	v_permlane32_swap_b32_e32 v41, v140
	s_nop 0
	v_pk_fma_f32 v[6:7], v[24:25], s[0:1], v[6:7] op_sel_hi:[1,0,1]
	v_lshlrev_b32_e32 v38, 16, v141
	v_and_b32_e32 v39, 0xffff0000, v141
	v_pk_fma_f32 v[8:9], v[38:39], s[0:1], v[8:9] op_sel_hi:[1,0,1]
	s_waitcnt lgkmcnt(0)
	v_add_f32_e32 v24, v41, v140
	v_fmamk_f32 v41, v24, 0xbc800000, v139
	v_fmamk_f32 v141, v24, 0xbc800000, v137
	v_fmamk_f32 v25, v24, 0xbc800000, v138
	v_fmamk_f32 v140, v24, 0xbc800000, v136
	v_mul_f32_e32 v141, v141, v141
	v_mul_f32_e32 v41, v41, v41
	v_lshlrev_b32_e32 v38, 16, v142
	v_and_b32_e32 v39, 0xffff0000, v142
	v_fmac_f32_e32 v141, v140, v140
	v_fmac_f32_e32 v41, v25, v25
	v_fmamk_f32 v140, v24, 0xbc800000, v135
	v_fmamk_f32 v142, v24, 0xbc800000, v133
	v_add_f32_e32 v25, v141, v41
	v_fmamk_f32 v41, v24, 0xbc800000, v134
	v_fmamk_f32 v141, v24, 0xbc800000, v132
	v_mul_f32_e32 v142, v142, v142
	v_mul_f32_e32 v140, v140, v140
	v_fmac_f32_e32 v142, v141, v141
	v_fmac_f32_e32 v140, v41, v41
	v_add_f32_e32 v41, v142, v140
	v_fmamk_f32 v140, v24, 0xbc800000, v129
	v_fmamk_f32 v142, v24, 0xbc800000, v127
	v_add_f32_e32 v25, v25, v41
	v_fmamk_f32 v41, v24, 0xbc800000, v128
	v_fmamk_f32 v141, v24, 0xbc800000, v126
	v_mul_f32_e32 v142, v142, v142
	v_mul_f32_e32 v140, v140, v140
	v_fmac_f32_e32 v142, v141, v141
	v_fmac_f32_e32 v140, v41, v41
	v_add_f32_e32 v41, v142, v140
	v_fmamk_f32 v140, v24, 0xbc800000, v125
	v_fmamk_f32 v142, v24, 0xbc800000, v123
	v_add_f32_e32 v25, v41, v25
	v_fmamk_f32 v41, v24, 0xbc800000, v124
	v_fmamk_f32 v141, v24, 0xbc800000, v122
	v_mul_f32_e32 v142, v142, v142
	v_mul_f32_e32 v140, v140, v140
	v_fmac_f32_e32 v142, v141, v141
	v_fmac_f32_e32 v140, v41, v41
	v_add_f32_e32 v41, v142, v140
	v_add_f32_e32 v25, v41, v25
	v_mov_b32_e32 v140, v25
	s_nop 1
	v_permlane16_swap_b32_e32 v25, v140
	s_nop 0
	v_lshlrev_b32_e32 v40, 16, v143
	v_and_b32_e32 v41, 0xffff0000, v143
	v_pk_fma_f32 v[2:3], v[38:39], s[0:1], v[2:3] op_sel_hi:[1,0,1]
	v_pk_fma_f32 v[4:5], v[40:41], s[0:1], v[4:5] op_sel_hi:[1,0,1]
	s_waitcnt lgkmcnt(0)
	v_add_f32_e32 v25, v25, v140
	v_mov_b32_e32 v38, v25
	s_nop 1
	v_permlane32_swap_b32_e32 v25, v38
	s_nop 0
	s_lshl_b32 s0, s49, 3
	v_cmp_eq_u32_e32 vcc, 0, v215
	s_add_i32 s17, s0, 0
	s_and_saveexec_b64 s[18:19], vcc
	s_cbranch_execz .LBB0_1053
	s_lshl_b32 s0, s47, 11
	s_add_i32 s0, s17, s0
	v_mul_f32_e32 v24, 0x3c800000, v24
	s_waitcnt lgkmcnt(0)
	v_add_f32_e32 v25, v25, v38
	v_lshl_add_u32 v38, v1, 5, s0
	ds_write_b64 v38, v[24:25]
; __device__ __forceinline__ float shfl_lane(float v, int srclane) { return __int_as_float(__builtin_amdgcn_ds_bpermute(srclane << 2, __float_as_int(v))); }
;     __device__ __forceinline__ void fused(AccT& acc, const Unit& u, int wr, int wc, int fr_in, int fq_in, LAS unsigned char* lds, int wid, int lane_in) const {
;     ...
; #pragma unroll
;         for (int ai = 0; ai < 2; ++ai)
; #pragma unroll
;             for (int m = 0; m < 4; ++m) {
;                 float s = 0.f;
; #pragma unroll
;                 for (int bj = 0; bj < 2; ++bj)
; #pragma unroll
;                     for (int n = 0; n < 2; ++n) { const f32x4 x = acc[ai][bj][m][n]; s += (x[0] + x[1]) + (x[2] + x[3]); }
;                 s += shfl_lane(s, lane ^ 16); s += shfl_lane(s, lane ^ 32);
;                 const float mw = s * (1.0f / 64.0f); float q = 0.f;
; #pragma unroll
;                 for (int bj = 0; bj < 2; ++bj)
; #pragma unroll
;                     for (int n = 0; n < 2; ++n) { const f32x4 d = acc[ai][bj][m][n] - mw; q += (d[0] * d[0] + d[1] * d[1]) + (d[2] * d[2] + d[3] * d[3]); }
;                 q += shfl_lane(q, lane ^ 16); q += shfl_lane(q, lane ^ 32);
;                 if (fq == 0) P[(ai * HALF + wr * 64 + m * 16 + fr) * 4 + wc] = (f32x2){mw, q};
.LBB0_1053:
	s_or_b64 exec, exec, s[18:19]
	v_mov_b32_e32 v24, v107
	v_mov_b32_e32 v25, v108
	s_waitcnt lgkmcnt(0)
	v_mov_b32_e32 v38, v106
	v_mov_b32_e32 v39, v109
	v_pk_add_f32 v[24:25], v[24:25], v[38:39]
	v_mov_b32_e32 v38, v111
	v_mov_b32_e32 v39, v112
	v_mov_b32_e32 v40, v110
	v_mov_b32_e32 v41, v113
	v_pk_add_f32 v[38:39], v[38:39], v[40:41]
	v_add_f32_e32 v24, v24, v25
	v_pk_add_f32 v[38:39], v[38:39], v[38:39] op_sel_hi:[0,1]
	v_add_f32_e32 v25, 0, v24
	v_add_f32_e32 v41, v114, v115
	v_add_f32_e32 v141, v116, v117
	v_mov_b32_e32 v40, v118
	v_mov_b32_e32 v140, v119
	v_mov_b32_e32 v38, v120
	v_mov_b32_e32 v24, v121
	v_pk_add_f32 v[40:41], v[40:41], v[140:141]
	v_pk_add_f32 v[24:25], v[38:39], v[24:25]
	s_nop 0
	v_pk_add_f32 v[24:25], v[40:41], v[24:25]
	s_nop 0
	v_add_f32_e32 v24, v24, v25
	v_mov_b32_e32 v25, v24
	s_nop 1
	v_permlane16_swap_b32_e32 v24, v25
	s_nop 0
	s_waitcnt lgkmcnt(0)
	v_add_f32_e32 v24, v24, v25
	v_mov_b32_e32 v25, v24
	s_nop 1
	v_permlane32_swap_b32_e32 v24, v25
	s_nop 0
	s_waitcnt lgkmcnt(0)
	v_add_f32_e32 v24, v24, v25
	v_fmamk_f32 v38, v24, 0xbc800000, v109
	v_fmamk_f32 v40, v24, 0xbc800000, v107
	v_fmamk_f32 v25, v24, 0xbc800000, v108
	v_fmamk_f32 v39, v24, 0xbc800000, v106
	v_mul_f32_e32 v40, v40, v40
	v_mul_f32_e32 v38, v38, v38
	v_fmac_f32_e32 v40, v39, v39
	v_fmac_f32_e32 v38, v25, v25
	v_fmamk_f32 v39, v24, 0xbc800000, v113
	v_fmamk_f32 v41, v24, 0xbc800000, v111
	v_add_f32_e32 v25, v40, v38
	v_fmamk_f32 v38, v24, 0xbc800000, v112
	v_fmamk_f32 v40, v24, 0xbc800000, v110
	v_mul_f32_e32 v41, v41, v41
	v_mul_f32_e32 v39, v39, v39
	v_fmac_f32_e32 v41, v40, v40
	v_fmac_f32_e32 v39, v38, v38
	v_add_f32_e32 v38, v41, v39
	v_fmamk_f32 v39, v24, 0xbc800000, v117
	v_fmamk_f32 v41, v24, 0xbc800000, v115
	v_add_f32_e32 v25, v25, v38
	v_fmamk_f32 v38, v24, 0xbc800000, v116
	v_fmamk_f32 v40, v24, 0xbc800000, v114
	v_mul_f32_e32 v41, v41, v41
	v_mul_f32_e32 v39, v39, v39
	v_fmac_f32_e32 v41, v40, v40
	v_fmac_f32_e32 v39, v38, v38
	v_add_f32_e32 v38, v41, v39
	v_fmamk_f32 v39, v24, 0xbc800000, v121
	v_fmamk_f32 v41, v24, 0xbc800000, v119
	v_add_f32_e32 v25, v38, v25
	v_fmamk_f32 v38, v24, 0xbc800000, v120
	v_fmamk_f32 v40, v24, 0xbc800000, v118
	v_mul_f32_e32 v41, v41, v41
	v_mul_f32_e32 v39, v39, v39
	v_fmac_f32_e32 v41, v40, v40
	v_fmac_f32_e32 v39, v38, v38
	v_add_f32_e32 v38, v41, v39
	v_add_f32_e32 v25, v38, v25
	v_mov_b32_e32 v38, v25
	s_nop 1
	v_permlane16_swap_b32_e32 v25, v38
	s_nop 0
	s_waitcnt lgkmcnt(0)
	v_add_f32_e32 v25, v25, v38
	v_mov_b32_e32 v38, v25
	s_nop 1
	v_permlane32_swap_b32_e32 v25, v38
	s_nop 0
	s_and_saveexec_b64 s[18:19], vcc
	v_readlane_b32 s26, v254, 38
	v_readlane_b32 s27, v254, 39
	s_mov_b32 s49, 0x1a000
	s_mov_b32 s50, 0x8000
	s_cbranch_execz .LBB0_1055
	s_lshl_b32 s0, s47, 11
	s_add_i32 s0, s17, s0
	v_mul_f32_e32 v24, 0x3c800000, v24
	s_waitcnt lgkmcnt(0)
	v_add_f32_e32 v25, v25, v38
	v_lshl_add_u32 v38, v1, 5, s0
	ds_write_b64 v38, v[24:25] offset:512
.LBB0_1055:
	s_or_b64 exec, exec, s[18:19]
	v_mov_b32_e32 v24, v91
	v_mov_b32_e32 v25, v92
	s_waitcnt lgkmcnt(0)
	v_mov_b32_e32 v38, v90
	v_mov_b32_e32 v39, v93
	v_pk_add_f32 v[24:25], v[24:25], v[38:39]
	v_mov_b32_e32 v38, v95
	v_mov_b32_e32 v39, v96
	v_mov_b32_e32 v40, v94
	v_mov_b32_e32 v41, v97
	v_pk_add_f32 v[38:39], v[38:39], v[40:41]
	v_add_f32_e32 v24, v24, v25
	v_pk_add_f32 v[38:39], v[38:39], v[38:39] op_sel_hi:[0,1]
	v_add_f32_e32 v25, 0, v24
	v_add_f32_e32 v41, v98, v99
	v_add_f32_e32 v141, v100, v101
	v_mov_b32_e32 v40, v102
	v_mov_b32_e32 v140, v103
	v_mov_b32_e32 v38, v104
	v_mov_b32_e32 v24, v105
	v_pk_add_f32 v[40:41], v[40:41], v[140:141]
	v_pk_add_f32 v[24:25], v[38:39], v[24:25]
	s_nop 0
	v_pk_add_f32 v[24:25], v[40:41], v[24:25]
	s_nop 0
	v_add_f32_e32 v24, v24, v25
	v_mov_b32_e32 v25, v24
	s_nop 1
	v_permlane16_swap_b32_e32 v24, v25
	s_nop 0
	s_waitcnt lgkmcnt(0)
	v_add_f32_e32 v24, v24, v25
	v_mov_b32_e32 v25, v24
	s_nop 1
	v_permlane32_swap_b32_e32 v24, v25
	s_nop 0
	s_waitcnt lgkmcnt(0)
	v_add_f32_e32 v24, v24, v25
	v_fmamk_f32 v38, v24, 0xbc800000, v93
	v_fmamk_f32 v40, v24, 0xbc800000, v91
	v_fmamk_f32 v25, v24, 0xbc800000, v92
	v_fmamk_f32 v39, v24, 0xbc800000, v90
	v_mul_f32_e32 v40, v40, v40
	v_mul_f32_e32 v38, v38, v38
	v_fmac_f32_e32 v40, v39, v39
	v_fmac_f32_e32 v38, v25, v25
	v_fmamk_f32 v39, v24, 0xbc800000, v97
	v_fmamk_f32 v41, v24, 0xbc800000, v95
	v_add_f32_e32 v25, v40, v38
	v_fmamk_f32 v38, v24, 0xbc800000, v96
	v_fmamk_f32 v40, v24, 0xbc800000, v94
	v_mul_f32_e32 v41, v41, v41
	v_mul_f32_e32 v39, v39, v39
	v_fmac_f32_e32 v41, v40, v40
	v_fmac_f32_e32 v39, v38, v38
	v_add_f32_e32 v38, v41, v39
	v_fmamk_f32 v39, v24, 0xbc800000, v101
	v_fmamk_f32 v41, v24, 0xbc800000, v99
	v_add_f32_e32 v25, v25, v38
	v_fmamk_f32 v38, v24, 0xbc800000, v100
	v_fmamk_f32 v40, v24, 0xbc800000, v98
	v_mul_f32_e32 v41, v41, v41
	v_mul_f32_e32 v39, v39, v39
	v_fmac_f32_e32 v41, v40, v40
	v_fmac_f32_e32 v39, v38, v38
	v_add_f32_e32 v38, v41, v39
	v_fmamk_f32 v39, v24, 0xbc800000, v105
	v_fmamk_f32 v41, v24, 0xbc800000, v103
	v_add_f32_e32 v25, v38, v25
	v_fmamk_f32 v38, v24, 0xbc800000, v104
	v_fmamk_f32 v40, v24, 0xbc800000, v102
	v_mul_f32_e32 v41, v41, v41
	v_mul_f32_e32 v39, v39, v39
	v_fmac_f32_e32 v41, v40, v40
	v_fmac_f32_e32 v39, v38, v38
	v_add_f32_e32 v38, v41, v39
	v_add_f32_e32 v25, v38, v25
	v_mov_b32_e32 v38, v25
	s_nop 1
	v_permlane16_swap_b32_e32 v25, v38
	s_nop 0
	s_waitcnt lgkmcnt(0)
	v_add_f32_e32 v25, v25, v38
	v_mov_b32_e32 v38, v25
	s_nop 1
	v_permlane32_swap_b32_e32 v25, v38
	s_nop 0
	s_and_saveexec_b64 s[18:19], vcc
	s_cbranch_execz .LBB0_1057
	s_lshl_b32 s0, s47, 11
	s_add_i32 s0, s17, s0
	v_mul_f32_e32 v24, 0x3c800000, v24
	s_waitcnt lgkmcnt(0)
	v_add_f32_e32 v25, v25, v38
	v_lshl_add_u32 v38, v1, 5, s0
	ds_write_b64 v38, v[24:25] offset:1024
; __device__ __forceinline__ float shfl_lane(float v, int srclane) { return __int_as_float(__builtin_amdgcn_ds_bpermute(srclane << 2, __float_as_int(v))); }
;     __device__ __forceinline__ void fused(AccT& acc, const Unit& u, int wr, int wc, int fr_in, int fq_in, LAS unsigned char* lds, int wid, int lane_in) const {
;     ...
; #pragma unroll
;         for (int ai = 0; ai < 2; ++ai)
; #pragma unroll
;             for (int m = 0; m < 4; ++m) {
;                 float s = 0.f;
; #pragma unroll
;                 for (int bj = 0; bj < 2; ++bj)
; #pragma unroll
;                     for (int n = 0; n < 2; ++n) { const f32x4 x = acc[ai][bj][m][n]; s += (x[0] + x[1]) + (x[2] + x[3]); }
;                 s += shfl_lane(s, lane ^ 16); s += shfl_lane(s, lane ^ 32);
;                 const float mw = s * (1.0f / 64.0f); float q = 0.f;
; #pragma unroll
;                 for (int bj = 0; bj < 2; ++bj)
; #pragma unroll
;                     for (int n = 0; n < 2; ++n) { const f32x4 d = acc[ai][bj][m][n] - mw; q += (d[0] * d[0] + d[1] * d[1]) + (d[2] * d[2] + d[3] * d[3]); }
;                 q += shfl_lane(q, lane ^ 16); q += shfl_lane(q, lane ^ 32);
;                 if (fq == 0) P[(ai * HALF + wr * 64 + m * 16 + fr) * 4 + wc] = (f32x2){mw, q};
.LBB0_1057:
	s_or_b64 exec, exec, s[18:19]
	v_mov_b32_e32 v24, v75
	v_mov_b32_e32 v25, v76
	s_waitcnt lgkmcnt(0)
	v_mov_b32_e32 v38, v74
	v_mov_b32_e32 v39, v77
	v_pk_add_f32 v[24:25], v[24:25], v[38:39]
	v_mov_b32_e32 v38, v79
	v_mov_b32_e32 v39, v80
	v_mov_b32_e32 v40, v78
	v_mov_b32_e32 v41, v81
	v_pk_add_f32 v[38:39], v[38:39], v[40:41]
	v_add_f32_e32 v24, v24, v25
	v_pk_add_f32 v[38:39], v[38:39], v[38:39] op_sel_hi:[0,1]
	v_add_f32_e32 v25, 0, v24
	v_add_f32_e32 v41, v70, v71
	v_add_f32_e32 v141, v72, v73
	v_mov_b32_e32 v40, v66
	v_mov_b32_e32 v140, v67
	v_mov_b32_e32 v38, v68
	v_mov_b32_e32 v24, v69
	v_pk_add_f32 v[40:41], v[40:41], v[140:141]
	v_pk_add_f32 v[24:25], v[38:39], v[24:25]
	s_nop 0
	v_pk_add_f32 v[24:25], v[40:41], v[24:25]
	s_nop 0
	v_add_f32_e32 v24, v24, v25
	v_mov_b32_e32 v25, v24
	s_nop 1
	v_permlane16_swap_b32_e32 v24, v25
	s_nop 0
	s_waitcnt lgkmcnt(0)
	v_add_f32_e32 v24, v24, v25
	v_mov_b32_e32 v25, v24
	s_nop 1
	v_permlane32_swap_b32_e32 v24, v25
	s_nop 0
	s_waitcnt lgkmcnt(0)
	v_add_f32_e32 v24, v24, v25
	v_fmamk_f32 v38, v24, 0xbc800000, v77
	v_fmamk_f32 v40, v24, 0xbc800000, v75
	v_fmamk_f32 v25, v24, 0xbc800000, v76
	v_fmamk_f32 v39, v24, 0xbc800000, v74
	v_mul_f32_e32 v40, v40, v40
	v_mul_f32_e32 v38, v38, v38
	v_fmac_f32_e32 v40, v39, v39
	v_fmac_f32_e32 v38, v25, v25
	v_fmamk_f32 v39, v24, 0xbc800000, v81
	v_fmamk_f32 v41, v24, 0xbc800000, v79
	v_add_f32_e32 v25, v40, v38
	v_fmamk_f32 v38, v24, 0xbc800000, v80
	v_fmamk_f32 v40, v24, 0xbc800000, v78
	v_mul_f32_e32 v41, v41, v41
	v_mul_f32_e32 v39, v39, v39
	v_fmac_f32_e32 v41, v40, v40
	v_fmac_f32_e32 v39, v38, v38
	v_add_f32_e32 v38, v41, v39
	v_fmamk_f32 v39, v24, 0xbc800000, v73
	v_fmamk_f32 v41, v24, 0xbc800000, v71
	v_add_f32_e32 v25, v25, v38
	v_fmamk_f32 v38, v24, 0xbc800000, v72
	v_fmamk_f32 v40, v24, 0xbc800000, v70
	v_mul_f32_e32 v41, v41, v41
	v_mul_f32_e32 v39, v39, v39
	v_fmac_f32_e32 v41, v40, v40
	v_fmac_f32_e32 v39, v38, v38
	v_add_f32_e32 v38, v41, v39
	v_fmamk_f32 v39, v24, 0xbc800000, v69
	v_fmamk_f32 v41, v24, 0xbc800000, v67
	v_add_f32_e32 v25, v38, v25
	v_fmamk_f32 v38, v24, 0xbc800000, v68
	v_fmamk_f32 v40, v24, 0xbc800000, v66
	v_mul_f32_e32 v41, v41, v41
	v_mul_f32_e32 v39, v39, v39
	v_fmac_f32_e32 v41, v40, v40
	v_fmac_f32_e32 v39, v38, v38
	v_add_f32_e32 v38, v41, v39
	v_add_f32_e32 v25, v38, v25
	v_mov_b32_e32 v38, v25
	s_nop 1
	v_permlane16_swap_b32_e32 v25, v38
	s_nop 0
	s_waitcnt lgkmcnt(0)
	v_add_f32_e32 v25, v25, v38
	v_mov_b32_e32 v38, v25
	s_nop 1
	v_permlane32_swap_b32_e32 v25, v38
	s_nop 0
	s_and_saveexec_b64 s[18:19], vcc
	s_cbranch_execz .LBB0_1059
	s_lshl_b32 s0, s47, 11
	s_add_i32 s0, s17, s0
	v_mul_f32_e32 v24, 0x3c800000, v24
	s_waitcnt lgkmcnt(0)
	v_add_f32_e32 v25, v25, v38
	v_lshl_add_u32 v38, v1, 5, s0
	ds_write_b64 v38, v[24:25] offset:1536
.LBB0_1059:
	s_or_b64 exec, exec, s[18:19]
	v_mov_b32_e32 v24, v63
	v_mov_b32_e32 v25, v64
	s_waitcnt lgkmcnt(0)
	v_mov_b32_e32 v38, v62
	v_mov_b32_e32 v39, v65
	v_pk_add_f32 v[24:25], v[24:25], v[38:39]
	v_mov_b32_e32 v38, v59
	v_mov_b32_e32 v39, v60
	v_mov_b32_e32 v40, v58
	v_mov_b32_e32 v41, v61
	v_pk_add_f32 v[38:39], v[38:39], v[40:41]
	v_add_f32_e32 v24, v24, v25
	v_pk_add_f32 v[38:39], v[38:39], v[38:39] op_sel_hi:[0,1]
	v_add_f32_e32 v25, 0, v24
	v_add_f32_e32 v41, v82, v83
	v_add_f32_e32 v141, v84, v85
	v_mov_b32_e32 v40, v86
	v_mov_b32_e32 v140, v87
	v_mov_b32_e32 v38, v88
	v_mov_b32_e32 v24, v89
	v_pk_add_f32 v[40:41], v[40:41], v[140:141]
	v_pk_add_f32 v[24:25], v[38:39], v[24:25]
	s_nop 0
	v_pk_add_f32 v[24:25], v[40:41], v[24:25]
	s_nop 0
	v_add_f32_e32 v24, v24, v25
	v_mov_b32_e32 v25, v24
	s_nop 1
	v_permlane16_swap_b32_e32 v24, v25
	s_nop 0
	s_waitcnt lgkmcnt(0)
	v_add_f32_e32 v24, v24, v25
	v_mov_b32_e32 v25, v24
	s_nop 1
	v_permlane32_swap_b32_e32 v24, v25
	s_nop 0
	s_waitcnt lgkmcnt(0)
	v_add_f32_e32 v24, v24, v25
	v_fmamk_f32 v38, v24, 0xbc800000, v65
	v_fmamk_f32 v40, v24, 0xbc800000, v63
	v_fmamk_f32 v25, v24, 0xbc800000, v64
	v_fmamk_f32 v39, v24, 0xbc800000, v62
	v_mul_f32_e32 v40, v40, v40
	v_mul_f32_e32 v38, v38, v38
	v_fmac_f32_e32 v40, v39, v39
	v_fmac_f32_e32 v38, v25, v25
	v_fmamk_f32 v39, v24, 0xbc800000, v61
	v_fmamk_f32 v41, v24, 0xbc800000, v59
	v_add_f32_e32 v25, v40, v38
	v_fmamk_f32 v38, v24, 0xbc800000, v60
	v_fmamk_f32 v40, v24, 0xbc800000, v58
	v_mul_f32_e32 v41, v41, v41
	v_mul_f32_e32 v39, v39, v39
	v_fmac_f32_e32 v41, v40, v40
	v_fmac_f32_e32 v39, v38, v38
	v_add_f32_e32 v38, v41, v39
	v_fmamk_f32 v39, v24, 0xbc800000, v85
	v_fmamk_f32 v41, v24, 0xbc800000, v83
	v_add_f32_e32 v25, v25, v38
	v_fmamk_f32 v38, v24, 0xbc800000, v84
	v_fmamk_f32 v40, v24, 0xbc800000, v82
	v_mul_f32_e32 v41, v41, v41
	v_mul_f32_e32 v39, v39, v39
	v_fmac_f32_e32 v41, v40, v40
	v_fmac_f32_e32 v39, v38, v38
	v_add_f32_e32 v38, v41, v39
	v_fmamk_f32 v39, v24, 0xbc800000, v89
	v_fmamk_f32 v41, v24, 0xbc800000, v87
	v_add_f32_e32 v25, v38, v25
	v_fmamk_f32 v38, v24, 0xbc800000, v88
	v_fmamk_f32 v40, v24, 0xbc800000, v86
	v_mul_f32_e32 v41, v41, v41
	v_mul_f32_e32 v39, v39, v39
	v_fmac_f32_e32 v41, v40, v40
	v_fmac_f32_e32 v39, v38, v38
	v_add_f32_e32 v38, v41, v39
	v_add_f32_e32 v25, v38, v25
	v_mov_b32_e32 v38, v25
	s_nop 1
	v_permlane16_swap_b32_e32 v25, v38
	s_nop 0
	s_waitcnt lgkmcnt(0)
	v_add_f32_e32 v25, v25, v38
	v_mov_b32_e32 v38, v25
	s_nop 1
	v_permlane32_swap_b32_e32 v25, v38
	s_nop 0
	s_and_saveexec_b64 s[18:19], vcc
	s_cbranch_execz .LBB0_1061
	s_lshl_b32 s0, s47, 11
	s_add_i32 s0, s17, s0
	v_mul_f32_e32 v24, 0x3c800000, v24
	s_waitcnt lgkmcnt(0)
	v_add_f32_e32 v25, v25, v38
	v_lshl_add_u32 v38, v1, 5, s0
	ds_write_b64 v38, v[24:25] offset:4096
; __device__ __forceinline__ float shfl_lane(float v, int srclane) { return __int_as_float(__builtin_amdgcn_ds_bpermute(srclane << 2, __float_as_int(v))); }
;     __device__ __forceinline__ void fused(AccT& acc, const Unit& u, int wr, int wc, int fr_in, int fq_in, LAS unsigned char* lds, int wid, int lane_in) const {
;     ...
; #pragma unroll
;         for (int ai = 0; ai < 2; ++ai)
; #pragma unroll
;             for (int m = 0; m < 4; ++m) {
;                 float s = 0.f;
; #pragma unroll
;                 for (int bj = 0; bj < 2; ++bj)
; #pragma unroll
;                     for (int n = 0; n < 2; ++n) { const f32x4 x = acc[ai][bj][m][n]; s += (x[0] + x[1]) + (x[2] + x[3]); }
;                 s += shfl_lane(s, lane ^ 16); s += shfl_lane(s, lane ^ 32);
;                 const float mw = s * (1.0f / 64.0f); float q = 0.f;
; #pragma unroll
;                 for (int bj = 0; bj < 2; ++bj)
; #pragma unroll
;                     for (int n = 0; n < 2; ++n) { const f32x4 d = acc[ai][bj][m][n] - mw; q += (d[0] * d[0] + d[1] * d[1]) + (d[2] * d[2] + d[3] * d[3]); }
;                 q += shfl_lane(q, lane ^ 16); q += shfl_lane(q, lane ^ 32);
;                 if (fq == 0) P[(ai * HALF + wr * 64 + m * 16 + fr) * 4 + wc] = (f32x2){mw, q};
.LBB0_1061:
	s_or_b64 exec, exec, s[18:19]
	v_mov_b32_e32 v24, v43
	v_mov_b32_e32 v25, v44
	s_waitcnt lgkmcnt(0)
	v_mov_b32_e32 v38, v42
	v_mov_b32_e32 v39, v45
	v_pk_add_f32 v[24:25], v[24:25], v[38:39]
	v_mov_b32_e32 v38, v47
	v_mov_b32_e32 v39, v48
	v_mov_b32_e32 v40, v46
	v_mov_b32_e32 v41, v49
	v_pk_add_f32 v[38:39], v[38:39], v[40:41]
	v_add_f32_e32 v24, v24, v25
	v_pk_add_f32 v[38:39], v[38:39], v[38:39] op_sel_hi:[0,1]
	v_add_f32_e32 v25, 0, v24
	v_add_f32_e32 v41, v50, v51
	v_add_f32_e32 v141, v52, v53
	v_mov_b32_e32 v40, v54
	v_mov_b32_e32 v140, v55
	v_mov_b32_e32 v38, v56
	v_mov_b32_e32 v24, v57
	v_pk_add_f32 v[40:41], v[40:41], v[140:141]
	v_pk_add_f32 v[24:25], v[38:39], v[24:25]
	s_nop 0
	v_pk_add_f32 v[24:25], v[40:41], v[24:25]
	s_nop 0
	v_add_f32_e32 v24, v24, v25
	v_mov_b32_e32 v25, v24
	s_nop 1
	v_permlane16_swap_b32_e32 v24, v25
	s_nop 0
	s_waitcnt lgkmcnt(0)
	v_add_f32_e32 v24, v24, v25
	v_mov_b32_e32 v25, v24
	s_nop 1
	v_permlane32_swap_b32_e32 v24, v25
	s_nop 0
	s_waitcnt lgkmcnt(0)
	v_add_f32_e32 v24, v24, v25
	v_fmamk_f32 v38, v24, 0xbc800000, v45
	v_fmamk_f32 v40, v24, 0xbc800000, v43
	v_fmamk_f32 v25, v24, 0xbc800000, v44
	v_fmamk_f32 v39, v24, 0xbc800000, v42
	v_mul_f32_e32 v40, v40, v40
	v_mul_f32_e32 v38, v38, v38
	v_fmac_f32_e32 v40, v39, v39
	v_fmac_f32_e32 v38, v25, v25
	v_fmamk_f32 v39, v24, 0xbc800000, v49
	v_fmamk_f32 v41, v24, 0xbc800000, v47
	v_add_f32_e32 v25, v40, v38
	v_fmamk_f32 v38, v24, 0xbc800000, v48
	v_fmamk_f32 v40, v24, 0xbc800000, v46
	v_mul_f32_e32 v41, v41, v41
	v_mul_f32_e32 v39, v39, v39
	v_fmac_f32_e32 v41, v40, v40
	v_fmac_f32_e32 v39, v38, v38
	v_add_f32_e32 v38, v41, v39
	v_fmamk_f32 v39, v24, 0xbc800000, v53
	v_fmamk_f32 v41, v24, 0xbc800000, v51
	v_add_f32_e32 v25, v25, v38
	v_fmamk_f32 v38, v24, 0xbc800000, v52
	v_fmamk_f32 v40, v24, 0xbc800000, v50
	v_mul_f32_e32 v41, v41, v41
	v_mul_f32_e32 v39, v39, v39
	v_fmac_f32_e32 v41, v40, v40
	v_fmac_f32_e32 v39, v38, v38
	v_add_f32_e32 v38, v41, v39
	v_fmamk_f32 v39, v24, 0xbc800000, v57
	v_fmamk_f32 v41, v24, 0xbc800000, v55
	v_add_f32_e32 v25, v38, v25
	v_fmamk_f32 v38, v24, 0xbc800000, v56
	v_fmamk_f32 v40, v24, 0xbc800000, v54
	v_mul_f32_e32 v41, v41, v41
	v_mul_f32_e32 v39, v39, v39
	v_fmac_f32_e32 v41, v40, v40
	v_fmac_f32_e32 v39, v38, v38
	v_add_f32_e32 v38, v41, v39
	v_add_f32_e32 v25, v38, v25
	v_mov_b32_e32 v38, v25
	s_nop 1
	v_permlane16_swap_b32_e32 v25, v38
	s_nop 0
	s_waitcnt lgkmcnt(0)
	v_add_f32_e32 v25, v25, v38
	v_mov_b32_e32 v38, v25
	s_nop 1
	v_permlane32_swap_b32_e32 v25, v38
	s_nop 0
	s_and_saveexec_b64 s[18:19], vcc
	s_cbranch_execz .LBB0_1063
	s_lshl_b32 s0, s47, 11
	s_add_i32 s0, s17, s0
	v_mul_f32_e32 v24, 0x3c800000, v24
	s_waitcnt lgkmcnt(0)
	v_add_f32_e32 v25, v25, v38
	v_lshl_add_u32 v38, v1, 5, s0
	ds_write_b64 v38, v[24:25] offset:4608
; __device__ __forceinline__ float shfl_lane(float v, int srclane) { return __int_as_float(__builtin_amdgcn_ds_bpermute(srclane << 2, __float_as_int(v))); }
;     __device__ __forceinline__ void fused(AccT& acc, const Unit& u, int wr, int wc, int fr_in, int fq_in, LAS unsigned char* lds, int wid, int lane_in) const {
;     ...
; #pragma unroll
;         for (int ai = 0; ai < 2; ++ai)
; #pragma unroll
;             for (int m = 0; m < 4; ++m) {
;                 float s = 0.f;
; #pragma unroll
;                 for (int bj = 0; bj < 2; ++bj)
; #pragma unroll
;                     for (int n = 0; n < 2; ++n) { const f32x4 x = acc[ai][bj][m][n]; s += (x[0] + x[1]) + (x[2] + x[3]); }
;                 s += shfl_lane(s, lane ^ 16); s += shfl_lane(s, lane ^ 32);
;                 const float mw = s * (1.0f / 64.0f); float q = 0.f;
; #pragma unroll
;                 for (int bj = 0; bj < 2; ++bj)
; #pragma unroll
;                     for (int n = 0; n < 2; ++n) { const f32x4 d = acc[ai][bj][m][n] - mw; q += (d[0] * d[0] + d[1] * d[1]) + (d[2] * d[2] + d[3] * d[3]); }
;                 q += shfl_lane(q, lane ^ 16); q += shfl_lane(q, lane ^ 32);
;                 if (fq == 0) P[(ai * HALF + wr * 64 + m * 16 + fr) * 4 + wc] = (f32x2){mw, q};
.LBB0_1063:
	s_or_b64 exec, exec, s[18:19]
	v_mov_b32_e32 v24, v27
	v_mov_b32_e32 v25, v28
	s_waitcnt lgkmcnt(0)
	v_mov_b32_e32 v38, v26
	v_mov_b32_e32 v39, v29
	v_pk_add_f32 v[24:25], v[24:25], v[38:39]
	v_mov_b32_e32 v38, v31
	v_mov_b32_e32 v39, v32
	v_mov_b32_e32 v40, v30
	v_mov_b32_e32 v41, v33
	v_pk_add_f32 v[38:39], v[38:39], v[40:41]
	v_add_f32_e32 v24, v24, v25
	v_pk_add_f32 v[38:39], v[38:39], v[38:39] op_sel_hi:[0,1]
	v_add_f32_e32 v25, 0, v24
	v_add_f32_e32 v41, v18, v19
	v_add_f32_e32 v141, v20, v21
	v_mov_b32_e32 v40, v34
	v_mov_b32_e32 v140, v35
	v_mov_b32_e32 v38, v36
	v_mov_b32_e32 v24, v37
	v_pk_add_f32 v[40:41], v[40:41], v[140:141]
	v_pk_add_f32 v[24:25], v[38:39], v[24:25]
	s_nop 0
	v_pk_add_f32 v[24:25], v[40:41], v[24:25]
	s_nop 0
	v_add_f32_e32 v24, v24, v25
	v_mov_b32_e32 v25, v24
	s_nop 1
	v_permlane16_swap_b32_e32 v24, v25
	s_nop 0
	s_waitcnt lgkmcnt(0)
	v_add_f32_e32 v24, v24, v25
	v_mov_b32_e32 v25, v24
	s_nop 1
	v_permlane32_swap_b32_e32 v24, v25
	s_nop 0
	s_waitcnt lgkmcnt(0)
	v_add_f32_e32 v24, v24, v25
	v_fmamk_f32 v38, v24, 0xbc800000, v29
	v_fmamk_f32 v40, v24, 0xbc800000, v27
	v_fmamk_f32 v25, v24, 0xbc800000, v28
	v_fmamk_f32 v39, v24, 0xbc800000, v26
	v_mul_f32_e32 v40, v40, v40
	v_mul_f32_e32 v38, v38, v38
	v_fmac_f32_e32 v40, v39, v39
	v_fmac_f32_e32 v38, v25, v25
	v_fmamk_f32 v39, v24, 0xbc800000, v33
	v_fmamk_f32 v41, v24, 0xbc800000, v31
	v_add_f32_e32 v25, v40, v38
	v_fmamk_f32 v38, v24, 0xbc800000, v32
	v_fmamk_f32 v40, v24, 0xbc800000, v30
	v_mul_f32_e32 v41, v41, v41
	v_mul_f32_e32 v39, v39, v39
	v_fmac_f32_e32 v41, v40, v40
	v_fmac_f32_e32 v39, v38, v38
	v_add_f32_e32 v38, v41, v39
	v_fmamk_f32 v39, v24, 0xbc800000, v21
	v_fmamk_f32 v41, v24, 0xbc800000, v19
	v_add_f32_e32 v25, v25, v38
	v_fmamk_f32 v38, v24, 0xbc800000, v20
	v_fmamk_f32 v40, v24, 0xbc800000, v18
	v_mul_f32_e32 v41, v41, v41
	v_mul_f32_e32 v39, v39, v39
	v_fmac_f32_e32 v41, v40, v40
	v_fmac_f32_e32 v39, v38, v38
	v_add_f32_e32 v38, v41, v39
	v_fmamk_f32 v39, v24, 0xbc800000, v37
	v_fmamk_f32 v41, v24, 0xbc800000, v35
	v_add_f32_e32 v25, v38, v25
	v_fmamk_f32 v38, v24, 0xbc800000, v36
	v_fmamk_f32 v40, v24, 0xbc800000, v34
	v_mul_f32_e32 v41, v41, v41
	v_mul_f32_e32 v39, v39, v39
	v_fmac_f32_e32 v41, v40, v40
	v_fmac_f32_e32 v39, v38, v38
	v_add_f32_e32 v38, v41, v39
	v_add_f32_e32 v25, v38, v25
	v_mov_b32_e32 v38, v25
	s_nop 1
	v_permlane16_swap_b32_e32 v25, v38
	s_nop 0
	s_waitcnt lgkmcnt(0)
	v_add_f32_e32 v25, v25, v38
	v_mov_b32_e32 v38, v25
	s_nop 1
	v_permlane32_swap_b32_e32 v25, v38
	s_nop 0
	s_and_saveexec_b64 s[18:19], vcc
	s_cbranch_execz .LBB0_1065
	s_lshl_b32 s0, s47, 11
	s_add_i32 s0, s17, s0
	v_mul_f32_e32 v24, 0x3c800000, v24
	s_waitcnt lgkmcnt(0)
	v_add_f32_e32 v25, v25, v38
	v_lshl_add_u32 v38, v1, 5, s0
	ds_write_b64 v38, v[24:25] offset:5120
.LBB0_1065:
	s_or_b64 exec, exec, s[18:19]
	v_mov_b32_e32 v24, v11
	v_mov_b32_e32 v25, v12
	s_waitcnt lgkmcnt(0)
	v_mov_b32_e32 v38, v10
	v_mov_b32_e32 v39, v13
	v_pk_add_f32 v[24:25], v[24:25], v[38:39]
	v_mov_b32_e32 v38, v15
	v_mov_b32_e32 v39, v16
	v_mov_b32_e32 v40, v14
	v_mov_b32_e32 v41, v17
	v_pk_add_f32 v[38:39], v[38:39], v[40:41]
	v_add_f32_e32 v24, v24, v25
	v_pk_add_f32 v[38:39], v[38:39], v[38:39] op_sel_hi:[0,1]
	v_add_f32_e32 v25, 0, v24
	v_add_f32_e32 v41, v6, v7
	v_add_f32_e32 v141, v8, v9
	v_mov_b32_e32 v40, v2
	v_mov_b32_e32 v140, v3
	v_mov_b32_e32 v38, v4
	v_mov_b32_e32 v24, v5
	v_pk_add_f32 v[40:41], v[40:41], v[140:141]
	v_pk_add_f32 v[24:25], v[38:39], v[24:25]
	s_nop 0
	v_pk_add_f32 v[24:25], v[40:41], v[24:25]
	s_nop 0
	v_add_f32_e32 v24, v24, v25
	v_mov_b32_e32 v25, v24
	s_nop 1
	v_permlane16_swap_b32_e32 v24, v25
	s_nop 0
	s_waitcnt lgkmcnt(0)
	v_add_f32_e32 v24, v24, v25
	v_mov_b32_e32 v25, v24
	s_nop 1
	v_permlane32_swap_b32_e32 v24, v25
	s_nop 0
	s_waitcnt lgkmcnt(0)
	v_add_f32_e32 v24, v24, v25
	v_fmamk_f32 v38, v24, 0xbc800000, v13
	v_fmamk_f32 v40, v24, 0xbc800000, v11
	v_fmamk_f32 v25, v24, 0xbc800000, v12
	v_fmamk_f32 v39, v24, 0xbc800000, v10
	v_mul_f32_e32 v40, v40, v40
	v_mul_f32_e32 v38, v38, v38
	v_fmac_f32_e32 v40, v39, v39
	v_fmac_f32_e32 v38, v25, v25
	v_fmamk_f32 v39, v24, 0xbc800000, v17
	v_fmamk_f32 v41, v24, 0xbc800000, v15
	v_add_f32_e32 v25, v40, v38
	v_fmamk_f32 v38, v24, 0xbc800000, v16
	v_fmamk_f32 v40, v24, 0xbc800000, v14
	v_mul_f32_e32 v41, v41, v41
	v_mul_f32_e32 v39, v39, v39
	v_fmac_f32_e32 v41, v40, v40
	v_fmac_f32_e32 v39, v38, v38
	v_add_f32_e32 v38, v41, v39
	v_fmamk_f32 v39, v24, 0xbc800000, v9
	v_fmamk_f32 v41, v24, 0xbc800000, v7
	v_add_f32_e32 v25, v25, v38
	v_fmamk_f32 v38, v24, 0xbc800000, v8
	v_fmamk_f32 v40, v24, 0xbc800000, v6
	v_mul_f32_e32 v41, v41, v41
	v_mul_f32_e32 v39, v39, v39
	v_fmac_f32_e32 v41, v40, v40
	v_fmac_f32_e32 v39, v38, v38
	v_add_f32_e32 v38, v41, v39
	v_fmamk_f32 v39, v24, 0xbc800000, v5
	v_fmamk_f32 v41, v24, 0xbc800000, v3
	v_add_f32_e32 v25, v38, v25
	v_fmamk_f32 v38, v24, 0xbc800000, v4
	v_fmamk_f32 v40, v24, 0xbc800000, v2
	v_mul_f32_e32 v41, v41, v41
	v_mul_f32_e32 v39, v39, v39
	v_fmac_f32_e32 v41, v40, v40
	v_fmac_f32_e32 v39, v38, v38
	v_add_f32_e32 v38, v41, v39
	v_add_f32_e32 v25, v38, v25
	v_mov_b32_e32 v22, v25
	s_nop 1
	v_permlane16_swap_b32_e32 v25, v22
	s_nop 0
	s_waitcnt lgkmcnt(0)
	v_add_f32_e32 v22, v25, v22
	v_mov_b32_e32 v23, v22
	s_nop 1
	v_permlane32_swap_b32_e32 v22, v23
	s_nop 0
	s_and_saveexec_b64 s[18:19], vcc
	s_cbranch_execz .LBB0_1067
	s_lshl_b32 s0, s47, 11
	s_add_i32 s17, s17, s0
	v_mul_f32_e32 v24, 0x3c800000, v24
	s_waitcnt lgkmcnt(0)
	v_add_f32_e32 v25, v22, v23
	v_lshl_add_u32 v1, v1, 5, s17
	ds_write_b64 v1, v[24:25] offset:5632

;     __device__ __forceinline__ void fused(AccT& acc, const Unit& u, int wr, int wc, int fr_in, int fq_in, LAS unsigned char* lds, int wid, int lane_in) const {
;     ...
;         const int col0 = u.pn * BM + wc * 32 + 8 * fq;
;         {
;             u32x4 xr[2][4][2];
; #pragma unroll
;             for (int ai = 0; ai < 2; ++ai)
; #pragma unroll
;                 for (int m = 0; m < 4; ++m) { const int rowi = u.pm * BM + ai * HALF + wr * 64 + m * 16 + fr;
; #pragma unroll
;                     for (int bj = 0; bj < 2; ++bj) xr[ai][m][bj] = *(const u32x4*)((const char*)XinB + blk_off(rowi, col0 + bj * HALF, D, false)); }
.LBB0_1233:
	s_lshl_b32 s0, s60, 5
	s_lshl_b32 s1, s16, 8
	v_and_b32_e32 v218, 63, v138
	v_bfe_u32 v215, v138, 4, 2
	s_or_b32 s0, s1, s0
	s_waitcnt vmcnt(0)
	s_barrier
	s_lshl_b32 s24, s56, 8
	v_lshl_add_u32 v214, v215, 3, s0
	v_add_u32_e32 v217, s66, v1
	v_ashrrev_i32_e32 v132, 6, v214
	v_add_u32_e32 v140, s24, v217
	v_lshlrev_b32_e32 v130, 1, v214
	v_ashrrev_i32_e32 v133, 31, v132
	v_bfe_u32 v193, v214, 5, 1
	v_and_b32_e32 v216, 48, v130
	v_lshlrev_b64 v[208:209], 14, v[132:133]
	v_ashrrev_i32_e32 v132, 7, v140
	v_lshrrev_b32_e32 v130, 3, v217
	v_ashrrev_i32_e32 v133, 31, v132
	v_and_or_b32 v130, v130, 14, v193
	v_lshlrev_b32_e32 v134, 6, v217
	s_movk_i32 s84, 0x3c0
	v_lshlrev_b32_e32 v135, 2, v217
	v_readlane_b32 s92, v254, 29
	v_add_u32_e32 v136, 0x80, v214
	v_lshlrev_b64 v[132:133], 19, v[132:133]
	v_and_or_b32 v134, v134, s84, v216
	v_lshlrev_b32_e32 v130, 10, v130
	v_and_b32_e32 v135, 32, v135
	v_readlane_b32 s93, v254, 30
	v_ashrrev_i32_e32 v136, 6, v136
	v_bitop3_b32 v130, v134, v130, v135 bitop3:0xde
	v_lshl_add_u64 v[212:213], s[92:93], 0, v[132:133]
	v_ashrrev_i32_e32 v137, 31, v136
	v_lshl_add_u64 v[132:133], v[212:213], 0, v[130:131]
	v_lshlrev_b64 v[206:207], 14, v[136:137]
	v_lshl_add_u64 v[134:135], v[132:133], 0, v[208:209]
	v_lshl_add_u64 v[136:137], v[132:133], 0, v[206:207]
	v_add_u32_e32 v138, 16, v140
	global_load_dwordx4 v[132:135], v[134:135], off
	s_nop 0
	global_load_dwordx4 v[194:197], v[136:137], off
	v_ashrrev_i32_e32 v136, 7, v138
	v_lshrrev_b32_e32 v139, 3, v138
	v_ashrrev_i32_e32 v137, 31, v136
	v_and_or_b32 v139, v139, 14, v193
	v_lshlrev_b32_e32 v141, 6, v138
	v_lshlrev_b32_e32 v138, 2, v138
	v_lshlrev_b64 v[136:137], 19, v[136:137]
	v_and_or_b32 v141, v141, s84, v216
	v_lshlrev_b32_e32 v139, 10, v139
	v_and_b32_e32 v138, 32, v138
	v_bitop3_b32 v138, v141, v139, v138 bitop3:0xde
	v_mov_b32_e32 v139, v131
	v_lshl_add_u64 v[136:137], s[92:93], 0, v[136:137]
	v_lshl_add_u64 v[136:137], v[136:137], 0, v[138:139]
	v_lshl_add_u64 v[138:139], v[136:137], 0, v[208:209]
	v_lshl_add_u64 v[136:137], v[136:137], 0, v[206:207]
	global_load_dwordx4 v[220:223], v[138:139], off
	global_load_dwordx4 v[188:191], v[136:137], off
	v_add_u32_e32 v138, 32, v140
	v_ashrrev_i32_e32 v136, 7, v138
	v_lshrrev_b32_e32 v139, 3, v138
	v_ashrrev_i32_e32 v137, 31, v136
	v_and_or_b32 v139, v139, 14, v193
	v_lshlrev_b32_e32 v141, 6, v138
	v_lshlrev_b32_e32 v138, 2, v138
	v_lshlrev_b64 v[136:137], 19, v[136:137]
	v_and_or_b32 v141, v141, s84, v216
	v_lshlrev_b32_e32 v139, 10, v139
	v_and_b32_e32 v138, 32, v138
	v_bitop3_b32 v138, v141, v139, v138 bitop3:0xde
	v_mov_b32_e32 v139, v131
	v_lshl_add_u64 v[136:137], s[92:93], 0, v[136:137]
	v_lshl_add_u64 v[136:137], v[136:137], 0, v[138:139]
	v_lshl_add_u64 v[138:139], v[136:137], 0, v[208:209]
	v_lshl_add_u64 v[136:137], v[136:137], 0, v[206:207]
	global_load_dwordx4 v[184:187], v[138:139], off
	global_load_dwordx4 v[180:183], v[136:137], off
	v_add_u32_e32 v138, 48, v140
	v_ashrrev_i32_e32 v136, 7, v138
	v_lshrrev_b32_e32 v139, 3, v138
	v_ashrrev_i32_e32 v137, 31, v136
	v_and_or_b32 v139, v139, 14, v193
	v_lshlrev_b32_e32 v141, 6, v138
	v_lshlrev_b32_e32 v138, 2, v138
	v_lshlrev_b64 v[136:137], 19, v[136:137]
	v_and_or_b32 v141, v141, s84, v216
	v_lshlrev_b32_e32 v139, 10, v139
	v_and_b32_e32 v138, 32, v138
	v_bitop3_b32 v138, v141, v139, v138 bitop3:0xde
	v_mov_b32_e32 v139, v131
	v_lshl_add_u64 v[136:137], s[92:93], 0, v[136:137]
	v_lshl_add_u64 v[136:137], v[136:137], 0, v[138:139]
	v_lshl_add_u64 v[138:139], v[136:137], 0, v[208:209]
	v_lshl_add_u64 v[136:137], v[136:137], 0, v[206:207]
	global_load_dwordx4 v[176:179], v[138:139], off
	global_load_dwordx4 v[172:175], v[136:137], off
	v_add_u32_e32 v136, 0x80, v140
	v_ashrrev_i32_e32 v136, 7, v136
	v_ashrrev_i32_e32 v137, 31, v136
	v_lshlrev_b64 v[136:137], 19, v[136:137]
	v_lshl_add_u64 v[210:211], s[92:93], 0, v[136:137]
	v_lshl_add_u64 v[136:137], v[210:211], 0, v[130:131]
	v_lshl_add_u64 v[138:139], v[136:137], 0, v[208:209]
	v_lshl_add_u64 v[136:137], v[136:137], 0, v[206:207]
	global_load_dwordx4 v[168:171], v[138:139], off
	global_load_dwordx4 v[164:167], v[136:137], off
	v_add_u32_e32 v138, 0x90, v140
	v_ashrrev_i32_e32 v136, 7, v138
	v_lshrrev_b32_e32 v139, 3, v138
	v_ashrrev_i32_e32 v137, 31, v136
	v_and_or_b32 v139, v139, 14, v193
	v_lshlrev_b32_e32 v141, 6, v138
	v_lshlrev_b32_e32 v138, 2, v138
	v_lshlrev_b64 v[136:137], 19, v[136:137]
	v_and_or_b32 v141, v141, s84, v216
	v_lshlrev_b32_e32 v139, 10, v139
	v_and_b32_e32 v138, 32, v138
	v_bitop3_b32 v138, v141, v139, v138 bitop3:0xde
	v_mov_b32_e32 v139, v131
	v_lshl_add_u64 v[136:137], s[92:93], 0, v[136:137]
	v_lshl_add_u64 v[136:137], v[136:137], 0, v[138:139]
	v_lshl_add_u64 v[138:139], v[136:137], 0, v[208:209]
	v_lshl_add_u64 v[136:137], v[136:137], 0, v[206:207]
	global_load_dwordx4 v[160:163], v[138:139], off
	global_load_dwordx4 v[156:159], v[136:137], off
	v_add_u32_e32 v138, 0xa0, v140
	v_ashrrev_i32_e32 v136, 7, v138
	v_lshrrev_b32_e32 v139, 3, v138
	v_ashrrev_i32_e32 v137, 31, v136
	v_and_or_b32 v139, v139, 14, v193
	v_lshlrev_b32_e32 v141, 6, v138
	v_lshlrev_b32_e32 v138, 2, v138
	v_lshlrev_b64 v[136:137], 19, v[136:137]
	v_and_or_b32 v141, v141, s84, v216
	v_lshlrev_b32_e32 v139, 10, v139
	v_and_b32_e32 v138, 32, v138
	v_bitop3_b32 v138, v141, v139, v138 bitop3:0xde
	v_mov_b32_e32 v139, v131
	v_lshl_add_u64 v[136:137], s[92:93], 0, v[136:137]
	v_lshl_add_u64 v[136:137], v[136:137], 0, v[138:139]
	v_lshl_add_u64 v[138:139], v[136:137], 0, v[208:209]
	v_lshl_add_u64 v[136:137], v[136:137], 0, v[206:207]
	global_load_dwordx4 v[152:155], v[138:139], off
	global_load_dwordx4 v[148:151], v[136:137], off
	v_add_u32_e32 v138, 0xb0, v140
	v_ashrrev_i32_e32 v136, 7, v138
	v_lshrrev_b32_e32 v139, 3, v138
	v_ashrrev_i32_e32 v137, 31, v136
	v_and_or_b32 v139, v139, 14, v193
	v_lshlrev_b32_e32 v140, 6, v138
	v_lshlrev_b32_e32 v138, 2, v138
	v_lshlrev_b64 v[136:137], 19, v[136:137]
	v_and_or_b32 v140, v140, s84, v216
	v_lshlrev_b32_e32 v139, 10, v139
	v_and_b32_e32 v138, 32, v138
	v_bitop3_b32 v138, v140, v139, v138 bitop3:0xde
	v_mov_b32_e32 v139, v131
	v_lshl_add_u64 v[136:137], s[92:93], 0, v[136:137]
	v_lshl_add_u64 v[136:137], v[136:137], 0, v[138:139]
	v_lshl_add_u64 v[138:139], v[136:137], 0, v[208:209]
	v_lshl_add_u64 v[136:137], v[136:137], 0, v[206:207]
	global_load_dwordx4 v[144:147], v[138:139], off
	global_load_dwordx4 v[140:143], v[136:137], off
	s_waitcnt vmcnt(0)
; __device__ __forceinline__ float bflo(unsigned w) { return __uint_as_float(w << 16); }
; __device__ __forceinline__ float bfhi(unsigned w) { return __uint_as_float(w & 0xffff0000u); }
;     __device__ __forceinline__ void fused(AccT& acc, const Unit& u, int wr, int wc, int fr_in, int fq_in, LAS unsigned char* lds, int wid, int lane_in) const {
;     ...
; #pragma unroll
;             for (int ai = 0; ai < 2; ++ai)
; #pragma unroll
;                 for (int m = 0; m < 4; ++m)
; #pragma unroll
;                     for (int bj = 0; bj < 2; ++bj) { const u32x4 w = xr[ai][m][bj];
;                         acc[ai][bj][m][0] += (f32x4){bflo(w.x), bfhi(w.x), bflo(w.y), bfhi(w.y)} * alpha; acc[ai][bj][m][1] += (f32x4){bflo(w.z), bfhi(w.z), bflo(w.w), bfhi(w.w)} * alpha;
;                         asm volatile("" : "+v"(acc[ai][bj][m][0]), "+v"(acc[ai][bj][m][1])); }
	v_lshlrev_b32_e32 v136, 16, v132
	v_and_b32_e32 v137, 0xffff0000, v132
	v_lshlrev_b32_e32 v132, 16, v133
	v_and_b32_e32 v133, 0xffff0000, v133
	s_mov_b32 s0, 0x3fd744fd
	v_pk_fma_f32 v[138:139], v[132:133], s[0:1], v[128:129] op_sel_hi:[1,0,1]
	v_pk_fma_f32 v[136:137], v[136:137], s[0:1], v[126:127] op_sel_hi:[1,0,1]
	v_lshlrev_b32_e32 v126, 16, v134
	v_and_b32_e32 v127, 0xffff0000, v134
	v_lshlrev_b32_e32 v128, 16, v135
	v_and_b32_e32 v129, 0xffff0000, v135
	v_pk_fma_f32 v[134:135], v[128:129], s[0:1], v[124:125] op_sel_hi:[1,0,1]
	v_pk_fma_f32 v[132:133], v[126:127], s[0:1], v[122:123] op_sel_hi:[1,0,1]
	v_lshlrev_b32_e32 v122, 16, v194
	v_and_b32_e32 v123, 0xffff0000, v194
	v_lshlrev_b32_e32 v124, 16, v195
	v_and_b32_e32 v125, 0xffff0000, v195
	v_pk_fma_f32 v[128:129], v[124:125], s[0:1], v[116:117] op_sel_hi:[1,0,1]
	v_pk_fma_f32 v[126:127], v[122:123], s[0:1], v[114:115] op_sel_hi:[1,0,1]
	v_lshlrev_b32_e32 v114, 16, v196
	v_and_b32_e32 v115, 0xffff0000, v196
	v_lshlrev_b32_e32 v116, 16, v197
	v_and_b32_e32 v117, 0xffff0000, v197
	v_pk_fma_f32 v[124:125], v[116:117], s[0:1], v[108:109] op_sel_hi:[1,0,1]
	v_pk_fma_f32 v[122:123], v[114:115], s[0:1], v[106:107] op_sel_hi:[1,0,1]
	v_lshlrev_b32_e32 v114, 16, v222
	v_and_b32_e32 v115, 0xffff0000, v222
	v_lshlrev_b32_e32 v116, 16, v223
	v_and_b32_e32 v117, 0xffff0000, v223
	v_pk_fma_f32 v[112:113], v[116:117], s[0:1], v[112:113] op_sel_hi:[1,0,1]
	v_pk_fma_f32 v[110:111], v[114:115], s[0:1], v[110:111] op_sel_hi:[1,0,1]
	v_lshlrev_b32_e32 v114, 16, v188
	v_and_b32_e32 v115, 0xffff0000, v188
	v_lshlrev_b32_e32 v116, 16, v189
	v_and_b32_e32 v117, 0xffff0000, v189
	v_lshlrev_b32_e32 v106, 16, v220
	v_and_b32_e32 v107, 0xffff0000, v220
	v_lshlrev_b32_e32 v108, 16, v221
	v_and_b32_e32 v109, 0xffff0000, v221
	v_pk_fma_f32 v[116:117], v[116:117], s[0:1], v[100:101] op_sel_hi:[1,0,1]
	v_pk_fma_f32 v[114:115], v[114:115], s[0:1], v[98:99] op_sel_hi:[1,0,1]
	v_lshlrev_b32_e32 v98, 16, v190
	v_and_b32_e32 v99, 0xffff0000, v190
	v_lshlrev_b32_e32 v100, 16, v191
	v_and_b32_e32 v101, 0xffff0000, v191
	v_pk_fma_f32 v[108:109], v[108:109], s[0:1], v[120:121] op_sel_hi:[1,0,1]
	v_pk_fma_f32 v[106:107], v[106:107], s[0:1], v[118:119] op_sel_hi:[1,0,1]
	v_pk_fma_f32 v[120:121], v[100:101], s[0:1], v[92:93] op_sel_hi:[1,0,1]
	v_pk_fma_f32 v[118:119], v[98:99], s[0:1], v[90:91] op_sel_hi:[1,0,1]
	v_lshlrev_b32_e32 v98, 16, v186
	v_and_b32_e32 v99, 0xffff0000, v186
	v_lshlrev_b32_e32 v100, 16, v187
	v_and_b32_e32 v101, 0xffff0000, v187
	v_pk_fma_f32 v[96:97], v[100:101], s[0:1], v[96:97] op_sel_hi:[1,0,1]
	v_pk_fma_f32 v[94:95], v[98:99], s[0:1], v[94:95] op_sel_hi:[1,0,1]
	v_lshlrev_b32_e32 v98, 16, v180
	v_and_b32_e32 v99, 0xffff0000, v180
	v_lshlrev_b32_e32 v100, 16, v181
	v_and_b32_e32 v101, 0xffff0000, v181
	v_lshlrev_b32_e32 v90, 16, v184
	v_and_b32_e32 v91, 0xffff0000, v184
	v_lshlrev_b32_e32 v92, 16, v185
	v_and_b32_e32 v93, 0xffff0000, v185
	v_pk_fma_f32 v[100:101], v[100:101], s[0:1], v[84:85] op_sel_hi:[1,0,1]
	v_pk_fma_f32 v[98:99], v[98:99], s[0:1], v[82:83] op_sel_hi:[1,0,1]
	v_lshlrev_b32_e32 v82, 16, v182
	v_and_b32_e32 v83, 0xffff0000, v182
	v_lshlrev_b32_e32 v84, 16, v183
	v_and_b32_e32 v85, 0xffff0000, v183
	v_pk_fma_f32 v[92:93], v[92:93], s[0:1], v[104:105] op_sel_hi:[1,0,1]
	v_pk_fma_f32 v[90:91], v[90:91], s[0:1], v[102:103] op_sel_hi:[1,0,1]
	v_pk_fma_f32 v[104:105], v[84:85], s[0:1], v[76:77] op_sel_hi:[1,0,1]
	v_pk_fma_f32 v[102:103], v[82:83], s[0:1], v[74:75] op_sel_hi:[1,0,1]
	v_lshlrev_b32_e32 v82, 16, v178
	v_and_b32_e32 v83, 0xffff0000, v178
	v_lshlrev_b32_e32 v84, 16, v179
	v_and_b32_e32 v85, 0xffff0000, v179
	v_pk_fma_f32 v[80:81], v[84:85], s[0:1], v[80:81] op_sel_hi:[1,0,1]
	v_pk_fma_f32 v[78:79], v[82:83], s[0:1], v[78:79] op_sel_hi:[1,0,1]
	v_lshlrev_b32_e32 v82, 16, v172
	v_and_b32_e32 v83, 0xffff0000, v172
	v_lshlrev_b32_e32 v84, 16, v173
	v_and_b32_e32 v85, 0xffff0000, v173
	v_pk_fma_f32 v[72:73], v[84:85], s[0:1], v[72:73] op_sel_hi:[1,0,1]
	v_pk_fma_f32 v[70:71], v[82:83], s[0:1], v[70:71] op_sel_hi:[1,0,1]
	v_lshlrev_b32_e32 v82, 16, v174
	v_and_b32_e32 v83, 0xffff0000, v174
	v_lshlrev_b32_e32 v84, 16, v175
	v_and_b32_e32 v85, 0xffff0000, v175
	v_pk_fma_f32 v[68:69], v[84:85], s[0:1], v[68:69] op_sel_hi:[1,0,1]
	v_pk_fma_f32 v[66:67], v[82:83], s[0:1], v[66:67] op_sel_hi:[1,0,1]
	v_lshlrev_b32_e32 v82, 16, v168
	v_and_b32_e32 v83, 0xffff0000, v168
	v_lshlrev_b32_e32 v84, 16, v169
	v_and_b32_e32 v85, 0xffff0000, v169
	v_pk_fma_f32 v[64:65], v[84:85], s[0:1], v[64:65] op_sel_hi:[1,0,1]
	v_pk_fma_f32 v[62:63], v[82:83], s[0:1], v[62:63] op_sel_hi:[1,0,1]
	v_lshlrev_b32_e32 v82, 16, v170
	v_and_b32_e32 v83, 0xffff0000, v170
	v_lshlrev_b32_e32 v84, 16, v171
	v_and_b32_e32 v85, 0xffff0000, v171
	v_pk_fma_f32 v[60:61], v[84:85], s[0:1], v[60:61] op_sel_hi:[1,0,1]
	v_pk_fma_f32 v[58:59], v[82:83], s[0:1], v[58:59] op_sel_hi:[1,0,1]
	v_lshlrev_b32_e32 v82, 16, v164
	v_and_b32_e32 v83, 0xffff0000, v164
	v_lshlrev_b32_e32 v84, 16, v165
	v_and_b32_e32 v85, 0xffff0000, v165
	v_lshlrev_b32_e32 v74, 16, v176
	v_and_b32_e32 v75, 0xffff0000, v176
	v_lshlrev_b32_e32 v76, 16, v177
	v_and_b32_e32 v77, 0xffff0000, v177
	v_pk_fma_f32 v[84:85], v[84:85], s[0:1], v[52:53] op_sel_hi:[1,0,1]
	v_pk_fma_f32 v[82:83], v[82:83], s[0:1], v[50:51] op_sel_hi:[1,0,1]
	v_lshlrev_b32_e32 v50, 16, v166
	v_and_b32_e32 v51, 0xffff0000, v166
	v_lshlrev_b32_e32 v52, 16, v167
	v_and_b32_e32 v53, 0xffff0000, v167
	v_pk_fma_f32 v[76:77], v[76:77], s[0:1], v[88:89] op_sel_hi:[1,0,1]
	v_pk_fma_f32 v[74:75], v[74:75], s[0:1], v[86:87] op_sel_hi:[1,0,1]
	v_pk_fma_f32 v[88:89], v[52:53], s[0:1], v[44:45] op_sel_hi:[1,0,1]
; __device__ __forceinline__ float bflo(unsigned w) { return __uint_as_float(w << 16); }
; __device__ __forceinline__ float bfhi(unsigned w) { return __uint_as_float(w & 0xffff0000u); }
; __device__ __forceinline__ float shfl_lane(float v, int srclane) { return __int_as_float(__builtin_amdgcn_ds_bpermute(srclane << 2, __float_as_int(v))); }
;     __device__ __forceinline__ void fused(AccT& acc, const Unit& u, int wr, int wc, int fr_in, int fq_in, LAS unsigned char* lds, int wid, int lane_in) const {
;     ...
;                         acc[ai][bj][m][0] += (f32x4){bflo(w.x), bfhi(w.x), bflo(w.y), bfhi(w.y)} * alpha; acc[ai][bj][m][1] += (f32x4){bflo(w.z), bfhi(w.z), bflo(w.w), bfhi(w.w)} * alpha;
;                         asm volatile("" : "+v"(acc[ai][bj][m][0]), "+v"(acc[ai][bj][m][1])); }
;             asm volatile("" ::: "memory");
;         }
; #pragma unroll
;         for (int ai = 0; ai < 2; ++ai)
; #pragma unroll
;             for (int m = 0; m < 4; ++m) {
;                 float s = 0.f;
; #pragma unroll
;                 for (int bj = 0; bj < 2; ++bj)
; #pragma unroll
;                     for (int n = 0; n < 2; ++n) { const f32x4 x = acc[ai][bj][m][n]; s += (x[0] + x[1]) + (x[2] + x[3]); }
;                 s += shfl_lane(s, lane ^ 16); s += shfl_lane(s, lane ^ 32);
;                 const float mw = s * (1.0f / 64.0f); float q = 0.f;
; #pragma unroll
;                 for (int bj = 0; bj < 2; ++bj)
; #pragma unroll
;                     for (int n = 0; n < 2; ++n) { const f32x4 d = acc[ai][bj][m][n] - mw; q += (d[0] * d[0] + d[1] * d[1]) + (d[2] * d[2] + d[3] * d[3]); }
;                 q += shfl_lane(q, lane ^ 16); q += shfl_lane(q, lane ^ 32);
;                 if (fq == 0) P[(ai * HALF + wr * 64 + m * 16 + fr) * 4 + wc] = (f32x2){mw, q};
	v_pk_fma_f32 v[86:87], v[50:51], s[0:1], v[42:43] op_sel_hi:[1,0,1]
	v_lshlrev_b32_e32 v50, 16, v162
	v_and_b32_e32 v51, 0xffff0000, v162
	v_lshlrev_b32_e32 v52, 16, v163
	v_and_b32_e32 v53, 0xffff0000, v163
	v_pk_fma_f32 v[48:49], v[52:53], s[0:1], v[48:49] op_sel_hi:[1,0,1]
	v_pk_fma_f32 v[46:47], v[50:51], s[0:1], v[46:47] op_sel_hi:[1,0,1]
	v_lshlrev_b32_e32 v50, 16, v156
	v_and_b32_e32 v51, 0xffff0000, v156
	v_lshlrev_b32_e32 v52, 16, v157
	v_and_b32_e32 v53, 0xffff0000, v157
	v_lshlrev_b32_e32 v42, 16, v160
	v_and_b32_e32 v43, 0xffff0000, v160
	v_lshlrev_b32_e32 v44, 16, v161
	v_and_b32_e32 v45, 0xffff0000, v161
	v_pk_fma_f32 v[52:53], v[52:53], s[0:1], v[36:37] op_sel_hi:[1,0,1]
	v_pk_fma_f32 v[50:51], v[50:51], s[0:1], v[34:35] op_sel_hi:[1,0,1]
	v_lshlrev_b32_e32 v34, 16, v158
	v_and_b32_e32 v35, 0xffff0000, v158
	v_lshlrev_b32_e32 v36, 16, v159
	v_and_b32_e32 v37, 0xffff0000, v159
	v_pk_fma_f32 v[44:45], v[44:45], s[0:1], v[56:57] op_sel_hi:[1,0,1]
	v_pk_fma_f32 v[42:43], v[42:43], s[0:1], v[54:55] op_sel_hi:[1,0,1]
	v_pk_fma_f32 v[56:57], v[36:37], s[0:1], v[28:29] op_sel_hi:[1,0,1]
	v_pk_fma_f32 v[54:55], v[34:35], s[0:1], v[26:27] op_sel_hi:[1,0,1]
	v_lshlrev_b32_e32 v34, 16, v154
	v_and_b32_e32 v35, 0xffff0000, v154
	v_lshlrev_b32_e32 v36, 16, v155
	v_and_b32_e32 v37, 0xffff0000, v155
	v_lshlrev_b32_e32 v26, 16, v152
	v_and_b32_e32 v27, 0xffff0000, v152
	v_lshlrev_b32_e32 v28, 16, v153
	v_and_b32_e32 v29, 0xffff0000, v153
	v_pk_fma_f32 v[32:33], v[36:37], s[0:1], v[32:33] op_sel_hi:[1,0,1]
	v_pk_fma_f32 v[30:31], v[34:35], s[0:1], v[30:31] op_sel_hi:[1,0,1]
	v_lshlrev_b32_e32 v34, 16, v148
	v_and_b32_e32 v35, 0xffff0000, v148
	v_lshlrev_b32_e32 v36, 16, v149
	v_and_b32_e32 v37, 0xffff0000, v149
	v_pk_fma_f32 v[28:29], v[28:29], s[0:1], v[40:41] op_sel_hi:[1,0,1]
	v_pk_fma_f32 v[26:27], v[26:27], s[0:1], v[38:39] op_sel_hi:[1,0,1]
	v_pk_fma_f32 v[20:21], v[36:37], s[0:1], v[20:21] op_sel_hi:[1,0,1]
	v_pk_fma_f32 v[18:19], v[34:35], s[0:1], v[18:19] op_sel_hi:[1,0,1]
	v_lshlrev_b32_e32 v34, 16, v150
	v_and_b32_e32 v35, 0xffff0000, v150
	v_lshlrev_b32_e32 v36, 16, v151
	v_and_b32_e32 v37, 0xffff0000, v151
	v_mov_b32_e32 v38, v137
	v_mov_b32_e32 v39, v138
	v_mov_b32_e32 v40, v136
	v_mov_b32_e32 v41, v139
	v_pk_fma_f32 v[36:37], v[36:37], s[0:1], v[12:13] op_sel_hi:[1,0,1]
	v_pk_fma_f32 v[34:35], v[34:35], s[0:1], v[10:11] op_sel_hi:[1,0,1]
	v_lshlrev_b32_e32 v10, 16, v144
	v_and_b32_e32 v11, 0xffff0000, v144
	v_lshlrev_b32_e32 v12, 16, v145
	v_and_b32_e32 v13, 0xffff0000, v145
	v_pk_add_f32 v[38:39], v[38:39], v[40:41]
	v_mov_b32_e32 v40, v133
	v_mov_b32_e32 v41, v134
	v_mov_b32_e32 v144, v132
	v_mov_b32_e32 v145, v135
	v_pk_add_f32 v[40:41], v[40:41], v[144:145]
	v_add_f32_e32 v38, v38, v39
	v_pk_add_f32 v[40:41], v[40:41], v[40:41] op_sel_hi:[0,1]
	v_pk_fma_f32 v[12:13], v[12:13], s[0:1], v[24:25] op_sel_hi:[1,0,1]
	v_pk_fma_f32 v[10:11], v[10:11], s[0:1], v[22:23] op_sel_hi:[1,0,1]
	v_lshlrev_b32_e32 v22, 16, v146
	v_and_b32_e32 v23, 0xffff0000, v146
	v_lshlrev_b32_e32 v24, 16, v147
	v_and_b32_e32 v25, 0xffff0000, v147
	v_add_f32_e32 v39, 0, v38
	v_add_f32_e32 v145, v126, v127
	v_add_f32_e32 v147, v128, v129
	v_mov_b32_e32 v144, v122
	v_mov_b32_e32 v146, v123
	v_mov_b32_e32 v40, v124
	v_mov_b32_e32 v38, v125
	v_pk_add_f32 v[144:145], v[144:145], v[146:147]
	v_pk_add_f32 v[38:39], v[40:41], v[38:39]
	v_pk_fma_f32 v[14:15], v[22:23], s[0:1], v[14:15] op_sel_hi:[1,0,1]
	v_lshlrev_b32_e32 v23, 2, v218
	v_pk_add_f32 v[38:39], v[144:145], v[38:39]
	v_xor_b32_e32 v22, 64, v23
	v_add_f32_e32 v40, v38, v39
	v_mov_b32_e32 v41, v40
	s_nop 1
	v_permlane16_swap_b32_e32 v40, v41
	s_nop 0
	v_xor_b32_e32 v23, 0x80, v23
	v_pk_fma_f32 v[16:17], v[24:25], s[0:1], v[16:17] op_sel_hi:[1,0,1]
	v_lshlrev_b32_e32 v24, 16, v140
	v_and_b32_e32 v25, 0xffff0000, v140
	s_waitcnt lgkmcnt(0)
	v_add_f32_e32 v41, v40, v41
	v_mov_b32_e32 v140, v41
	s_nop 1
	v_permlane32_swap_b32_e32 v41, v140
	s_nop 0
	v_pk_fma_f32 v[6:7], v[24:25], s[0:1], v[6:7] op_sel_hi:[1,0,1]
	v_lshlrev_b32_e32 v38, 16, v141
	v_and_b32_e32 v39, 0xffff0000, v141
	v_pk_fma_f32 v[8:9], v[38:39], s[0:1], v[8:9] op_sel_hi:[1,0,1]
	s_waitcnt lgkmcnt(0)
	v_add_f32_e32 v24, v41, v140
	v_fmamk_f32 v41, v24, 0xbc800000, v139
	v_fmamk_f32 v141, v24, 0xbc800000, v137
	v_fmamk_f32 v25, v24, 0xbc800000, v138
	v_fmamk_f32 v140, v24, 0xbc800000, v136
	v_mul_f32_e32 v141, v141, v141
	v_mul_f32_e32 v41, v41, v41
	v_lshlrev_b32_e32 v38, 16, v142
	v_and_b32_e32 v39, 0xffff0000, v142
	v_fmac_f32_e32 v141, v140, v140
	v_fmac_f32_e32 v41, v25, v25
	v_fmamk_f32 v140, v24, 0xbc800000, v135
	v_fmamk_f32 v142, v24, 0xbc800000, v133
	v_add_f32_e32 v25, v141, v41
	v_fmamk_f32 v41, v24, 0xbc800000, v134
	v_fmamk_f32 v141, v24, 0xbc800000, v132
	v_mul_f32_e32 v142, v142, v142
	v_mul_f32_e32 v140, v140, v140
	v_fmac_f32_e32 v142, v141, v141
	v_fmac_f32_e32 v140, v41, v41
	v_add_f32_e32 v41, v142, v140
	v_fmamk_f32 v140, v24, 0xbc800000, v129
	v_fmamk_f32 v142, v24, 0xbc800000, v127
	v_add_f32_e32 v25, v25, v41
	v_fmamk_f32 v41, v24, 0xbc800000, v128
	v_fmamk_f32 v141, v24, 0xbc800000, v126
	v_mul_f32_e32 v142, v142, v142
	v_mul_f32_e32 v140, v140, v140
	v_fmac_f32_e32 v142, v141, v141
	v_fmac_f32_e32 v140, v41, v41
	v_add_f32_e32 v41, v142, v140
	v_fmamk_f32 v140, v24, 0xbc800000, v125
	v_fmamk_f32 v142, v24, 0xbc800000, v123
	v_add_f32_e32 v25, v41, v25
	v_fmamk_f32 v41, v24, 0xbc800000, v124
	v_fmamk_f32 v141, v24, 0xbc800000, v122
	v_mul_f32_e32 v142, v142, v142
	v_mul_f32_e32 v140, v140, v140
	v_fmac_f32_e32 v142, v141, v141
	v_fmac_f32_e32 v140, v41, v41
	v_add_f32_e32 v41, v142, v140
	v_add_f32_e32 v25, v41, v25
	v_mov_b32_e32 v140, v25
	s_nop 1
	v_permlane16_swap_b32_e32 v25, v140
	s_nop 0
	v_lshlrev_b32_e32 v40, 16, v143
	v_and_b32_e32 v41, 0xffff0000, v143
	v_pk_fma_f32 v[2:3], v[38:39], s[0:1], v[2:3] op_sel_hi:[1,0,1]
	v_pk_fma_f32 v[4:5], v[40:41], s[0:1], v[4:5] op_sel_hi:[1,0,1]
	s_waitcnt lgkmcnt(0)
	v_add_f32_e32 v25, v25, v140
	v_mov_b32_e32 v38, v25
	s_nop 1
	v_permlane32_swap_b32_e32 v25, v38
	s_nop 0
	s_lshl_b32 s0, s60, 3
	v_cmp_eq_u32_e32 vcc, 0, v215
	s_add_i32 s20, s0, 0
	s_and_saveexec_b64 s[18:19], vcc
	s_cbranch_execz .LBB0_1235
	s_lshl_b32 s0, s57, 11
	s_add_i32 s0, s20, s0
	v_mul_f32_e32 v24, 0x3c800000, v24
	s_waitcnt lgkmcnt(0)
	v_add_f32_e32 v25, v25, v38
	v_lshl_add_u32 v38, v1, 5, s0
	ds_write_b64 v38, v[24:25]
; __device__ __forceinline__ float shfl_lane(float v, int srclane) { return __int_as_float(__builtin_amdgcn_ds_bpermute(srclane << 2, __float_as_int(v))); }
;     __device__ __forceinline__ void fused(AccT& acc, const Unit& u, int wr, int wc, int fr_in, int fq_in, LAS unsigned char* lds, int wid, int lane_in) const {
;     ...
; #pragma unroll
;         for (int ai = 0; ai < 2; ++ai)
; #pragma unroll
;             for (int m = 0; m < 4; ++m) {
;                 float s = 0.f;
; #pragma unroll
;                 for (int bj = 0; bj < 2; ++bj)
; #pragma unroll
;                     for (int n = 0; n < 2; ++n) { const f32x4 x = acc[ai][bj][m][n]; s += (x[0] + x[1]) + (x[2] + x[3]); }
;                 s += shfl_lane(s, lane ^ 16); s += shfl_lane(s, lane ^ 32);
;                 const float mw = s * (1.0f / 64.0f); float q = 0.f;
; #pragma unroll
;                 for (int bj = 0; bj < 2; ++bj)
; #pragma unroll
;                     for (int n = 0; n < 2; ++n) { const f32x4 d = acc[ai][bj][m][n] - mw; q += (d[0] * d[0] + d[1] * d[1]) + (d[2] * d[2] + d[3] * d[3]); }
;                 q += shfl_lane(q, lane ^ 16); q += shfl_lane(q, lane ^ 32);
;                 if (fq == 0) P[(ai * HALF + wr * 64 + m * 16 + fr) * 4 + wc] = (f32x2){mw, q};
.LBB0_1235:
	s_or_b64 exec, exec, s[18:19]
	v_mov_b32_e32 v24, v107
	v_mov_b32_e32 v25, v108
	s_waitcnt lgkmcnt(0)
	v_mov_b32_e32 v38, v106
	v_mov_b32_e32 v39, v109
	v_pk_add_f32 v[24:25], v[24:25], v[38:39]
	v_mov_b32_e32 v38, v111
	v_mov_b32_e32 v39, v112
	v_mov_b32_e32 v40, v110
	v_mov_b32_e32 v41, v113
	v_pk_add_f32 v[38:39], v[38:39], v[40:41]
	v_add_f32_e32 v24, v24, v25
	v_pk_add_f32 v[38:39], v[38:39], v[38:39] op_sel_hi:[0,1]
	v_add_f32_e32 v25, 0, v24
	v_add_f32_e32 v41, v114, v115
	v_add_f32_e32 v141, v116, v117
	v_mov_b32_e32 v40, v118
	v_mov_b32_e32 v140, v119
	v_mov_b32_e32 v38, v120
	v_mov_b32_e32 v24, v121
	v_pk_add_f32 v[40:41], v[40:41], v[140:141]
	v_pk_add_f32 v[24:25], v[38:39], v[24:25]
	s_nop 0
	v_pk_add_f32 v[24:25], v[40:41], v[24:25]
	s_nop 0
	v_add_f32_e32 v24, v24, v25
	v_mov_b32_e32 v25, v24
	s_nop 1
	v_permlane16_swap_b32_e32 v24, v25
	s_nop 0
	s_waitcnt lgkmcnt(0)
	v_add_f32_e32 v24, v24, v25
	v_mov_b32_e32 v25, v24
	s_nop 1
	v_permlane32_swap_b32_e32 v24, v25
	s_nop 0
	s_waitcnt lgkmcnt(0)
	v_add_f32_e32 v24, v24, v25
	v_fmamk_f32 v38, v24, 0xbc800000, v109
	v_fmamk_f32 v40, v24, 0xbc800000, v107
	v_fmamk_f32 v25, v24, 0xbc800000, v108
	v_fmamk_f32 v39, v24, 0xbc800000, v106
	v_mul_f32_e32 v40, v40, v40
	v_mul_f32_e32 v38, v38, v38
	v_fmac_f32_e32 v40, v39, v39
	v_fmac_f32_e32 v38, v25, v25
	v_fmamk_f32 v39, v24, 0xbc800000, v113
	v_fmamk_f32 v41, v24, 0xbc800000, v111
	v_add_f32_e32 v25, v40, v38
	v_fmamk_f32 v38, v24, 0xbc800000, v112
	v_fmamk_f32 v40, v24, 0xbc800000, v110
	v_mul_f32_e32 v41, v41, v41
	v_mul_f32_e32 v39, v39, v39
	v_fmac_f32_e32 v41, v40, v40
	v_fmac_f32_e32 v39, v38, v38
	v_add_f32_e32 v38, v41, v39
	v_fmamk_f32 v39, v24, 0xbc800000, v117
	v_fmamk_f32 v41, v24, 0xbc800000, v115
	v_add_f32_e32 v25, v25, v38
	v_fmamk_f32 v38, v24, 0xbc800000, v116
	v_fmamk_f32 v40, v24, 0xbc800000, v114
	v_mul_f32_e32 v41, v41, v41
	v_mul_f32_e32 v39, v39, v39
	v_fmac_f32_e32 v41, v40, v40
	v_fmac_f32_e32 v39, v38, v38
	v_add_f32_e32 v38, v41, v39
	v_fmamk_f32 v39, v24, 0xbc800000, v121
	v_fmamk_f32 v41, v24, 0xbc800000, v119
	v_add_f32_e32 v25, v38, v25
	v_fmamk_f32 v38, v24, 0xbc800000, v120
	v_fmamk_f32 v40, v24, 0xbc800000, v118
	v_mul_f32_e32 v41, v41, v41
	v_mul_f32_e32 v39, v39, v39
	v_fmac_f32_e32 v41, v40, v40
	v_fmac_f32_e32 v39, v38, v38
	v_add_f32_e32 v38, v41, v39
	v_add_f32_e32 v25, v38, v25
	v_mov_b32_e32 v38, v25
	s_nop 1
	v_permlane16_swap_b32_e32 v25, v38
	s_nop 0
	s_waitcnt lgkmcnt(0)
	v_add_f32_e32 v25, v25, v38
	v_mov_b32_e32 v38, v25
	s_nop 1
	v_permlane32_swap_b32_e32 v25, v38
	s_nop 0
	s_and_saveexec_b64 s[18:19], vcc
	v_readlane_b32 s26, v254, 38
	v_readlane_b32 s27, v254, 39
	v_readlane_b32 s85, v255, 6
	s_cbranch_execz .LBB0_1237
	s_lshl_b32 s0, s57, 11
	s_add_i32 s0, s20, s0
	v_mul_f32_e32 v24, 0x3c800000, v24
	s_waitcnt lgkmcnt(0)
	v_add_f32_e32 v25, v25, v38
	v_lshl_add_u32 v38, v1, 5, s0
	ds_write_b64 v38, v[24:25] offset:512
.LBB0_1237:
	s_or_b64 exec, exec, s[18:19]
	v_mov_b32_e32 v24, v91
	v_mov_b32_e32 v25, v92
	s_waitcnt lgkmcnt(0)
	v_mov_b32_e32 v38, v90
	v_mov_b32_e32 v39, v93
	v_pk_add_f32 v[24:25], v[24:25], v[38:39]
	v_mov_b32_e32 v38, v95
	v_mov_b32_e32 v39, v96
	v_mov_b32_e32 v40, v94
	v_mov_b32_e32 v41, v97
	v_pk_add_f32 v[38:39], v[38:39], v[40:41]
	v_add_f32_e32 v24, v24, v25
	v_pk_add_f32 v[38:39], v[38:39], v[38:39] op_sel_hi:[0,1]
	v_add_f32_e32 v25, 0, v24
	v_add_f32_e32 v41, v98, v99
	v_add_f32_e32 v141, v100, v101
	v_mov_b32_e32 v40, v102
	v_mov_b32_e32 v140, v103
	v_mov_b32_e32 v38, v104
	v_mov_b32_e32 v24, v105
	v_pk_add_f32 v[40:41], v[40:41], v[140:141]
	v_pk_add_f32 v[24:25], v[38:39], v[24:25]
	s_nop 0
	v_pk_add_f32 v[24:25], v[40:41], v[24:25]
	s_nop 0
	v_add_f32_e32 v24, v24, v25
	v_mov_b32_e32 v25, v24
	s_nop 1
	v_permlane16_swap_b32_e32 v24, v25
	s_nop 0
	s_waitcnt lgkmcnt(0)
	v_add_f32_e32 v24, v24, v25
	v_mov_b32_e32 v25, v24
	s_nop 1
	v_permlane32_swap_b32_e32 v24, v25
	s_nop 0
	s_waitcnt lgkmcnt(0)
	v_add_f32_e32 v24, v24, v25
	v_fmamk_f32 v38, v24, 0xbc800000, v93
	v_fmamk_f32 v40, v24, 0xbc800000, v91
	v_fmamk_f32 v25, v24, 0xbc800000, v92
	v_fmamk_f32 v39, v24, 0xbc800000, v90
	v_mul_f32_e32 v40, v40, v40
	v_mul_f32_e32 v38, v38, v38
	v_fmac_f32_e32 v40, v39, v39
	v_fmac_f32_e32 v38, v25, v25
	v_fmamk_f32 v39, v24, 0xbc800000, v97
	v_fmamk_f32 v41, v24, 0xbc800000, v95
	v_add_f32_e32 v25, v40, v38
	v_fmamk_f32 v38, v24, 0xbc800000, v96
	v_fmamk_f32 v40, v24, 0xbc800000, v94
	v_mul_f32_e32 v41, v41, v41
	v_mul_f32_e32 v39, v39, v39
	v_fmac_f32_e32 v41, v40, v40
	v_fmac_f32_e32 v39, v38, v38
	v_add_f32_e32 v38, v41, v39
	v_fmamk_f32 v39, v24, 0xbc800000, v101
	v_fmamk_f32 v41, v24, 0xbc800000, v99
	v_add_f32_e32 v25, v25, v38
	v_fmamk_f32 v38, v24, 0xbc800000, v100
	v_fmamk_f32 v40, v24, 0xbc800000, v98
	v_mul_f32_e32 v41, v41, v41
	v_mul_f32_e32 v39, v39, v39
	v_fmac_f32_e32 v41, v40, v40
	v_fmac_f32_e32 v39, v38, v38
	v_add_f32_e32 v38, v41, v39
	v_fmamk_f32 v39, v24, 0xbc800000, v105
	v_fmamk_f32 v41, v24, 0xbc800000, v103
	v_add_f32_e32 v25, v38, v25
	v_fmamk_f32 v38, v24, 0xbc800000, v104
	v_fmamk_f32 v40, v24, 0xbc800000, v102
	v_mul_f32_e32 v41, v41, v41
	v_mul_f32_e32 v39, v39, v39
	v_fmac_f32_e32 v41, v40, v40
	v_fmac_f32_e32 v39, v38, v38
	v_add_f32_e32 v38, v41, v39
	v_add_f32_e32 v25, v38, v25
	v_mov_b32_e32 v38, v25
	s_nop 1
	v_permlane16_swap_b32_e32 v25, v38
	s_nop 0
	s_waitcnt lgkmcnt(0)
	v_add_f32_e32 v25, v25, v38
	v_mov_b32_e32 v38, v25
	s_nop 1
	v_permlane32_swap_b32_e32 v25, v38
	s_nop 0
	s_and_saveexec_b64 s[18:19], vcc
	s_cbranch_execz .LBB0_1239
	s_lshl_b32 s0, s57, 11
	s_add_i32 s0, s20, s0
	v_mul_f32_e32 v24, 0x3c800000, v24
	s_waitcnt lgkmcnt(0)
	v_add_f32_e32 v25, v25, v38
	v_lshl_add_u32 v38, v1, 5, s0
	ds_write_b64 v38, v[24:25] offset:1024
; __device__ __forceinline__ float shfl_lane(float v, int srclane) { return __int_as_float(__builtin_amdgcn_ds_bpermute(srclane << 2, __float_as_int(v))); }
;     __device__ __forceinline__ void fused(AccT& acc, const Unit& u, int wr, int wc, int fr_in, int fq_in, LAS unsigned char* lds, int wid, int lane_in) const {
;     ...
; #pragma unroll
;         for (int ai = 0; ai < 2; ++ai)
; #pragma unroll
;             for (int m = 0; m < 4; ++m) {
;                 float s = 0.f;
; #pragma unroll
;                 for (int bj = 0; bj < 2; ++bj)
; #pragma unroll
;                     for (int n = 0; n < 2; ++n) { const f32x4 x = acc[ai][bj][m][n]; s += (x[0] + x[1]) + (x[2] + x[3]); }
;                 s += shfl_lane(s, lane ^ 16); s += shfl_lane(s, lane ^ 32);
;                 const float mw = s * (1.0f / 64.0f); float q = 0.f;
; #pragma unroll
;                 for (int bj = 0; bj < 2; ++bj)
; #pragma unroll
;                     for (int n = 0; n < 2; ++n) { const f32x4 d = acc[ai][bj][m][n] - mw; q += (d[0] * d[0] + d[1] * d[1]) + (d[2] * d[2] + d[3] * d[3]); }
;                 q += shfl_lane(q, lane ^ 16); q += shfl_lane(q, lane ^ 32);
;                 if (fq == 0) P[(ai * HALF + wr * 64 + m * 16 + fr) * 4 + wc] = (f32x2){mw, q};
.LBB0_1239:
	s_or_b64 exec, exec, s[18:19]
	v_mov_b32_e32 v24, v75
	v_mov_b32_e32 v25, v76
	s_waitcnt lgkmcnt(0)
	v_mov_b32_e32 v38, v74
	v_mov_b32_e32 v39, v77
	v_pk_add_f32 v[24:25], v[24:25], v[38:39]
	v_mov_b32_e32 v38, v79
	v_mov_b32_e32 v39, v80
	v_mov_b32_e32 v40, v78
	v_mov_b32_e32 v41, v81
	v_pk_add_f32 v[38:39], v[38:39], v[40:41]
	v_add_f32_e32 v24, v24, v25
	v_pk_add_f32 v[38:39], v[38:39], v[38:39] op_sel_hi:[0,1]
	v_add_f32_e32 v25, 0, v24
	v_add_f32_e32 v41, v70, v71
	v_add_f32_e32 v141, v72, v73
	v_mov_b32_e32 v40, v66
	v_mov_b32_e32 v140, v67
	v_mov_b32_e32 v38, v68
	v_mov_b32_e32 v24, v69
	v_pk_add_f32 v[40:41], v[40:41], v[140:141]
	v_pk_add_f32 v[24:25], v[38:39], v[24:25]
	s_nop 0
	v_pk_add_f32 v[24:25], v[40:41], v[24:25]
	s_nop 0
	v_add_f32_e32 v24, v24, v25
	v_mov_b32_e32 v25, v24
	s_nop 1
	v_permlane16_swap_b32_e32 v24, v25
	s_nop 0
	s_waitcnt lgkmcnt(0)
	v_add_f32_e32 v24, v24, v25
	v_mov_b32_e32 v25, v24
	s_nop 1
	v_permlane32_swap_b32_e32 v24, v25
	s_nop 0
	s_waitcnt lgkmcnt(0)
	v_add_f32_e32 v24, v24, v25
	v_fmamk_f32 v38, v24, 0xbc800000, v77
	v_fmamk_f32 v40, v24, 0xbc800000, v75
	v_fmamk_f32 v25, v24, 0xbc800000, v76
	v_fmamk_f32 v39, v24, 0xbc800000, v74
	v_mul_f32_e32 v40, v40, v40
	v_mul_f32_e32 v38, v38, v38
	v_fmac_f32_e32 v40, v39, v39
	v_fmac_f32_e32 v38, v25, v25
	v_fmamk_f32 v39, v24, 0xbc800000, v81
	v_fmamk_f32 v41, v24, 0xbc800000, v79
	v_add_f32_e32 v25, v40, v38
	v_fmamk_f32 v38, v24, 0xbc800000, v80
	v_fmamk_f32 v40, v24, 0xbc800000, v78
	v_mul_f32_e32 v41, v41, v41
	v_mul_f32_e32 v39, v39, v39
	v_fmac_f32_e32 v41, v40, v40
	v_fmac_f32_e32 v39, v38, v38
	v_add_f32_e32 v38, v41, v39
	v_fmamk_f32 v39, v24, 0xbc800000, v73
	v_fmamk_f32 v41, v24, 0xbc800000, v71
	v_add_f32_e32 v25, v25, v38
	v_fmamk_f32 v38, v24, 0xbc800000, v72
	v_fmamk_f32 v40, v24, 0xbc800000, v70
	v_mul_f32_e32 v41, v41, v41
	v_mul_f32_e32 v39, v39, v39
	v_fmac_f32_e32 v41, v40, v40
	v_fmac_f32_e32 v39, v38, v38
	v_add_f32_e32 v38, v41, v39
	v_fmamk_f32 v39, v24, 0xbc800000, v69
	v_fmamk_f32 v41, v24, 0xbc800000, v67
	v_add_f32_e32 v25, v38, v25
	v_fmamk_f32 v38, v24, 0xbc800000, v68
	v_fmamk_f32 v40, v24, 0xbc800000, v66
	v_mul_f32_e32 v41, v41, v41
	v_mul_f32_e32 v39, v39, v39
	v_fmac_f32_e32 v41, v40, v40
	v_fmac_f32_e32 v39, v38, v38
	v_add_f32_e32 v38, v41, v39
	v_add_f32_e32 v25, v38, v25
	v_mov_b32_e32 v38, v25
	s_nop 1
	v_permlane16_swap_b32_e32 v25, v38
	s_nop 0
	s_waitcnt lgkmcnt(0)
	v_add_f32_e32 v25, v25, v38
	v_mov_b32_e32 v38, v25
	s_nop 1
	v_permlane32_swap_b32_e32 v25, v38
	s_nop 0
	s_and_saveexec_b64 s[18:19], vcc
	s_cbranch_execz .LBB0_1241
	s_lshl_b32 s0, s57, 11
	s_add_i32 s0, s20, s0
	v_mul_f32_e32 v24, 0x3c800000, v24
	s_waitcnt lgkmcnt(0)
	v_add_f32_e32 v25, v25, v38
	v_lshl_add_u32 v38, v1, 5, s0
	ds_write_b64 v38, v[24:25] offset:1536
.LBB0_1241:
	s_or_b64 exec, exec, s[18:19]
	v_mov_b32_e32 v24, v63
	v_mov_b32_e32 v25, v64
	s_waitcnt lgkmcnt(0)
	v_mov_b32_e32 v38, v62
	v_mov_b32_e32 v39, v65
	v_pk_add_f32 v[24:25], v[24:25], v[38:39]
	v_mov_b32_e32 v38, v59
	v_mov_b32_e32 v39, v60
	v_mov_b32_e32 v40, v58
	v_mov_b32_e32 v41, v61
	v_pk_add_f32 v[38:39], v[38:39], v[40:41]
	v_add_f32_e32 v24, v24, v25
	v_pk_add_f32 v[38:39], v[38:39], v[38:39] op_sel_hi:[0,1]
	v_add_f32_e32 v25, 0, v24
	v_add_f32_e32 v41, v82, v83
	v_add_f32_e32 v141, v84, v85
	v_mov_b32_e32 v40, v86
	v_mov_b32_e32 v140, v87
	v_mov_b32_e32 v38, v88
	v_mov_b32_e32 v24, v89
	v_pk_add_f32 v[40:41], v[40:41], v[140:141]
	v_pk_add_f32 v[24:25], v[38:39], v[24:25]
	s_nop 0
	v_pk_add_f32 v[24:25], v[40:41], v[24:25]
	s_nop 0
	v_add_f32_e32 v24, v24, v25
	v_mov_b32_e32 v25, v24
	s_nop 1
	v_permlane16_swap_b32_e32 v24, v25
	s_nop 0
	s_waitcnt lgkmcnt(0)
	v_add_f32_e32 v24, v24, v25
	v_mov_b32_e32 v25, v24
	s_nop 1
	v_permlane32_swap_b32_e32 v24, v25
	s_nop 0
	s_waitcnt lgkmcnt(0)
	v_add_f32_e32 v24, v24, v25
	v_fmamk_f32 v38, v24, 0xbc800000, v65
	v_fmamk_f32 v40, v24, 0xbc800000, v63
	v_fmamk_f32 v25, v24, 0xbc800000, v64
	v_fmamk_f32 v39, v24, 0xbc800000, v62
	v_mul_f32_e32 v40, v40, v40
	v_mul_f32_e32 v38, v38, v38
	v_fmac_f32_e32 v40, v39, v39
	v_fmac_f32_e32 v38, v25, v25
	v_fmamk_f32 v39, v24, 0xbc800000, v61
	v_fmamk_f32 v41, v24, 0xbc800000, v59
	v_add_f32_e32 v25, v40, v38
	v_fmamk_f32 v38, v24, 0xbc800000, v60
	v_fmamk_f32 v40, v24, 0xbc800000, v58
	v_mul_f32_e32 v41, v41, v41
	v_mul_f32_e32 v39, v39, v39
	v_fmac_f32_e32 v41, v40, v40
	v_fmac_f32_e32 v39, v38, v38
	v_add_f32_e32 v38, v41, v39
	v_fmamk_f32 v39, v24, 0xbc800000, v85
	v_fmamk_f32 v41, v24, 0xbc800000, v83
	v_add_f32_e32 v25, v25, v38
	v_fmamk_f32 v38, v24, 0xbc800000, v84
	v_fmamk_f32 v40, v24, 0xbc800000, v82
	v_mul_f32_e32 v41, v41, v41
	v_mul_f32_e32 v39, v39, v39
	v_fmac_f32_e32 v41, v40, v40
	v_fmac_f32_e32 v39, v38, v38
	v_add_f32_e32 v38, v41, v39
	v_fmamk_f32 v39, v24, 0xbc800000, v89
	v_fmamk_f32 v41, v24, 0xbc800000, v87
	v_add_f32_e32 v25, v38, v25
	v_fmamk_f32 v38, v24, 0xbc800000, v88
	v_fmamk_f32 v40, v24, 0xbc800000, v86
	v_mul_f32_e32 v41, v41, v41
	v_mul_f32_e32 v39, v39, v39
	v_fmac_f32_e32 v41, v40, v40
	v_fmac_f32_e32 v39, v38, v38
	v_add_f32_e32 v38, v41, v39
	v_add_f32_e32 v25, v38, v25
	v_mov_b32_e32 v38, v25
	s_nop 1
	v_permlane16_swap_b32_e32 v25, v38
	s_nop 0
	s_waitcnt lgkmcnt(0)
	v_add_f32_e32 v25, v25, v38
	v_mov_b32_e32 v38, v25
	s_nop 1
	v_permlane32_swap_b32_e32 v25, v38
	s_nop 0
	s_and_saveexec_b64 s[18:19], vcc
	s_cbranch_execz .LBB0_1243
	s_lshl_b32 s0, s57, 11
	s_add_i32 s0, s20, s0
	v_mul_f32_e32 v24, 0x3c800000, v24
	s_waitcnt lgkmcnt(0)
	v_add_f32_e32 v25, v25, v38
	v_lshl_add_u32 v38, v1, 5, s0
	ds_write_b64 v38, v[24:25] offset:4096
; __device__ __forceinline__ float shfl_lane(float v, int srclane) { return __int_as_float(__builtin_amdgcn_ds_bpermute(srclane << 2, __float_as_int(v))); }
;     __device__ __forceinline__ void fused(AccT& acc, const Unit& u, int wr, int wc, int fr_in, int fq_in, LAS unsigned char* lds, int wid, int lane_in) const {
;     ...
; #pragma unroll
;         for (int ai = 0; ai < 2; ++ai)
; #pragma unroll
;             for (int m = 0; m < 4; ++m) {
;                 float s = 0.f;
; #pragma unroll
;                 for (int bj = 0; bj < 2; ++bj)
; #pragma unroll
;                     for (int n = 0; n < 2; ++n) { const f32x4 x = acc[ai][bj][m][n]; s += (x[0] + x[1]) + (x[2] + x[3]); }
;                 s += shfl_lane(s, lane ^ 16); s += shfl_lane(s, lane ^ 32);
;                 const float mw = s * (1.0f / 64.0f); float q = 0.f;
; #pragma unroll
;                 for (int bj = 0; bj < 2; ++bj)
; #pragma unroll
;                     for (int n = 0; n < 2; ++n) { const f32x4 d = acc[ai][bj][m][n] - mw; q += (d[0] * d[0] + d[1] * d[1]) + (d[2] * d[2] + d[3] * d[3]); }
;                 q += shfl_lane(q, lane ^ 16); q += shfl_lane(q, lane ^ 32);
;                 if (fq == 0) P[(ai * HALF + wr * 64 + m * 16 + fr) * 4 + wc] = (f32x2){mw, q};
;             }
.LBB0_1243:
	s_or_b64 exec, exec, s[18:19]
	v_mov_b32_e32 v24, v43
	v_mov_b32_e32 v25, v44
	s_waitcnt lgkmcnt(0)
	v_mov_b32_e32 v38, v42
	v_mov_b32_e32 v39, v45
	v_pk_add_f32 v[24:25], v[24:25], v[38:39]
	v_mov_b32_e32 v38, v47
	v_mov_b32_e32 v39, v48
	v_mov_b32_e32 v40, v46
	v_mov_b32_e32 v41, v49
	v_pk_add_f32 v[38:39], v[38:39], v[40:41]
	v_add_f32_e32 v24, v24, v25
	v_pk_add_f32 v[38:39], v[38:39], v[38:39] op_sel_hi:[0,1]
	v_add_f32_e32 v25, 0, v24
	v_add_f32_e32 v41, v50, v51
	v_add_f32_e32 v141, v52, v53
	v_mov_b32_e32 v40, v54
	v_mov_b32_e32 v140, v55
	v_mov_b32_e32 v38, v56
	v_mov_b32_e32 v24, v57
	v_pk_add_f32 v[40:41], v[40:41], v[140:141]
	v_pk_add_f32 v[24:25], v[38:39], v[24:25]
	s_nop 0
	v_pk_add_f32 v[24:25], v[40:41], v[24:25]
	s_nop 0
	v_add_f32_e32 v24, v24, v25
	v_mov_b32_e32 v25, v24
	s_nop 1
	v_permlane16_swap_b32_e32 v24, v25
	s_nop 0
	s_waitcnt lgkmcnt(0)
	v_add_f32_e32 v24, v24, v25
	v_mov_b32_e32 v25, v24
	s_nop 1
	v_permlane32_swap_b32_e32 v24, v25
	s_nop 0
	s_waitcnt lgkmcnt(0)
	v_add_f32_e32 v24, v24, v25
	v_fmamk_f32 v38, v24, 0xbc800000, v45
	v_fmamk_f32 v40, v24, 0xbc800000, v43
	v_fmamk_f32 v25, v24, 0xbc800000, v44
	v_fmamk_f32 v39, v24, 0xbc800000, v42
	v_mul_f32_e32 v40, v40, v40
	v_mul_f32_e32 v38, v38, v38
	v_fmac_f32_e32 v40, v39, v39
	v_fmac_f32_e32 v38, v25, v25
	v_fmamk_f32 v39, v24, 0xbc800000, v49
	v_fmamk_f32 v41, v24, 0xbc800000, v47
	v_add_f32_e32 v25, v40, v38
	v_fmamk_f32 v38, v24, 0xbc800000, v48
	v_fmamk_f32 v40, v24, 0xbc800000, v46
	v_mul_f32_e32 v41, v41, v41
	v_mul_f32_e32 v39, v39, v39
	v_fmac_f32_e32 v41, v40, v40
	v_fmac_f32_e32 v39, v38, v38
	v_add_f32_e32 v38, v41, v39
	v_fmamk_f32 v39, v24, 0xbc800000, v53
	v_fmamk_f32 v41, v24, 0xbc800000, v51
	v_add_f32_e32 v25, v25, v38
	v_fmamk_f32 v38, v24, 0xbc800000, v52
	v_fmamk_f32 v40, v24, 0xbc800000, v50
	v_mul_f32_e32 v41, v41, v41
	v_mul_f32_e32 v39, v39, v39
	v_fmac_f32_e32 v41, v40, v40
	v_fmac_f32_e32 v39, v38, v38
	v_add_f32_e32 v38, v41, v39
	v_fmamk_f32 v39, v24, 0xbc800000, v57
	v_fmamk_f32 v41, v24, 0xbc800000, v55
	v_add_f32_e32 v25, v38, v25
	v_fmamk_f32 v38, v24, 0xbc800000, v56
	v_fmamk_f32 v40, v24, 0xbc800000, v54
	v_mul_f32_e32 v41, v41, v41
	v_mul_f32_e32 v39, v39, v39
	v_fmac_f32_e32 v41, v40, v40
	v_fmac_f32_e32 v39, v38, v38
	v_add_f32_e32 v38, v41, v39
	v_add_f32_e32 v25, v38, v25
	v_mov_b32_e32 v38, v25
	s_nop 1
	v_permlane16_swap_b32_e32 v25, v38
	s_nop 0
	s_waitcnt lgkmcnt(0)
	v_add_f32_e32 v25, v25, v38
	v_mov_b32_e32 v38, v25
	s_nop 1
	v_permlane32_swap_b32_e32 v25, v38
	s_nop 0
	s_and_saveexec_b64 s[18:19], vcc
	s_cbranch_execz .LBB0_1245
	s_lshl_b32 s0, s57, 11
	s_add_i32 s0, s20, s0
	v_mul_f32_e32 v24, 0x3c800000, v24
	s_waitcnt lgkmcnt(0)
	v_add_f32_e32 v25, v25, v38
	v_lshl_add_u32 v38, v1, 5, s0
	ds_write_b64 v38, v[24:25] offset:4608
; __device__ __forceinline__ float shfl_lane(float v, int srclane) { return __int_as_float(__builtin_amdgcn_ds_bpermute(srclane << 2, __float_as_int(v))); }
;     __device__ __forceinline__ void fused(AccT& acc, const Unit& u, int wr, int wc, int fr_in, int fq_in, LAS unsigned char* lds, int wid, int lane_in) const {
;     ...
; #pragma unroll
;         for (int ai = 0; ai < 2; ++ai)
; #pragma unroll
;             for (int m = 0; m < 4; ++m) {
;                 float s = 0.f;
; #pragma unroll
;                 for (int bj = 0; bj < 2; ++bj)
; #pragma unroll
;                     for (int n = 0; n < 2; ++n) { const f32x4 x = acc[ai][bj][m][n]; s += (x[0] + x[1]) + (x[2] + x[3]); }
;                 s += shfl_lane(s, lane ^ 16); s += shfl_lane(s, lane ^ 32);
;                 const float mw = s * (1.0f / 64.0f); float q = 0.f;
; #pragma unroll
;                 for (int bj = 0; bj < 2; ++bj)
; #pragma unroll
;                     for (int n = 0; n < 2; ++n) { const f32x4 d = acc[ai][bj][m][n] - mw; q += (d[0] * d[0] + d[1] * d[1]) + (d[2] * d[2] + d[3] * d[3]); }
;                 q += shfl_lane(q, lane ^ 16); q += shfl_lane(q, lane ^ 32);
;                 if (fq == 0) P[(ai * HALF + wr * 64 + m * 16 + fr) * 4 + wc] = (f32x2){mw, q};
;             }
.LBB0_1245:
	s_or_b64 exec, exec, s[18:19]
	v_mov_b32_e32 v24, v27
	v_mov_b32_e32 v25, v28
	s_waitcnt lgkmcnt(0)
	v_mov_b32_e32 v38, v26
	v_mov_b32_e32 v39, v29
	v_pk_add_f32 v[24:25], v[24:25], v[38:39]
	v_mov_b32_e32 v38, v31
	v_mov_b32_e32 v39, v32
	v_mov_b32_e32 v40, v30
	v_mov_b32_e32 v41, v33
	v_pk_add_f32 v[38:39], v[38:39], v[40:41]
	v_add_f32_e32 v24, v24, v25
	v_pk_add_f32 v[38:39], v[38:39], v[38:39] op_sel_hi:[0,1]
	v_add_f32_e32 v25, 0, v24
	v_add_f32_e32 v41, v18, v19
	v_add_f32_e32 v141, v20, v21
	v_mov_b32_e32 v40, v34
	v_mov_b32_e32 v140, v35
	v_mov_b32_e32 v38, v36
	v_mov_b32_e32 v24, v37
	v_pk_add_f32 v[40:41], v[40:41], v[140:141]
	v_pk_add_f32 v[24:25], v[38:39], v[24:25]
	s_nop 0
	v_pk_add_f32 v[24:25], v[40:41], v[24:25]
	s_nop 0
	v_add_f32_e32 v24, v24, v25
	v_mov_b32_e32 v25, v24
	s_nop 1
	v_permlane16_swap_b32_e32 v24, v25
	s_nop 0
	s_waitcnt lgkmcnt(0)
	v_add_f32_e32 v24, v24, v25
	v_mov_b32_e32 v25, v24
	s_nop 1
	v_permlane32_swap_b32_e32 v24, v25
	s_nop 0
	s_waitcnt lgkmcnt(0)
	v_add_f32_e32 v24, v24, v25
	v_fmamk_f32 v38, v24, 0xbc800000, v29
	v_fmamk_f32 v40, v24, 0xbc800000, v27
	v_fmamk_f32 v25, v24, 0xbc800000, v28
	v_fmamk_f32 v39, v24, 0xbc800000, v26
	v_mul_f32_e32 v40, v40, v40
	v_mul_f32_e32 v38, v38, v38
	v_fmac_f32_e32 v40, v39, v39
	v_fmac_f32_e32 v38, v25, v25
	v_fmamk_f32 v39, v24, 0xbc800000, v33
	v_fmamk_f32 v41, v24, 0xbc800000, v31
	v_add_f32_e32 v25, v40, v38
	v_fmamk_f32 v38, v24, 0xbc800000, v32
	v_fmamk_f32 v40, v24, 0xbc800000, v30
	v_mul_f32_e32 v41, v41, v41
	v_mul_f32_e32 v39, v39, v39
	v_fmac_f32_e32 v41, v40, v40
	v_fmac_f32_e32 v39, v38, v38
	v_add_f32_e32 v38, v41, v39
	v_fmamk_f32 v39, v24, 0xbc800000, v21
	v_fmamk_f32 v41, v24, 0xbc800000, v19
	v_add_f32_e32 v25, v25, v38
	v_fmamk_f32 v38, v24, 0xbc800000, v20
	v_fmamk_f32 v40, v24, 0xbc800000, v18
	v_mul_f32_e32 v41, v41, v41
	v_mul_f32_e32 v39, v39, v39
	v_fmac_f32_e32 v41, v40, v40
	v_fmac_f32_e32 v39, v38, v38
	v_add_f32_e32 v38, v41, v39
	v_fmamk_f32 v39, v24, 0xbc800000, v37
	v_fmamk_f32 v41, v24, 0xbc800000, v35
	v_add_f32_e32 v25, v38, v25
	v_fmamk_f32 v38, v24, 0xbc800000, v36
	v_fmamk_f32 v40, v24, 0xbc800000, v34
	v_mul_f32_e32 v41, v41, v41
	v_mul_f32_e32 v39, v39, v39
	v_fmac_f32_e32 v41, v40, v40
	v_fmac_f32_e32 v39, v38, v38
	v_add_f32_e32 v38, v41, v39
	v_add_f32_e32 v25, v38, v25
	v_mov_b32_e32 v38, v25
	s_nop 1
	v_permlane16_swap_b32_e32 v25, v38
	s_nop 0
	s_waitcnt lgkmcnt(0)
	v_add_f32_e32 v25, v25, v38
	v_mov_b32_e32 v38, v25
	s_nop 1
	v_permlane32_swap_b32_e32 v25, v38
	s_nop 0
	s_and_saveexec_b64 s[18:19], vcc
	s_cbranch_execz .LBB0_1247
	s_lshl_b32 s0, s57, 11
	s_add_i32 s0, s20, s0
	v_mul_f32_e32 v24, 0x3c800000, v24
	s_waitcnt lgkmcnt(0)
	v_add_f32_e32 v25, v25, v38
	v_lshl_add_u32 v38, v1, 5, s0
	ds_write_b64 v38, v[24:25] offset:5120
.LBB0_1247:
	s_or_b64 exec, exec, s[18:19]
	v_mov_b32_e32 v24, v11
	v_mov_b32_e32 v25, v12
	s_waitcnt lgkmcnt(0)
	v_mov_b32_e32 v38, v10
	v_mov_b32_e32 v39, v13
	v_pk_add_f32 v[24:25], v[24:25], v[38:39]
	v_mov_b32_e32 v38, v15
	v_mov_b32_e32 v39, v16
	v_mov_b32_e32 v40, v14
	v_mov_b32_e32 v41, v17
	v_pk_add_f32 v[38:39], v[38:39], v[40:41]
	v_add_f32_e32 v24, v24, v25
	v_pk_add_f32 v[38:39], v[38:39], v[38:39] op_sel_hi:[0,1]
	v_add_f32_e32 v25, 0, v24
	v_add_f32_e32 v41, v6, v7
	v_add_f32_e32 v141, v8, v9
	v_mov_b32_e32 v40, v2
	v_mov_b32_e32 v140, v3
	v_mov_b32_e32 v38, v4
	v_mov_b32_e32 v24, v5
	v_pk_add_f32 v[40:41], v[40:41], v[140:141]
	v_pk_add_f32 v[24:25], v[38:39], v[24:25]
	s_nop 0
	v_pk_add_f32 v[24:25], v[40:41], v[24:25]
	s_nop 0
	v_add_f32_e32 v24, v24, v25
	v_mov_b32_e32 v25, v24
	s_nop 1
	v_permlane16_swap_b32_e32 v24, v25
	s_nop 0
	s_waitcnt lgkmcnt(0)
	v_add_f32_e32 v24, v24, v25
	v_mov_b32_e32 v25, v24
	s_nop 1
	v_permlane32_swap_b32_e32 v24, v25
	s_nop 0
	s_waitcnt lgkmcnt(0)
	v_add_f32_e32 v24, v24, v25
	v_fmamk_f32 v38, v24, 0xbc800000, v13
	v_fmamk_f32 v40, v24, 0xbc800000, v11
	v_fmamk_f32 v25, v24, 0xbc800000, v12
	v_fmamk_f32 v39, v24, 0xbc800000, v10
	v_mul_f32_e32 v40, v40, v40
	v_mul_f32_e32 v38, v38, v38
	v_fmac_f32_e32 v40, v39, v39
	v_fmac_f32_e32 v38, v25, v25
	v_fmamk_f32 v39, v24, 0xbc800000, v17
	v_fmamk_f32 v41, v24, 0xbc800000, v15
	v_add_f32_e32 v25, v40, v38
	v_fmamk_f32 v38, v24, 0xbc800000, v16
	v_fmamk_f32 v40, v24, 0xbc800000, v14
	v_mul_f32_e32 v41, v41, v41
	v_mul_f32_e32 v39, v39, v39
	v_fmac_f32_e32 v41, v40, v40
	v_fmac_f32_e32 v39, v38, v38
	v_add_f32_e32 v38, v41, v39
	v_fmamk_f32 v39, v24, 0xbc800000, v9
	v_fmamk_f32 v41, v24, 0xbc800000, v7
	v_add_f32_e32 v25, v25, v38
	v_fmamk_f32 v38, v24, 0xbc800000, v8
	v_fmamk_f32 v40, v24, 0xbc800000, v6
	v_mul_f32_e32 v41, v41, v41
	v_mul_f32_e32 v39, v39, v39
	v_fmac_f32_e32 v41, v40, v40
	v_fmac_f32_e32 v39, v38, v38
	v_add_f32_e32 v38, v41, v39
	v_fmamk_f32 v39, v24, 0xbc800000, v5
	v_fmamk_f32 v41, v24, 0xbc800000, v3
	v_add_f32_e32 v25, v38, v25
	v_fmamk_f32 v38, v24, 0xbc800000, v4
	v_fmamk_f32 v40, v24, 0xbc800000, v2
	v_mul_f32_e32 v41, v41, v41
	v_mul_f32_e32 v39, v39, v39
	v_fmac_f32_e32 v41, v40, v40
	v_fmac_f32_e32 v39, v38, v38
	v_add_f32_e32 v38, v41, v39
	v_add_f32_e32 v25, v38, v25
	v_mov_b32_e32 v22, v25
	s_nop 1
	v_permlane16_swap_b32_e32 v25, v22
	s_nop 0
	s_waitcnt lgkmcnt(0)
	v_add_f32_e32 v22, v25, v22
	v_mov_b32_e32 v23, v22
	s_nop 1
	v_permlane32_swap_b32_e32 v22, v23
	s_nop 0
	s_and_saveexec_b64 s[18:19], vcc
	s_cbranch_execz .LBB0_1249
	s_lshl_b32 s0, s57, 11
	s_add_i32 s20, s20, s0
	v_mul_f32_e32 v24, 0x3c800000, v24
	s_waitcnt lgkmcnt(0)
	v_add_f32_e32 v25, v22, v23
	v_lshl_add_u32 v1, v1, 5, s20
	ds_write_b64 v1, v[24:25] offset:5632

; __host__ __device__ __forceinline__ size_t blk_off(int row, int k, int K, bool perm) {
;     const int r = row & 127, slot = perm ? ((r & ~31) + perm32inv(r & 31)) : r; return ((size_t)(row >> 7) * (K >> 6) + (k >> 6)) * BLK + lds_byte(slot, k & 63); }
;     __device__ __forceinline__ void fused(AccT& acc, const Unit& u, int wr, int wc, int fr_in, int fq_in, LAS unsigned char* lds, int wid, int lane_in) const {
;     ...
;         const int col0 = u.pn * BM + wc * 32 + 8 * fq;
;         {
;             u32x4 xr[2][4][2];
; #pragma unroll
;             for (int ai = 0; ai < 2; ++ai)
; #pragma unroll
;                 for (int m = 0; m < 4; ++m) { const int rowi = u.pm * BM + ai * HALF + wr * 64 + m * 16 + fr;
; #pragma unroll
;                     for (int bj = 0; bj < 2; ++bj) xr[ai][m][bj] = *(const u32x4*)((const char*)XinB + blk_off(rowi, col0 + bj * HALF, D, false)); }
.LBB0_1294:
	s_lshl_b32 s0, s56, 5
	s_lshl_b32 s1, s16, 8
	v_and_b32_e32 v207, 63, v134
	v_bfe_u32 v209, v134, 4, 2
	s_or_b32 s0, s1, s0
	s_waitcnt vmcnt(0)
	s_barrier
	s_lshl_b32 s2, s51, 8
	v_lshl_add_u32 v222, v209, 3, s0
	v_lshlrev_b32_e32 v126, 1, v222
	v_add_u32_e32 v193, s66, v1
	v_and_b32_e32 v145, 48, v126
	v_ashrrev_i32_e32 v126, 6, v222
	v_add_u32_e32 v220, s2, v193
	v_ashrrev_i32_e32 v127, 31, v126
	v_bfe_u32 v144, v222, 5, 1
	v_lshlrev_b64 v[132:133], 14, v[126:127]
	v_ashrrev_i32_e32 v126, 7, v220
	v_lshrrev_b32_e32 v128, 3, v193
	v_ashrrev_i32_e32 v127, 31, v126
	v_and_or_b32 v128, v128, 14, v144
	v_lshlrev_b32_e32 v129, 6, v193
	s_movk_i32 s84, 0x3c0
	v_lshlrev_b32_e32 v130, 2, v193
	v_readlane_b32 s92, v254, 29
	v_add_u32_e32 v134, 0x80, v222
	v_lshlrev_b64 v[126:127], 19, v[126:127]
	v_and_or_b32 v129, v129, s84, v145
	v_lshlrev_b32_e32 v128, 10, v128
	v_and_b32_e32 v130, 32, v130
	v_readlane_b32 s93, v254, 30
	v_ashrrev_i32_e32 v134, 6, v134
	v_bitop3_b32 v130, v129, v128, v130 bitop3:0xde
	v_lshl_add_u64 v[126:127], s[92:93], 0, v[126:127]
	v_ashrrev_i32_e32 v135, 31, v134
	v_lshl_add_u64 v[126:127], v[126:127], 0, v[130:131]
	v_lshlrev_b64 v[134:135], 14, v[134:135]
	v_lshl_add_u64 v[128:129], v[126:127], 0, v[132:133]
	v_lshl_add_u64 v[140:141], v[126:127], 0, v[134:135]
	v_add_u32_e32 v218, 16, v220
	global_load_dwordx4 v[126:129], v[128:129], off
	s_nop 0
	global_load_dwordx4 v[194:197], v[140:141], off
	v_ashrrev_i32_e32 v140, 7, v218
	v_lshrrev_b32_e32 v142, 3, v218
	v_ashrrev_i32_e32 v141, 31, v140
	v_and_or_b32 v142, v142, 14, v144
	v_lshlrev_b32_e32 v143, 6, v218
	v_lshlrev_b32_e32 v146, 2, v218
	v_lshlrev_b64 v[140:141], 19, v[140:141]
	v_and_or_b32 v143, v143, s84, v145
	v_lshlrev_b32_e32 v142, 10, v142
	v_and_b32_e32 v146, 32, v146
	v_bitop3_b32 v142, v143, v142, v146 bitop3:0xde
	v_mov_b32_e32 v143, v131
	v_lshl_add_u64 v[140:141], s[92:93], 0, v[140:141]
	v_lshl_add_u64 v[140:141], v[140:141], 0, v[142:143]
	v_lshl_add_u64 v[142:143], v[140:141], 0, v[132:133]
	v_lshl_add_u64 v[140:141], v[140:141], 0, v[134:135]
	v_add_u32_e32 v216, 32, v220
	global_load_dwordx4 v[236:239], v[142:143], off
	global_load_dwordx4 v[188:191], v[140:141], off
	v_ashrrev_i32_e32 v140, 7, v216
	v_lshrrev_b32_e32 v142, 3, v216
	v_ashrrev_i32_e32 v141, 31, v140
	v_and_or_b32 v142, v142, 14, v144
	v_lshlrev_b32_e32 v143, 6, v216
	v_lshlrev_b32_e32 v146, 2, v216
	v_lshlrev_b64 v[140:141], 19, v[140:141]
	v_and_or_b32 v143, v143, s84, v145
	v_lshlrev_b32_e32 v142, 10, v142
	v_and_b32_e32 v146, 32, v146
	v_bitop3_b32 v142, v143, v142, v146 bitop3:0xde
	v_mov_b32_e32 v143, v131
	v_lshl_add_u64 v[140:141], s[92:93], 0, v[140:141]
	v_lshl_add_u64 v[140:141], v[140:141], 0, v[142:143]
	v_lshl_add_u64 v[142:143], v[140:141], 0, v[132:133]
	v_lshl_add_u64 v[140:141], v[140:141], 0, v[134:135]
	v_add_u32_e32 v214, 48, v220
	global_load_dwordx4 v[184:187], v[142:143], off
	global_load_dwordx4 v[180:183], v[140:141], off
	v_ashrrev_i32_e32 v140, 7, v214
	v_lshrrev_b32_e32 v142, 3, v214
	v_ashrrev_i32_e32 v141, 31, v140
	v_and_or_b32 v142, v142, 14, v144
	v_lshlrev_b32_e32 v143, 6, v214
	v_lshlrev_b32_e32 v146, 2, v214
	v_lshlrev_b64 v[140:141], 19, v[140:141]
	v_and_or_b32 v143, v143, s84, v145
	v_lshlrev_b32_e32 v142, 10, v142
	v_and_b32_e32 v146, 32, v146
	v_bitop3_b32 v142, v143, v142, v146 bitop3:0xde
	v_mov_b32_e32 v143, v131
	v_lshl_add_u64 v[140:141], s[92:93], 0, v[140:141]
	v_lshl_add_u64 v[140:141], v[140:141], 0, v[142:143]
	v_lshl_add_u64 v[142:143], v[140:141], 0, v[132:133]
	v_lshl_add_u64 v[140:141], v[140:141], 0, v[134:135]
	v_add_u32_e32 v212, 0x80, v220
	global_load_dwordx4 v[176:179], v[142:143], off
	global_load_dwordx4 v[172:175], v[140:141], off
	v_ashrrev_i32_e32 v140, 7, v212
	v_ashrrev_i32_e32 v141, 31, v140
	v_lshlrev_b64 v[140:141], 19, v[140:141]
	v_lshl_add_u64 v[140:141], s[92:93], 0, v[140:141]
	v_lshl_add_u64 v[140:141], v[140:141], 0, v[130:131]
	v_lshl_add_u64 v[142:143], v[140:141], 0, v[132:133]
	v_lshl_add_u64 v[140:141], v[140:141], 0, v[134:135]
	v_add_u32_e32 v210, 0x90, v220
	global_load_dwordx4 v[168:171], v[142:143], off
	global_load_dwordx4 v[164:167], v[140:141], off
	v_ashrrev_i32_e32 v140, 7, v210
	v_lshrrev_b32_e32 v130, 3, v210
	v_ashrrev_i32_e32 v141, 31, v140
	v_and_or_b32 v130, v130, 14, v144
	v_lshlrev_b32_e32 v142, 6, v210
	v_lshlrev_b32_e32 v143, 2, v210
	v_lshlrev_b64 v[140:141], 19, v[140:141]
	v_and_or_b32 v142, v142, s84, v145
	v_lshlrev_b32_e32 v130, 10, v130
	v_and_b32_e32 v143, 32, v143
	v_bitop3_b32 v130, v142, v130, v143 bitop3:0xde
	v_lshl_add_u64 v[140:141], s[92:93], 0, v[140:141]
	v_lshl_add_u64 v[140:141], v[140:141], 0, v[130:131]
	v_lshl_add_u64 v[142:143], v[140:141], 0, v[132:133]
	v_lshl_add_u64 v[140:141], v[140:141], 0, v[134:135]
	v_add_u32_e32 v208, 0xa0, v220
	global_load_dwordx4 v[160:163], v[142:143], off
	global_load_dwordx4 v[156:159], v[140:141], off
	v_ashrrev_i32_e32 v140, 7, v208
	v_lshrrev_b32_e32 v130, 3, v208
	v_ashrrev_i32_e32 v141, 31, v140
	v_and_or_b32 v130, v130, 14, v144
	v_lshlrev_b32_e32 v142, 6, v208
	v_lshlrev_b32_e32 v143, 2, v208
	v_lshlrev_b64 v[140:141], 19, v[140:141]
	v_and_or_b32 v142, v142, s84, v145
	v_lshlrev_b32_e32 v130, 10, v130
	v_and_b32_e32 v143, 32, v143
	v_bitop3_b32 v130, v142, v130, v143 bitop3:0xde
	v_lshl_add_u64 v[140:141], s[92:93], 0, v[140:141]
	v_lshl_add_u64 v[140:141], v[140:141], 0, v[130:131]
	v_lshl_add_u64 v[142:143], v[140:141], 0, v[132:133]
	v_lshl_add_u64 v[140:141], v[140:141], 0, v[134:135]
	v_add_u32_e32 v206, 0xb0, v220
	global_load_dwordx4 v[152:155], v[142:143], off
	global_load_dwordx4 v[148:151], v[140:141], off
	v_ashrrev_i32_e32 v140, 7, v206
	v_lshrrev_b32_e32 v130, 3, v206
	v_ashrrev_i32_e32 v141, 31, v140
	v_and_or_b32 v130, v130, 14, v144
	v_lshlrev_b32_e32 v142, 6, v206
	v_lshlrev_b32_e32 v143, 2, v206
	v_lshlrev_b64 v[140:141], 19, v[140:141]
	v_and_or_b32 v142, v142, s84, v145
	v_lshlrev_b32_e32 v130, 10, v130
	v_and_b32_e32 v143, 32, v143
	v_bitop3_b32 v130, v142, v130, v143 bitop3:0xde
	v_lshl_add_u64 v[140:141], s[92:93], 0, v[140:141]
	v_lshl_add_u64 v[140:141], v[140:141], 0, v[130:131]
	v_lshl_add_u64 v[132:133], v[140:141], 0, v[132:133]
	v_lshl_add_u64 v[134:135], v[140:141], 0, v[134:135]
	global_load_dwordx4 v[144:147], v[132:133], off
	global_load_dwordx4 v[140:143], v[134:135], off
	s_waitcnt vmcnt(0)
; __device__ __forceinline__ float bflo(unsigned w) { return __uint_as_float(w << 16); }
; __device__ __forceinline__ float bfhi(unsigned w) { return __uint_as_float(w & 0xffff0000u); }
;     __device__ __forceinline__ void fused(AccT& acc, const Unit& u, int wr, int wc, int fr_in, int fq_in, LAS unsigned char* lds, int wid, int lane_in) const {
;     ...
; #pragma unroll
;             for (int ai = 0; ai < 2; ++ai)
; #pragma unroll
;                 for (int m = 0; m < 4; ++m)
; #pragma unroll
;                     for (int bj = 0; bj < 2; ++bj) { const u32x4 w = xr[ai][m][bj];
;                         acc[ai][bj][m][0] += (f32x4){bflo(w.x), bfhi(w.x), bflo(w.y), bfhi(w.y)} * alpha; acc[ai][bj][m][1] += (f32x4){bflo(w.z), bfhi(w.z), bflo(w.w), bfhi(w.w)} * alpha;
;                         asm volatile("" : "+v"(acc[ai][bj][m][0]), "+v"(acc[ai][bj][m][1])); }
	v_lshlrev_b32_e32 v132, 16, v126
	v_and_b32_e32 v133, 0xffff0000, v126
	v_lshlrev_b32_e32 v126, 16, v127
	v_and_b32_e32 v127, 0xffff0000, v127
	s_mov_b32 s0, 0x3fd744fd
	v_pk_fma_f32 v[134:135], v[126:127], s[0:1], v[120:121] op_sel_hi:[1,0,1]
	v_pk_fma_f32 v[132:133], v[132:133], s[0:1], v[118:119] op_sel_hi:[1,0,1]
	v_lshlrev_b32_e32 v118, 16, v128
	v_and_b32_e32 v119, 0xffff0000, v128
	v_lshlrev_b32_e32 v120, 16, v129
	v_and_b32_e32 v121, 0xffff0000, v129
	v_pk_fma_f32 v[128:129], v[120:121], s[0:1], v[116:117] op_sel_hi:[1,0,1]
	v_pk_fma_f32 v[126:127], v[118:119], s[0:1], v[114:115] op_sel_hi:[1,0,1]
	v_lshlrev_b32_e32 v114, 16, v194
	v_and_b32_e32 v115, 0xffff0000, v194
	v_lshlrev_b32_e32 v116, 16, v195
	v_and_b32_e32 v117, 0xffff0000, v195
	v_pk_fma_f32 v[120:121], v[116:117], s[0:1], v[100:101] op_sel_hi:[1,0,1]
	v_pk_fma_f32 v[118:119], v[114:115], s[0:1], v[98:99] op_sel_hi:[1,0,1]
	v_lshlrev_b32_e32 v98, 16, v196
	v_and_b32_e32 v99, 0xffff0000, v196
	v_lshlrev_b32_e32 v100, 16, v197
	v_and_b32_e32 v101, 0xffff0000, v197
	v_pk_fma_f32 v[116:117], v[100:101], s[0:1], v[84:85] op_sel_hi:[1,0,1]
	v_pk_fma_f32 v[114:115], v[98:99], s[0:1], v[82:83] op_sel_hi:[1,0,1]
	v_lshlrev_b32_e32 v98, 16, v238
	v_and_b32_e32 v99, 0xffff0000, v238
	v_lshlrev_b32_e32 v100, 16, v239
	v_and_b32_e32 v101, 0xffff0000, v239
	v_pk_fma_f32 v[88:89], v[100:101], s[0:1], v[88:89] op_sel_hi:[1,0,1]
	v_pk_fma_f32 v[86:87], v[98:99], s[0:1], v[86:87] op_sel_hi:[1,0,1]
	v_lshlrev_b32_e32 v98, 16, v188
	v_and_b32_e32 v99, 0xffff0000, v188
	v_lshlrev_b32_e32 v100, 16, v189
	v_and_b32_e32 v101, 0xffff0000, v189
	v_pk_fma_f32 v[92:93], v[100:101], s[0:1], v[92:93] op_sel_hi:[1,0,1]
	v_pk_fma_f32 v[90:91], v[98:99], s[0:1], v[90:91] op_sel_hi:[1,0,1]
	v_lshlrev_b32_e32 v98, 16, v190
	v_and_b32_e32 v99, 0xffff0000, v190
	v_lshlrev_b32_e32 v100, 16, v191
	v_and_b32_e32 v101, 0xffff0000, v191
	v_pk_fma_f32 v[100:101], v[100:101], s[0:1], v[96:97] op_sel_hi:[1,0,1]
	v_pk_fma_f32 v[98:99], v[98:99], s[0:1], v[94:95] op_sel_hi:[1,0,1]
	v_lshlrev_b32_e32 v94, 16, v184
	v_and_b32_e32 v95, 0xffff0000, v184
	v_lshlrev_b32_e32 v96, 16, v185
	v_and_b32_e32 v97, 0xffff0000, v185
	v_pk_fma_f32 v[96:97], v[96:97], s[0:1], v[112:113] op_sel_hi:[1,0,1]
	v_pk_fma_f32 v[94:95], v[94:95], s[0:1], v[110:111] op_sel_hi:[1,0,1]
	v_lshlrev_b32_e32 v110, 16, v186
	v_and_b32_e32 v111, 0xffff0000, v186
	v_lshlrev_b32_e32 v112, 16, v187
	v_and_b32_e32 v113, 0xffff0000, v187
	v_pk_fma_f32 v[104:105], v[112:113], s[0:1], v[104:105] op_sel_hi:[1,0,1]
	v_pk_fma_f32 v[102:103], v[110:111], s[0:1], v[102:103] op_sel_hi:[1,0,1]
	v_lshlrev_b32_e32 v110, 16, v180
	v_and_b32_e32 v111, 0xffff0000, v180
	v_lshlrev_b32_e32 v112, 16, v181
	v_and_b32_e32 v113, 0xffff0000, v181
	v_pk_fma_f32 v[108:109], v[112:113], s[0:1], v[108:109] op_sel_hi:[1,0,1]
	v_pk_fma_f32 v[106:107], v[110:111], s[0:1], v[106:107] op_sel_hi:[1,0,1]
	v_lshlrev_b32_e32 v110, 16, v182
	v_and_b32_e32 v111, 0xffff0000, v182
	v_lshlrev_b32_e32 v112, 16, v183
	v_and_b32_e32 v113, 0xffff0000, v183
	v_pk_fma_f32 v[112:113], v[112:113], s[0:1], v[76:77] op_sel_hi:[1,0,1]
	v_pk_fma_f32 v[110:111], v[110:111], s[0:1], v[74:75] op_sel_hi:[1,0,1]
	v_lshlrev_b32_e32 v74, 16, v176
	v_and_b32_e32 v75, 0xffff0000, v176
	v_lshlrev_b32_e32 v76, 16, v177
	v_and_b32_e32 v77, 0xffff0000, v177
	v_pk_fma_f32 v[76:77], v[76:77], s[0:1], v[124:125] op_sel_hi:[1,0,1]
	v_pk_fma_f32 v[74:75], v[74:75], s[0:1], v[122:123] op_sel_hi:[1,0,1]
	v_lshlrev_b32_e32 v122, 16, v178
	v_and_b32_e32 v123, 0xffff0000, v178
	v_lshlrev_b32_e32 v124, 16, v179
	v_and_b32_e32 v125, 0xffff0000, v179
	v_pk_fma_f32 v[80:81], v[124:125], s[0:1], v[80:81] op_sel_hi:[1,0,1]
	v_pk_fma_f32 v[78:79], v[122:123], s[0:1], v[78:79] op_sel_hi:[1,0,1]
	v_lshlrev_b32_e32 v122, 16, v172
	v_and_b32_e32 v123, 0xffff0000, v172
	v_lshlrev_b32_e32 v124, 16, v173
	v_and_b32_e32 v125, 0xffff0000, v173
	v_pk_fma_f32 v[72:73], v[124:125], s[0:1], v[72:73] op_sel_hi:[1,0,1]
	v_pk_fma_f32 v[70:71], v[122:123], s[0:1], v[70:71] op_sel_hi:[1,0,1]
	v_lshlrev_b32_e32 v122, 16, v174
	v_and_b32_e32 v123, 0xffff0000, v174
	v_lshlrev_b32_e32 v124, 16, v175
	v_and_b32_e32 v125, 0xffff0000, v175
	v_pk_fma_f32 v[68:69], v[124:125], s[0:1], v[68:69] op_sel_hi:[1,0,1]
	v_pk_fma_f32 v[66:67], v[122:123], s[0:1], v[66:67] op_sel_hi:[1,0,1]
	v_lshlrev_b32_e32 v122, 16, v168
	v_and_b32_e32 v123, 0xffff0000, v168
	v_lshlrev_b32_e32 v124, 16, v169
	v_and_b32_e32 v125, 0xffff0000, v169
	v_pk_fma_f32 v[64:65], v[124:125], s[0:1], v[64:65] op_sel_hi:[1,0,1]
	v_pk_fma_f32 v[62:63], v[122:123], s[0:1], v[62:63] op_sel_hi:[1,0,1]
	v_lshlrev_b32_e32 v122, 16, v170
	v_and_b32_e32 v123, 0xffff0000, v170
	v_lshlrev_b32_e32 v124, 16, v171
	v_and_b32_e32 v125, 0xffff0000, v171
	v_pk_fma_f32 v[60:61], v[124:125], s[0:1], v[60:61] op_sel_hi:[1,0,1]
	v_pk_fma_f32 v[58:59], v[122:123], s[0:1], v[58:59] op_sel_hi:[1,0,1]
	v_lshlrev_b32_e32 v122, 16, v164
	v_and_b32_e32 v123, 0xffff0000, v164
	v_lshlrev_b32_e32 v124, 16, v165
	v_and_b32_e32 v125, 0xffff0000, v165
	v_pk_fma_f32 v[52:53], v[124:125], s[0:1], v[52:53] op_sel_hi:[1,0,1]
	v_pk_fma_f32 v[50:51], v[122:123], s[0:1], v[50:51] op_sel_hi:[1,0,1]
	v_lshlrev_b32_e32 v122, 16, v166
	v_and_b32_e32 v123, 0xffff0000, v166
	v_lshlrev_b32_e32 v124, 16, v167
	v_and_b32_e32 v125, 0xffff0000, v167
	v_pk_fma_f32 v[124:125], v[124:125], s[0:1], v[44:45] op_sel_hi:[1,0,1]
	v_pk_fma_f32 v[122:123], v[122:123], s[0:1], v[42:43] op_sel_hi:[1,0,1]
	v_lshlrev_b32_e32 v42, 16, v160
	v_and_b32_e32 v43, 0xffff0000, v160
	v_lshlrev_b32_e32 v44, 16, v161
	v_and_b32_e32 v45, 0xffff0000, v161
; __device__ __forceinline__ float bflo(unsigned w) { return __uint_as_float(w << 16); }
; __device__ __forceinline__ float bfhi(unsigned w) { return __uint_as_float(w & 0xffff0000u); }
; __device__ __forceinline__ float shfl_lane(float v, int srclane) { return __int_as_float(__builtin_amdgcn_ds_bpermute(srclane << 2, __float_as_int(v))); }
;     __device__ __forceinline__ void fused(AccT& acc, const Unit& u, int wr, int wc, int fr_in, int fq_in, LAS unsigned char* lds, int wid, int lane_in) const {
;     ...
; #pragma unroll
;             for (int ai = 0; ai < 2; ++ai)
; #pragma unroll
;                 for (int m = 0; m < 4; ++m)
; #pragma unroll
;                     for (int bj = 0; bj < 2; ++bj) { const u32x4 w = xr[ai][m][bj];
;                         acc[ai][bj][m][0] += (f32x4){bflo(w.x), bfhi(w.x), bflo(w.y), bfhi(w.y)} * alpha; acc[ai][bj][m][1] += (f32x4){bflo(w.z), bfhi(w.z), bflo(w.w), bfhi(w.w)} * alpha;
;                         asm volatile("" : "+v"(acc[ai][bj][m][0]), "+v"(acc[ai][bj][m][1])); }
;             asm volatile("" ::: "memory");
;         }
; #pragma unroll
;         for (int ai = 0; ai < 2; ++ai)
; #pragma unroll
;             for (int m = 0; m < 4; ++m) {
;                 float s = 0.f;
; #pragma unroll
;                 for (int bj = 0; bj < 2; ++bj)
; #pragma unroll
;                     for (int n = 0; n < 2; ++n) { const f32x4 x = acc[ai][bj][m][n]; s += (x[0] + x[1]) + (x[2] + x[3]); }
;                 s += shfl_lane(s, lane ^ 16); s += shfl_lane(s, lane ^ 32);
;                 const float mw = s * (1.0f / 64.0f); float q = 0.f;
; #pragma unroll
;                 for (int bj = 0; bj < 2; ++bj)
; #pragma unroll
;                     for (int n = 0; n < 2; ++n) { const f32x4 d = acc[ai][bj][m][n] - mw; q += (d[0] * d[0] + d[1] * d[1]) + (d[2] * d[2] + d[3] * d[3]); }
;                 q += shfl_lane(q, lane ^ 16); q += shfl_lane(q, lane ^ 32);
;                 if (fq == 0) P[(ai * HALF + wr * 64 + m * 16 + fr) * 4 + wc] = (f32x2){mw, q};
;             }
	v_pk_fma_f32 v[44:45], v[44:45], s[0:1], v[56:57] op_sel_hi:[1,0,1]
	v_pk_fma_f32 v[42:43], v[42:43], s[0:1], v[54:55] op_sel_hi:[1,0,1]
	v_lshlrev_b32_e32 v54, 16, v162
	v_and_b32_e32 v55, 0xffff0000, v162
	v_lshlrev_b32_e32 v56, 16, v163
	v_and_b32_e32 v57, 0xffff0000, v163
	v_pk_fma_f32 v[48:49], v[56:57], s[0:1], v[48:49] op_sel_hi:[1,0,1]
	v_pk_fma_f32 v[46:47], v[54:55], s[0:1], v[46:47] op_sel_hi:[1,0,1]
	v_lshlrev_b32_e32 v54, 16, v156
	v_and_b32_e32 v55, 0xffff0000, v156
	v_lshlrev_b32_e32 v56, 16, v157
	v_and_b32_e32 v57, 0xffff0000, v157
	v_pk_fma_f32 v[36:37], v[56:57], s[0:1], v[36:37] op_sel_hi:[1,0,1]
	v_pk_fma_f32 v[34:35], v[54:55], s[0:1], v[34:35] op_sel_hi:[1,0,1]
	v_lshlrev_b32_e32 v54, 16, v158
	v_and_b32_e32 v55, 0xffff0000, v158
	v_lshlrev_b32_e32 v56, 16, v159
	v_and_b32_e32 v57, 0xffff0000, v159
	v_pk_fma_f32 v[56:57], v[56:57], s[0:1], v[28:29] op_sel_hi:[1,0,1]
	v_pk_fma_f32 v[54:55], v[54:55], s[0:1], v[26:27] op_sel_hi:[1,0,1]
	v_lshlrev_b32_e32 v26, 16, v152
	v_and_b32_e32 v27, 0xffff0000, v152
	v_lshlrev_b32_e32 v28, 16, v153
	v_and_b32_e32 v29, 0xffff0000, v153
	v_pk_fma_f32 v[28:29], v[28:29], s[0:1], v[40:41] op_sel_hi:[1,0,1]
	v_pk_fma_f32 v[26:27], v[26:27], s[0:1], v[38:39] op_sel_hi:[1,0,1]
	v_lshlrev_b32_e32 v38, 16, v154
	v_and_b32_e32 v39, 0xffff0000, v154
	v_lshlrev_b32_e32 v40, 16, v155
	v_and_b32_e32 v41, 0xffff0000, v155
	v_lshlrev_b32_e32 v82, 16, v236
	v_and_b32_e32 v83, 0xffff0000, v236
	v_lshlrev_b32_e32 v84, 16, v237
	v_and_b32_e32 v85, 0xffff0000, v237
	v_pk_fma_f32 v[32:33], v[40:41], s[0:1], v[32:33] op_sel_hi:[1,0,1]
	v_pk_fma_f32 v[30:31], v[38:39], s[0:1], v[30:31] op_sel_hi:[1,0,1]
	v_lshlrev_b32_e32 v38, 16, v148
	v_and_b32_e32 v39, 0xffff0000, v148
	v_lshlrev_b32_e32 v40, 16, v149
	v_and_b32_e32 v41, 0xffff0000, v149
	v_pk_fma_f32 v[84:85], v[84:85], s[0:1], v[138:139] op_sel_hi:[1,0,1]
	v_pk_fma_f32 v[82:83], v[82:83], s[0:1], v[136:137] op_sel_hi:[1,0,1]
	v_pk_fma_f32 v[20:21], v[40:41], s[0:1], v[20:21] op_sel_hi:[1,0,1]
	v_pk_fma_f32 v[18:19], v[38:39], s[0:1], v[18:19] op_sel_hi:[1,0,1]
	v_lshlrev_b32_e32 v38, 16, v150
	v_and_b32_e32 v39, 0xffff0000, v150
	v_lshlrev_b32_e32 v40, 16, v151
	v_and_b32_e32 v41, 0xffff0000, v151
	v_mov_b32_e32 v136, v133
	v_mov_b32_e32 v137, v134
	v_mov_b32_e32 v138, v132
	v_mov_b32_e32 v139, v135
	v_pk_fma_f32 v[40:41], v[40:41], s[0:1], v[12:13] op_sel_hi:[1,0,1]
	v_pk_fma_f32 v[38:39], v[38:39], s[0:1], v[10:11] op_sel_hi:[1,0,1]
	v_lshlrev_b32_e32 v10, 16, v144
	v_and_b32_e32 v11, 0xffff0000, v144
	v_lshlrev_b32_e32 v12, 16, v145
	v_and_b32_e32 v13, 0xffff0000, v145
	v_pk_add_f32 v[136:137], v[136:137], v[138:139]
	v_mov_b32_e32 v138, v127
	v_mov_b32_e32 v139, v128
	v_mov_b32_e32 v144, v126
	v_mov_b32_e32 v145, v129
	v_pk_add_f32 v[138:139], v[138:139], v[144:145]
	v_add_f32_e32 v130, v136, v137
	v_pk_add_f32 v[138:139], v[138:139], v[138:139] op_sel_hi:[0,1]
	v_pk_fma_f32 v[12:13], v[12:13], s[0:1], v[24:25] op_sel_hi:[1,0,1]
	v_pk_fma_f32 v[10:11], v[10:11], s[0:1], v[22:23] op_sel_hi:[1,0,1]
	v_lshlrev_b32_e32 v22, 16, v146
	v_and_b32_e32 v23, 0xffff0000, v146
	v_lshlrev_b32_e32 v24, 16, v147
	v_and_b32_e32 v25, 0xffff0000, v147
	v_add_f32_e32 v137, 0, v130
	v_add_f32_e32 v145, v118, v119
	v_add_f32_e32 v147, v120, v121
	v_mov_b32_e32 v144, v114
	v_mov_b32_e32 v146, v115
	v_mov_b32_e32 v138, v116
	v_mov_b32_e32 v136, v117
	v_pk_add_f32 v[144:145], v[144:145], v[146:147]
	v_pk_add_f32 v[136:137], v[138:139], v[136:137]
	v_pk_fma_f32 v[14:15], v[22:23], s[0:1], v[14:15] op_sel_hi:[1,0,1]
	v_lshlrev_b32_e32 v23, 2, v207
	v_pk_add_f32 v[136:137], v[144:145], v[136:137]
	v_xor_b32_e32 v22, 64, v23
	v_add_f32_e32 v130, v136, v137
	v_mov_b32_e32 v138, v130
	s_nop 1
	v_permlane16_swap_b32_e32 v130, v138
	s_nop 0
	v_xor_b32_e32 v23, 0x80, v23
	v_pk_fma_f32 v[16:17], v[24:25], s[0:1], v[16:17] op_sel_hi:[1,0,1]
	v_lshlrev_b32_e32 v24, 16, v140
	v_and_b32_e32 v25, 0xffff0000, v140
	s_waitcnt lgkmcnt(0)
	v_add_f32_e32 v130, v130, v138
	v_mov_b32_e32 v139, v130
	s_nop 1
	v_permlane32_swap_b32_e32 v130, v139
	s_nop 0
	v_pk_fma_f32 v[6:7], v[24:25], s[0:1], v[6:7] op_sel_hi:[1,0,1]
	v_lshlrev_b32_e32 v136, 16, v141
	v_and_b32_e32 v137, 0xffff0000, v141
	v_pk_fma_f32 v[8:9], v[136:137], s[0:1], v[8:9] op_sel_hi:[1,0,1]
	s_waitcnt lgkmcnt(0)
	v_add_f32_e32 v24, v130, v139
	v_fmamk_f32 v130, v24, 0xbc800000, v135
	v_fmamk_f32 v140, v24, 0xbc800000, v133
	v_fmamk_f32 v25, v24, 0xbc800000, v134
	v_fmamk_f32 v139, v24, 0xbc800000, v132
	v_mul_f32_e32 v140, v140, v140
	v_mul_f32_e32 v130, v130, v130
	v_fmac_f32_e32 v140, v139, v139
	v_fmac_f32_e32 v130, v25, v25
	v_fmamk_f32 v139, v24, 0xbc800000, v129
	v_fmamk_f32 v141, v24, 0xbc800000, v127
	v_add_f32_e32 v25, v140, v130
	v_fmamk_f32 v130, v24, 0xbc800000, v128
	v_fmamk_f32 v140, v24, 0xbc800000, v126
	v_mul_f32_e32 v141, v141, v141
	v_mul_f32_e32 v139, v139, v139
	v_fmac_f32_e32 v141, v140, v140
	v_fmac_f32_e32 v139, v130, v130
	v_add_f32_e32 v130, v141, v139
	v_fmamk_f32 v139, v24, 0xbc800000, v121
	v_fmamk_f32 v141, v24, 0xbc800000, v119
	v_add_f32_e32 v25, v25, v130
	v_fmamk_f32 v130, v24, 0xbc800000, v120
	v_fmamk_f32 v140, v24, 0xbc800000, v118
	v_mul_f32_e32 v141, v141, v141
	v_mul_f32_e32 v139, v139, v139
	v_fmac_f32_e32 v141, v140, v140
	v_fmac_f32_e32 v139, v130, v130
	v_add_f32_e32 v130, v141, v139
	v_fmamk_f32 v139, v24, 0xbc800000, v117
	v_fmamk_f32 v141, v24, 0xbc800000, v115
	v_add_f32_e32 v25, v130, v25
	v_fmamk_f32 v130, v24, 0xbc800000, v116
	v_fmamk_f32 v140, v24, 0xbc800000, v114
	v_mul_f32_e32 v141, v141, v141
	v_mul_f32_e32 v139, v139, v139
	v_fmac_f32_e32 v141, v140, v140
	v_fmac_f32_e32 v139, v130, v130
	v_add_f32_e32 v130, v141, v139
	v_add_f32_e32 v25, v130, v25
	v_mov_b32_e32 v130, v25
	s_nop 1
	v_permlane16_swap_b32_e32 v25, v130
	s_nop 0
	v_lshlrev_b32_e32 v136, 16, v142
	v_and_b32_e32 v137, 0xffff0000, v142
	v_lshlrev_b32_e32 v138, 16, v143
	v_and_b32_e32 v139, 0xffff0000, v143
	s_waitcnt lgkmcnt(0)
	v_add_f32_e32 v25, v25, v130
	v_mov_b32_e32 v130, v25
	s_nop 1
	v_permlane32_swap_b32_e32 v25, v130
	s_nop 0
	v_pk_fma_f32 v[4:5], v[138:139], s[0:1], v[4:5] op_sel_hi:[1,0,1]
	v_pk_fma_f32 v[2:3], v[136:137], s[0:1], v[2:3] op_sel_hi:[1,0,1]
	s_nop 0
	s_lshl_b32 s0, s56, 3
	v_cmp_eq_u32_e32 vcc, 0, v209
	s_add_i32 s20, s0, 0
	s_and_saveexec_b64 s[18:19], vcc
	s_cbranch_execz .LBB0_1296
	s_lshl_b32 s0, s55, 11
	s_add_i32 s0, s20, s0
	v_mul_f32_e32 v24, 0x3c800000, v24
	s_waitcnt lgkmcnt(0)
	v_add_f32_e32 v25, v25, v130
	v_lshl_add_u32 v130, v1, 5, s0
	ds_write_b64 v130, v[24:25]
; __device__ __forceinline__ float shfl_lane(float v, int srclane) { return __int_as_float(__builtin_amdgcn_ds_bpermute(srclane << 2, __float_as_int(v))); }
;     __device__ __forceinline__ void fused(AccT& acc, const Unit& u, int wr, int wc, int fr_in, int fq_in, LAS unsigned char* lds, int wid, int lane_in) const {
;     ...
; #pragma unroll
;         for (int ai = 0; ai < 2; ++ai)
; #pragma unroll
;             for (int m = 0; m < 4; ++m) {
;                 float s = 0.f;
; #pragma unroll
;                 for (int bj = 0; bj < 2; ++bj)
; #pragma unroll
;                     for (int n = 0; n < 2; ++n) { const f32x4 x = acc[ai][bj][m][n]; s += (x[0] + x[1]) + (x[2] + x[3]); }
;                 s += shfl_lane(s, lane ^ 16); s += shfl_lane(s, lane ^ 32);
;                 const float mw = s * (1.0f / 64.0f); float q = 0.f;
; #pragma unroll
;                 for (int bj = 0; bj < 2; ++bj)
; #pragma unroll
;                     for (int n = 0; n < 2; ++n) { const f32x4 d = acc[ai][bj][m][n] - mw; q += (d[0] * d[0] + d[1] * d[1]) + (d[2] * d[2] + d[3] * d[3]); }
;                 q += shfl_lane(q, lane ^ 16); q += shfl_lane(q, lane ^ 32);
;                 if (fq == 0) P[(ai * HALF + wr * 64 + m * 16 + fr) * 4 + wc] = (f32x2){mw, q};
;             }
.LBB0_1296:
	s_or_b64 exec, exec, s[18:19]
	v_mov_b32_e32 v24, v83
	v_mov_b32_e32 v25, v84
	v_mov_b32_e32 v136, v82
	v_mov_b32_e32 v137, v85
	v_pk_add_f32 v[24:25], v[24:25], v[136:137]
	v_mov_b32_e32 v136, v87
	v_mov_b32_e32 v137, v88
	v_mov_b32_e32 v138, v86
	v_mov_b32_e32 v139, v89
	v_pk_add_f32 v[136:137], v[136:137], v[138:139]
	v_add_f32_e32 v24, v24, v25
	v_pk_add_f32 v[136:137], v[136:137], v[136:137] op_sel_hi:[0,1]
	v_add_f32_e32 v25, 0, v24
	v_add_f32_e32 v139, v90, v91
	v_add_f32_e32 v141, v92, v93
	v_mov_b32_e32 v138, v98
	v_mov_b32_e32 v140, v99
	v_mov_b32_e32 v136, v100
	v_mov_b32_e32 v24, v101
	v_pk_add_f32 v[138:139], v[138:139], v[140:141]
	v_pk_add_f32 v[24:25], v[136:137], v[24:25]
	s_nop 0
	v_pk_add_f32 v[24:25], v[138:139], v[24:25]
	s_nop 0
	v_add_f32_e32 v24, v24, v25
	v_mov_b32_e32 v25, v24
	s_nop 1
	v_permlane16_swap_b32_e32 v24, v25
	s_nop 0
	s_waitcnt lgkmcnt(0)
	v_add_f32_e32 v24, v24, v25
	v_mov_b32_e32 v25, v24
	s_nop 1
	v_permlane32_swap_b32_e32 v24, v25
	s_nop 0
	s_waitcnt lgkmcnt(0)
	v_add_f32_e32 v24, v24, v25
	v_fmamk_f32 v130, v24, 0xbc800000, v85
	v_fmamk_f32 v137, v24, 0xbc800000, v83
	v_fmamk_f32 v25, v24, 0xbc800000, v84
	v_fmamk_f32 v136, v24, 0xbc800000, v82
	v_mul_f32_e32 v137, v137, v137
	v_mul_f32_e32 v130, v130, v130
	v_fmac_f32_e32 v137, v136, v136
	v_fmac_f32_e32 v130, v25, v25
	v_fmamk_f32 v136, v24, 0xbc800000, v89
	v_fmamk_f32 v138, v24, 0xbc800000, v87
	v_add_f32_e32 v25, v137, v130
	v_fmamk_f32 v130, v24, 0xbc800000, v88
	v_fmamk_f32 v137, v24, 0xbc800000, v86
	v_mul_f32_e32 v138, v138, v138
	v_mul_f32_e32 v136, v136, v136
	v_fmac_f32_e32 v138, v137, v137
	v_fmac_f32_e32 v136, v130, v130
	v_add_f32_e32 v130, v138, v136
	v_fmamk_f32 v136, v24, 0xbc800000, v93
	v_fmamk_f32 v138, v24, 0xbc800000, v91
	v_add_f32_e32 v25, v25, v130
	v_fmamk_f32 v130, v24, 0xbc800000, v92
	v_fmamk_f32 v137, v24, 0xbc800000, v90
	v_mul_f32_e32 v138, v138, v138
	v_mul_f32_e32 v136, v136, v136
	v_fmac_f32_e32 v138, v137, v137
	v_fmac_f32_e32 v136, v130, v130
	v_add_f32_e32 v130, v138, v136
	v_fmamk_f32 v136, v24, 0xbc800000, v101
	v_fmamk_f32 v138, v24, 0xbc800000, v99
	v_add_f32_e32 v25, v130, v25
	v_fmamk_f32 v130, v24, 0xbc800000, v100
	v_fmamk_f32 v137, v24, 0xbc800000, v98
	v_mul_f32_e32 v138, v138, v138
	v_mul_f32_e32 v136, v136, v136
	v_fmac_f32_e32 v138, v137, v137
	v_fmac_f32_e32 v136, v130, v130
	v_add_f32_e32 v130, v138, v136
	v_add_f32_e32 v25, v130, v25
	v_mov_b32_e32 v130, v25
	s_nop 1
	v_permlane16_swap_b32_e32 v25, v130
	s_nop 0
	s_waitcnt lgkmcnt(0)
	v_add_f32_e32 v25, v25, v130
	v_mov_b32_e32 v130, v25
	s_nop 1
	v_permlane32_swap_b32_e32 v25, v130
	s_nop 0
	s_and_saveexec_b64 s[18:19], vcc
	v_readlane_b32 s26, v254, 38
	v_readlane_b32 s27, v254, 39
	v_readlane_b32 s85, v255, 6
	s_cbranch_execz .LBB0_1298
	s_lshl_b32 s0, s55, 11
	s_add_i32 s0, s20, s0
	v_mul_f32_e32 v24, 0x3c800000, v24
	s_waitcnt lgkmcnt(0)
	v_add_f32_e32 v25, v25, v130
	v_lshl_add_u32 v130, v1, 5, s0
	ds_write_b64 v130, v[24:25] offset:512
.LBB0_1298:
	s_or_b64 exec, exec, s[18:19]
	v_mov_b32_e32 v24, v95
	v_mov_b32_e32 v25, v96
	v_mov_b32_e32 v136, v94
	v_mov_b32_e32 v137, v97
	v_pk_add_f32 v[24:25], v[24:25], v[136:137]
	v_mov_b32_e32 v136, v103
	v_mov_b32_e32 v137, v104
	v_mov_b32_e32 v138, v102
	v_mov_b32_e32 v139, v105
	v_pk_add_f32 v[136:137], v[136:137], v[138:139]
	v_add_f32_e32 v24, v24, v25
	v_pk_add_f32 v[136:137], v[136:137], v[136:137] op_sel_hi:[0,1]
	v_add_f32_e32 v25, 0, v24
	v_add_f32_e32 v139, v106, v107
	v_add_f32_e32 v141, v108, v109
	v_mov_b32_e32 v138, v110
	v_mov_b32_e32 v140, v111
	v_mov_b32_e32 v136, v112
	v_mov_b32_e32 v24, v113
	v_pk_add_f32 v[138:139], v[138:139], v[140:141]
	v_pk_add_f32 v[24:25], v[136:137], v[24:25]
	s_nop 0
	v_pk_add_f32 v[24:25], v[138:139], v[24:25]
	s_nop 0
	v_add_f32_e32 v24, v24, v25
	v_mov_b32_e32 v25, v24
	s_nop 1
	v_permlane16_swap_b32_e32 v24, v25
	s_nop 0
	s_waitcnt lgkmcnt(0)
	v_add_f32_e32 v24, v24, v25
	v_mov_b32_e32 v25, v24
	s_nop 1
	v_permlane32_swap_b32_e32 v24, v25
	s_nop 0
	s_waitcnt lgkmcnt(0)
	v_add_f32_e32 v24, v24, v25
	v_fmamk_f32 v130, v24, 0xbc800000, v97
	v_fmamk_f32 v137, v24, 0xbc800000, v95
	v_fmamk_f32 v25, v24, 0xbc800000, v96
	v_fmamk_f32 v136, v24, 0xbc800000, v94
	v_mul_f32_e32 v137, v137, v137
	v_mul_f32_e32 v130, v130, v130
	v_fmac_f32_e32 v137, v136, v136
	v_fmac_f32_e32 v130, v25, v25
	v_fmamk_f32 v136, v24, 0xbc800000, v105
	v_fmamk_f32 v138, v24, 0xbc800000, v103
	v_add_f32_e32 v25, v137, v130
	v_fmamk_f32 v130, v24, 0xbc800000, v104
	v_fmamk_f32 v137, v24, 0xbc800000, v102
	v_mul_f32_e32 v138, v138, v138
	v_mul_f32_e32 v136, v136, v136
	v_fmac_f32_e32 v138, v137, v137
	v_fmac_f32_e32 v136, v130, v130
	v_add_f32_e32 v130, v138, v136
	v_fmamk_f32 v136, v24, 0xbc800000, v109
	v_fmamk_f32 v138, v24, 0xbc800000, v107
	v_add_f32_e32 v25, v25, v130
	v_fmamk_f32 v130, v24, 0xbc800000, v108
	v_fmamk_f32 v137, v24, 0xbc800000, v106
	v_mul_f32_e32 v138, v138, v138
	v_mul_f32_e32 v136, v136, v136
	v_fmac_f32_e32 v138, v137, v137
	v_fmac_f32_e32 v136, v130, v130
	v_add_f32_e32 v130, v138, v136
	v_fmamk_f32 v136, v24, 0xbc800000, v113
	v_fmamk_f32 v138, v24, 0xbc800000, v111
	v_add_f32_e32 v25, v130, v25
	v_fmamk_f32 v130, v24, 0xbc800000, v112
	v_fmamk_f32 v137, v24, 0xbc800000, v110
	v_mul_f32_e32 v138, v138, v138
	v_mul_f32_e32 v136, v136, v136
	v_fmac_f32_e32 v138, v137, v137
	v_fmac_f32_e32 v136, v130, v130
	v_add_f32_e32 v130, v138, v136
	v_add_f32_e32 v25, v130, v25
	v_mov_b32_e32 v130, v25
	s_nop 1
	v_permlane16_swap_b32_e32 v25, v130
	s_nop 0
	s_waitcnt lgkmcnt(0)
	v_add_f32_e32 v25, v25, v130
	v_mov_b32_e32 v130, v25
	s_nop 1
	v_permlane32_swap_b32_e32 v25, v130
	s_nop 0
	s_and_saveexec_b64 s[18:19], vcc
	s_cbranch_execz .LBB0_1300
	s_lshl_b32 s0, s55, 11
	s_add_i32 s0, s20, s0
	v_mul_f32_e32 v24, 0x3c800000, v24
	s_waitcnt lgkmcnt(0)
	v_add_f32_e32 v25, v25, v130
	v_lshl_add_u32 v130, v1, 5, s0
	ds_write_b64 v130, v[24:25] offset:1024
; __device__ __forceinline__ float shfl_lane(float v, int srclane) { return __int_as_float(__builtin_amdgcn_ds_bpermute(srclane << 2, __float_as_int(v))); }
;     __device__ __forceinline__ void fused(AccT& acc, const Unit& u, int wr, int wc, int fr_in, int fq_in, LAS unsigned char* lds, int wid, int lane_in) const {
;     ...
; #pragma unroll
;         for (int ai = 0; ai < 2; ++ai)
; #pragma unroll
;             for (int m = 0; m < 4; ++m) {
;                 float s = 0.f;
; #pragma unroll
;                 for (int bj = 0; bj < 2; ++bj)
; #pragma unroll
;                     for (int n = 0; n < 2; ++n) { const f32x4 x = acc[ai][bj][m][n]; s += (x[0] + x[1]) + (x[2] + x[3]); }
;                 s += shfl_lane(s, lane ^ 16); s += shfl_lane(s, lane ^ 32);
;                 const float mw = s * (1.0f / 64.0f); float q = 0.f;
; #pragma unroll
;                 for (int bj = 0; bj < 2; ++bj)
; #pragma unroll
;                     for (int n = 0; n < 2; ++n) { const f32x4 d = acc[ai][bj][m][n] - mw; q += (d[0] * d[0] + d[1] * d[1]) + (d[2] * d[2] + d[3] * d[3]); }
;                 q += shfl_lane(q, lane ^ 16); q += shfl_lane(q, lane ^ 32);
;                 if (fq == 0) P[(ai * HALF + wr * 64 + m * 16 + fr) * 4 + wc] = (f32x2){mw, q};
;             }
.LBB0_1300:
	s_or_b64 exec, exec, s[18:19]
	v_mov_b32_e32 v24, v75
	v_mov_b32_e32 v25, v76
	v_mov_b32_e32 v136, v74
	v_mov_b32_e32 v137, v77
	v_pk_add_f32 v[24:25], v[24:25], v[136:137]
	v_mov_b32_e32 v136, v79
	v_mov_b32_e32 v137, v80
	v_mov_b32_e32 v138, v78
	v_mov_b32_e32 v139, v81
	v_pk_add_f32 v[136:137], v[136:137], v[138:139]
	v_add_f32_e32 v24, v24, v25
	v_pk_add_f32 v[136:137], v[136:137], v[136:137] op_sel_hi:[0,1]
	v_add_f32_e32 v25, 0, v24
	v_add_f32_e32 v139, v70, v71
	v_add_f32_e32 v141, v72, v73
	v_mov_b32_e32 v138, v66
	v_mov_b32_e32 v140, v67
	v_mov_b32_e32 v136, v68
	v_mov_b32_e32 v24, v69
	v_pk_add_f32 v[138:139], v[138:139], v[140:141]
	v_pk_add_f32 v[24:25], v[136:137], v[24:25]
	s_nop 0
	v_pk_add_f32 v[24:25], v[138:139], v[24:25]
	s_nop 0
	v_add_f32_e32 v24, v24, v25
	v_mov_b32_e32 v25, v24
	s_nop 1
	v_permlane16_swap_b32_e32 v24, v25
	s_nop 0
	s_waitcnt lgkmcnt(0)
	v_add_f32_e32 v24, v24, v25
	v_mov_b32_e32 v25, v24
	s_nop 1
	v_permlane32_swap_b32_e32 v24, v25
	s_nop 0
	s_waitcnt lgkmcnt(0)
	v_add_f32_e32 v24, v24, v25
	v_fmamk_f32 v130, v24, 0xbc800000, v77
	v_fmamk_f32 v137, v24, 0xbc800000, v75
	v_fmamk_f32 v25, v24, 0xbc800000, v76
	v_fmamk_f32 v136, v24, 0xbc800000, v74
	v_mul_f32_e32 v137, v137, v137
	v_mul_f32_e32 v130, v130, v130
	v_fmac_f32_e32 v137, v136, v136
	v_fmac_f32_e32 v130, v25, v25
	v_fmamk_f32 v136, v24, 0xbc800000, v81
	v_fmamk_f32 v138, v24, 0xbc800000, v79
	v_add_f32_e32 v25, v137, v130
	v_fmamk_f32 v130, v24, 0xbc800000, v80
	v_fmamk_f32 v137, v24, 0xbc800000, v78
	v_mul_f32_e32 v138, v138, v138
	v_mul_f32_e32 v136, v136, v136
	v_fmac_f32_e32 v138, v137, v137
	v_fmac_f32_e32 v136, v130, v130
	v_add_f32_e32 v130, v138, v136
	v_fmamk_f32 v136, v24, 0xbc800000, v73
	v_fmamk_f32 v138, v24, 0xbc800000, v71
	v_add_f32_e32 v25, v25, v130
	v_fmamk_f32 v130, v24, 0xbc800000, v72
	v_fmamk_f32 v137, v24, 0xbc800000, v70
	v_mul_f32_e32 v138, v138, v138
	v_mul_f32_e32 v136, v136, v136
	v_fmac_f32_e32 v138, v137, v137
	v_fmac_f32_e32 v136, v130, v130
	v_add_f32_e32 v130, v138, v136
	v_fmamk_f32 v136, v24, 0xbc800000, v69
	v_fmamk_f32 v138, v24, 0xbc800000, v67
	v_add_f32_e32 v25, v130, v25
	v_fmamk_f32 v130, v24, 0xbc800000, v68
	v_fmamk_f32 v137, v24, 0xbc800000, v66
	v_mul_f32_e32 v138, v138, v138
	v_mul_f32_e32 v136, v136, v136
	v_fmac_f32_e32 v138, v137, v137
	v_fmac_f32_e32 v136, v130, v130
	v_add_f32_e32 v130, v138, v136
	v_add_f32_e32 v25, v130, v25
	v_mov_b32_e32 v130, v25
	s_nop 1
	v_permlane16_swap_b32_e32 v25, v130
	s_nop 0
	s_waitcnt lgkmcnt(0)
	v_add_f32_e32 v25, v25, v130
	v_mov_b32_e32 v130, v25
	s_nop 1
	v_permlane32_swap_b32_e32 v25, v130
	s_nop 0
	s_and_saveexec_b64 s[18:19], vcc
	s_cbranch_execz .LBB0_1302
	s_lshl_b32 s0, s55, 11
	s_add_i32 s0, s20, s0
	v_mul_f32_e32 v24, 0x3c800000, v24
	s_waitcnt lgkmcnt(0)
	v_add_f32_e32 v25, v25, v130
	v_lshl_add_u32 v130, v1, 5, s0
	ds_write_b64 v130, v[24:25] offset:1536
.LBB0_1302:
	s_or_b64 exec, exec, s[18:19]
	v_mov_b32_e32 v24, v63
	v_mov_b32_e32 v25, v64
	v_mov_b32_e32 v136, v62
	v_mov_b32_e32 v137, v65
	v_pk_add_f32 v[24:25], v[24:25], v[136:137]
	v_mov_b32_e32 v136, v59
	v_mov_b32_e32 v137, v60
	v_mov_b32_e32 v138, v58
	v_mov_b32_e32 v139, v61
	v_pk_add_f32 v[136:137], v[136:137], v[138:139]
	v_add_f32_e32 v24, v24, v25
	v_pk_add_f32 v[136:137], v[136:137], v[136:137] op_sel_hi:[0,1]
	v_add_f32_e32 v25, 0, v24
	v_add_f32_e32 v139, v50, v51
	v_add_f32_e32 v141, v52, v53
	v_mov_b32_e32 v138, v122
	v_mov_b32_e32 v140, v123
	v_mov_b32_e32 v136, v124
	v_mov_b32_e32 v24, v125
	v_pk_add_f32 v[138:139], v[138:139], v[140:141]
	v_pk_add_f32 v[24:25], v[136:137], v[24:25]
	s_nop 0
	v_pk_add_f32 v[24:25], v[138:139], v[24:25]
	s_nop 0
	v_add_f32_e32 v24, v24, v25
	v_mov_b32_e32 v25, v24
	s_nop 1
	v_permlane16_swap_b32_e32 v24, v25
	s_nop 0
	s_waitcnt lgkmcnt(0)
	v_add_f32_e32 v24, v24, v25
	v_mov_b32_e32 v25, v24
	s_nop 1
	v_permlane32_swap_b32_e32 v24, v25
	s_nop 0
	s_waitcnt lgkmcnt(0)
	v_add_f32_e32 v24, v24, v25
	v_fmamk_f32 v130, v24, 0xbc800000, v65
	v_fmamk_f32 v137, v24, 0xbc800000, v63
	v_fmamk_f32 v25, v24, 0xbc800000, v64
	v_fmamk_f32 v136, v24, 0xbc800000, v62
	v_mul_f32_e32 v137, v137, v137
	v_mul_f32_e32 v130, v130, v130
	v_fmac_f32_e32 v137, v136, v136
	v_fmac_f32_e32 v130, v25, v25
	v_fmamk_f32 v136, v24, 0xbc800000, v61
	v_fmamk_f32 v138, v24, 0xbc800000, v59
	v_add_f32_e32 v25, v137, v130
	v_fmamk_f32 v130, v24, 0xbc800000, v60
	v_fmamk_f32 v137, v24, 0xbc800000, v58
	v_mul_f32_e32 v138, v138, v138
	v_mul_f32_e32 v136, v136, v136
	v_fmac_f32_e32 v138, v137, v137
	v_fmac_f32_e32 v136, v130, v130
	v_add_f32_e32 v130, v138, v136
	v_fmamk_f32 v136, v24, 0xbc800000, v53
	v_fmamk_f32 v138, v24, 0xbc800000, v51
	v_add_f32_e32 v25, v25, v130
	v_fmamk_f32 v130, v24, 0xbc800000, v52
	v_fmamk_f32 v137, v24, 0xbc800000, v50
	v_mul_f32_e32 v138, v138, v138
	v_mul_f32_e32 v136, v136, v136
	v_fmac_f32_e32 v138, v137, v137
	v_fmac_f32_e32 v136, v130, v130
	v_add_f32_e32 v130, v138, v136
	v_fmamk_f32 v136, v24, 0xbc800000, v125
	v_fmamk_f32 v138, v24, 0xbc800000, v123
	v_add_f32_e32 v25, v130, v25
	v_fmamk_f32 v130, v24, 0xbc800000, v124
	v_fmamk_f32 v137, v24, 0xbc800000, v122
	v_mul_f32_e32 v138, v138, v138
	v_mul_f32_e32 v136, v136, v136
	v_fmac_f32_e32 v138, v137, v137
	v_fmac_f32_e32 v136, v130, v130
	v_add_f32_e32 v130, v138, v136
	v_add_f32_e32 v25, v130, v25
	v_mov_b32_e32 v130, v25
	s_nop 1
	v_permlane16_swap_b32_e32 v25, v130
	s_nop 0
	s_waitcnt lgkmcnt(0)
	v_add_f32_e32 v25, v25, v130
	v_mov_b32_e32 v130, v25
	s_nop 1
	v_permlane32_swap_b32_e32 v25, v130
	s_nop 0
	s_and_saveexec_b64 s[18:19], vcc
	s_cbranch_execz .LBB0_1304
	s_lshl_b32 s0, s55, 11
	s_add_i32 s0, s20, s0
	v_mul_f32_e32 v24, 0x3c800000, v24
	s_waitcnt lgkmcnt(0)
	v_add_f32_e32 v25, v25, v130
	v_lshl_add_u32 v130, v1, 5, s0
	ds_write_b64 v130, v[24:25] offset:4096
; __device__ __forceinline__ float shfl_lane(float v, int srclane) { return __int_as_float(__builtin_amdgcn_ds_bpermute(srclane << 2, __float_as_int(v))); }
;     __device__ __forceinline__ void fused(AccT& acc, const Unit& u, int wr, int wc, int fr_in, int fq_in, LAS unsigned char* lds, int wid, int lane_in) const {
;     ...
; #pragma unroll
;         for (int ai = 0; ai < 2; ++ai)
; #pragma unroll
;             for (int m = 0; m < 4; ++m) {
;                 float s = 0.f;
; #pragma unroll
;                 for (int bj = 0; bj < 2; ++bj)
; #pragma unroll
;                     for (int n = 0; n < 2; ++n) { const f32x4 x = acc[ai][bj][m][n]; s += (x[0] + x[1]) + (x[2] + x[3]); }
;                 s += shfl_lane(s, lane ^ 16); s += shfl_lane(s, lane ^ 32);
;                 const float mw = s * (1.0f / 64.0f); float q = 0.f;
; #pragma unroll
;                 for (int bj = 0; bj < 2; ++bj)
; #pragma unroll
;                     for (int n = 0; n < 2; ++n) { const f32x4 d = acc[ai][bj][m][n] - mw; q += (d[0] * d[0] + d[1] * d[1]) + (d[2] * d[2] + d[3] * d[3]); }
;                 q += shfl_lane(q, lane ^ 16); q += shfl_lane(q, lane ^ 32);
;                 if (fq == 0) P[(ai * HALF + wr * 64 + m * 16 + fr) * 4 + wc] = (f32x2){mw, q};
;             }
.LBB0_1304:
	s_or_b64 exec, exec, s[18:19]
	v_mov_b32_e32 v24, v43
	v_mov_b32_e32 v25, v44
	v_mov_b32_e32 v136, v42
	v_mov_b32_e32 v137, v45
	v_pk_add_f32 v[24:25], v[24:25], v[136:137]
	v_mov_b32_e32 v136, v47
	v_mov_b32_e32 v137, v48
	v_mov_b32_e32 v138, v46
	v_mov_b32_e32 v139, v49
	v_pk_add_f32 v[136:137], v[136:137], v[138:139]
	v_add_f32_e32 v24, v24, v25
	v_pk_add_f32 v[136:137], v[136:137], v[136:137] op_sel_hi:[0,1]
	v_add_f32_e32 v25, 0, v24
	v_add_f32_e32 v139, v34, v35
	v_add_f32_e32 v141, v36, v37
	v_mov_b32_e32 v138, v54
	v_mov_b32_e32 v140, v55
	v_mov_b32_e32 v136, v56
	v_mov_b32_e32 v24, v57
	v_pk_add_f32 v[138:139], v[138:139], v[140:141]
	v_pk_add_f32 v[24:25], v[136:137], v[24:25]
	s_nop 0
	v_pk_add_f32 v[24:25], v[138:139], v[24:25]
	s_nop 0
	v_add_f32_e32 v24, v24, v25
	v_mov_b32_e32 v25, v24
	s_nop 1
	v_permlane16_swap_b32_e32 v24, v25
	s_nop 0
	s_waitcnt lgkmcnt(0)
	v_add_f32_e32 v24, v24, v25
	v_mov_b32_e32 v25, v24
	s_nop 1
	v_permlane32_swap_b32_e32 v24, v25
	s_nop 0
	s_waitcnt lgkmcnt(0)
	v_add_f32_e32 v24, v24, v25
	v_fmamk_f32 v130, v24, 0xbc800000, v45
	v_fmamk_f32 v137, v24, 0xbc800000, v43
	v_fmamk_f32 v25, v24, 0xbc800000, v44
	v_fmamk_f32 v136, v24, 0xbc800000, v42
	v_mul_f32_e32 v137, v137, v137
	v_mul_f32_e32 v130, v130, v130
	v_fmac_f32_e32 v137, v136, v136
	v_fmac_f32_e32 v130, v25, v25
	v_fmamk_f32 v136, v24, 0xbc800000, v49
	v_fmamk_f32 v138, v24, 0xbc800000, v47
	v_add_f32_e32 v25, v137, v130
	v_fmamk_f32 v130, v24, 0xbc800000, v48
	v_fmamk_f32 v137, v24, 0xbc800000, v46
	v_mul_f32_e32 v138, v138, v138
	v_mul_f32_e32 v136, v136, v136
	v_fmac_f32_e32 v138, v137, v137
	v_fmac_f32_e32 v136, v130, v130
	v_add_f32_e32 v130, v138, v136
	v_fmamk_f32 v136, v24, 0xbc800000, v37
	v_fmamk_f32 v138, v24, 0xbc800000, v35
	v_add_f32_e32 v25, v25, v130
	v_fmamk_f32 v130, v24, 0xbc800000, v36
	v_fmamk_f32 v137, v24, 0xbc800000, v34
	v_mul_f32_e32 v138, v138, v138
	v_mul_f32_e32 v136, v136, v136
	v_fmac_f32_e32 v138, v137, v137
	v_fmac_f32_e32 v136, v130, v130
	v_add_f32_e32 v130, v138, v136
	v_fmamk_f32 v136, v24, 0xbc800000, v57
	v_fmamk_f32 v138, v24, 0xbc800000, v55
	v_add_f32_e32 v25, v130, v25
	v_fmamk_f32 v130, v24, 0xbc800000, v56
	v_fmamk_f32 v137, v24, 0xbc800000, v54
	v_mul_f32_e32 v138, v138, v138
	v_mul_f32_e32 v136, v136, v136
	v_fmac_f32_e32 v138, v137, v137
	v_fmac_f32_e32 v136, v130, v130
	v_add_f32_e32 v130, v138, v136
	v_add_f32_e32 v25, v130, v25
	v_mov_b32_e32 v130, v25
	s_nop 1
	v_permlane16_swap_b32_e32 v25, v130
	s_nop 0
	s_waitcnt lgkmcnt(0)
	v_add_f32_e32 v25, v25, v130
	v_mov_b32_e32 v130, v25
	s_nop 1
	v_permlane32_swap_b32_e32 v25, v130
	s_nop 0
	s_and_saveexec_b64 s[18:19], vcc
	s_cbranch_execz .LBB0_1306
	s_lshl_b32 s0, s55, 11
	s_add_i32 s0, s20, s0
	v_mul_f32_e32 v24, 0x3c800000, v24
	s_waitcnt lgkmcnt(0)
	v_add_f32_e32 v25, v25, v130
	v_lshl_add_u32 v130, v1, 5, s0
	ds_write_b64 v130, v[24:25] offset:4608
; __device__ __forceinline__ float shfl_lane(float v, int srclane) { return __int_as_float(__builtin_amdgcn_ds_bpermute(srclane << 2, __float_as_int(v))); }
;     __device__ __forceinline__ void fused(AccT& acc, const Unit& u, int wr, int wc, int fr_in, int fq_in, LAS unsigned char* lds, int wid, int lane_in) const {
;     ...
; #pragma unroll
;         for (int ai = 0; ai < 2; ++ai)
; #pragma unroll
;             for (int m = 0; m < 4; ++m) {
;                 float s = 0.f;
; #pragma unroll
;                 for (int bj = 0; bj < 2; ++bj)
; #pragma unroll
;                     for (int n = 0; n < 2; ++n) { const f32x4 x = acc[ai][bj][m][n]; s += (x[0] + x[1]) + (x[2] + x[3]); }
;                 s += shfl_lane(s, lane ^ 16); s += shfl_lane(s, lane ^ 32);
;                 const float mw = s * (1.0f / 64.0f); float q = 0.f;
; #pragma unroll
;                 for (int bj = 0; bj < 2; ++bj)
; #pragma unroll
;                     for (int n = 0; n < 2; ++n) { const f32x4 d = acc[ai][bj][m][n] - mw; q += (d[0] * d[0] + d[1] * d[1]) + (d[2] * d[2] + d[3] * d[3]); }
;                 q += shfl_lane(q, lane ^ 16); q += shfl_lane(q, lane ^ 32);
;                 if (fq == 0) P[(ai * HALF + wr * 64 + m * 16 + fr) * 4 + wc] = (f32x2){mw, q};
;             }
.LBB0_1306:
	s_or_b64 exec, exec, s[18:19]
	v_mov_b32_e32 v24, v27
	v_mov_b32_e32 v25, v28
	v_mov_b32_e32 v136, v26
	v_mov_b32_e32 v137, v29
	v_pk_add_f32 v[24:25], v[24:25], v[136:137]
	v_mov_b32_e32 v136, v31
	v_mov_b32_e32 v137, v32
	v_mov_b32_e32 v138, v30
	v_mov_b32_e32 v139, v33
	v_pk_add_f32 v[136:137], v[136:137], v[138:139]
	v_add_f32_e32 v24, v24, v25
	v_pk_add_f32 v[136:137], v[136:137], v[136:137] op_sel_hi:[0,1]
	v_add_f32_e32 v25, 0, v24
	v_add_f32_e32 v139, v18, v19
	v_add_f32_e32 v141, v20, v21
	v_mov_b32_e32 v138, v38
	v_mov_b32_e32 v140, v39
	v_mov_b32_e32 v136, v40
	v_mov_b32_e32 v24, v41
	v_pk_add_f32 v[138:139], v[138:139], v[140:141]
	v_pk_add_f32 v[24:25], v[136:137], v[24:25]
	s_nop 0
	v_pk_add_f32 v[24:25], v[138:139], v[24:25]
	s_nop 0
	v_add_f32_e32 v24, v24, v25
	v_mov_b32_e32 v25, v24
	s_nop 1
	v_permlane16_swap_b32_e32 v24, v25
	s_nop 0
	s_waitcnt lgkmcnt(0)
	v_add_f32_e32 v24, v24, v25
	v_mov_b32_e32 v25, v24
	s_nop 1
	v_permlane32_swap_b32_e32 v24, v25
	s_nop 0
	s_waitcnt lgkmcnt(0)
	v_add_f32_e32 v24, v24, v25
	v_fmamk_f32 v130, v24, 0xbc800000, v29
	v_fmamk_f32 v137, v24, 0xbc800000, v27
	v_fmamk_f32 v25, v24, 0xbc800000, v28
	v_fmamk_f32 v136, v24, 0xbc800000, v26
	v_mul_f32_e32 v137, v137, v137
	v_mul_f32_e32 v130, v130, v130
	v_fmac_f32_e32 v137, v136, v136
	v_fmac_f32_e32 v130, v25, v25
	v_fmamk_f32 v136, v24, 0xbc800000, v33
	v_fmamk_f32 v138, v24, 0xbc800000, v31
	v_add_f32_e32 v25, v137, v130
	v_fmamk_f32 v130, v24, 0xbc800000, v32
	v_fmamk_f32 v137, v24, 0xbc800000, v30
	v_mul_f32_e32 v138, v138, v138
	v_mul_f32_e32 v136, v136, v136
	v_fmac_f32_e32 v138, v137, v137
	v_fmac_f32_e32 v136, v130, v130
	v_add_f32_e32 v130, v138, v136
	v_fmamk_f32 v136, v24, 0xbc800000, v21
	v_fmamk_f32 v138, v24, 0xbc800000, v19
	v_add_f32_e32 v25, v25, v130
	v_fmamk_f32 v130, v24, 0xbc800000, v20
	v_fmamk_f32 v137, v24, 0xbc800000, v18
	v_mul_f32_e32 v138, v138, v138
	v_mul_f32_e32 v136, v136, v136
	v_fmac_f32_e32 v138, v137, v137
	v_fmac_f32_e32 v136, v130, v130
	v_add_f32_e32 v130, v138, v136
	v_fmamk_f32 v136, v24, 0xbc800000, v41
	v_fmamk_f32 v138, v24, 0xbc800000, v39
	v_add_f32_e32 v25, v130, v25
	v_fmamk_f32 v130, v24, 0xbc800000, v40
	v_fmamk_f32 v137, v24, 0xbc800000, v38
	v_mul_f32_e32 v138, v138, v138
	v_mul_f32_e32 v136, v136, v136
	v_fmac_f32_e32 v138, v137, v137
	v_fmac_f32_e32 v136, v130, v130
	v_add_f32_e32 v130, v138, v136
	v_add_f32_e32 v25, v130, v25
	v_mov_b32_e32 v130, v25
	s_nop 1
	v_permlane16_swap_b32_e32 v25, v130
	s_nop 0
	s_waitcnt lgkmcnt(0)
	v_add_f32_e32 v25, v25, v130
	v_mov_b32_e32 v130, v25
	s_nop 1
	v_permlane32_swap_b32_e32 v25, v130
	s_nop 0
	s_and_saveexec_b64 s[18:19], vcc
	s_cbranch_execz .LBB0_1308
	s_lshl_b32 s0, s55, 11
	s_add_i32 s0, s20, s0
	v_mul_f32_e32 v24, 0x3c800000, v24
	s_waitcnt lgkmcnt(0)
	v_add_f32_e32 v25, v25, v130
	v_lshl_add_u32 v130, v1, 5, s0
	ds_write_b64 v130, v[24:25] offset:5120
.LBB0_1308:
	s_or_b64 exec, exec, s[18:19]
	v_mov_b32_e32 v24, v11
	v_mov_b32_e32 v25, v12
	v_mov_b32_e32 v136, v10
	v_mov_b32_e32 v137, v13
	v_pk_add_f32 v[24:25], v[24:25], v[136:137]
	v_mov_b32_e32 v136, v15
	v_mov_b32_e32 v137, v16
	v_mov_b32_e32 v138, v14
	v_mov_b32_e32 v139, v17
	v_pk_add_f32 v[136:137], v[136:137], v[138:139]
	v_add_f32_e32 v24, v24, v25
	v_pk_add_f32 v[136:137], v[136:137], v[136:137] op_sel_hi:[0,1]
	v_add_f32_e32 v25, 0, v24
	v_add_f32_e32 v139, v6, v7
	v_add_f32_e32 v141, v8, v9
	v_mov_b32_e32 v138, v2
	v_mov_b32_e32 v140, v3
	v_mov_b32_e32 v136, v4
	v_mov_b32_e32 v24, v5
	v_pk_add_f32 v[138:139], v[138:139], v[140:141]
	v_pk_add_f32 v[24:25], v[136:137], v[24:25]
	s_nop 0
	v_pk_add_f32 v[24:25], v[138:139], v[24:25]
	s_nop 0
	v_add_f32_e32 v24, v24, v25
	v_mov_b32_e32 v25, v24
	s_nop 1
	v_permlane16_swap_b32_e32 v24, v25
	s_nop 0
	s_waitcnt lgkmcnt(0)
	v_add_f32_e32 v24, v24, v25
	v_mov_b32_e32 v25, v24
	s_nop 1
	v_permlane32_swap_b32_e32 v24, v25
	s_nop 0
	s_waitcnt lgkmcnt(0)
	v_add_f32_e32 v24, v24, v25
	v_fmamk_f32 v130, v24, 0xbc800000, v13
	v_fmamk_f32 v137, v24, 0xbc800000, v11
	v_fmamk_f32 v25, v24, 0xbc800000, v12
	v_fmamk_f32 v136, v24, 0xbc800000, v10
	v_mul_f32_e32 v137, v137, v137
	v_mul_f32_e32 v130, v130, v130
	v_fmac_f32_e32 v137, v136, v136
	v_fmac_f32_e32 v130, v25, v25
	v_fmamk_f32 v136, v24, 0xbc800000, v17
	v_fmamk_f32 v138, v24, 0xbc800000, v15
	v_add_f32_e32 v25, v137, v130
	v_fmamk_f32 v130, v24, 0xbc800000, v16
	v_fmamk_f32 v137, v24, 0xbc800000, v14
	v_mul_f32_e32 v138, v138, v138
	v_mul_f32_e32 v136, v136, v136
	v_fmac_f32_e32 v138, v137, v137
	v_fmac_f32_e32 v136, v130, v130
	v_add_f32_e32 v130, v138, v136
	v_fmamk_f32 v136, v24, 0xbc800000, v9
	v_fmamk_f32 v138, v24, 0xbc800000, v7
	v_add_f32_e32 v25, v25, v130
	v_fmamk_f32 v130, v24, 0xbc800000, v8
	v_fmamk_f32 v137, v24, 0xbc800000, v6
	v_mul_f32_e32 v138, v138, v138
	v_mul_f32_e32 v136, v136, v136
	v_fmac_f32_e32 v138, v137, v137
	v_fmac_f32_e32 v136, v130, v130
	v_add_f32_e32 v130, v138, v136
	v_fmamk_f32 v136, v24, 0xbc800000, v5
	v_fmamk_f32 v138, v24, 0xbc800000, v3
	v_add_f32_e32 v25, v130, v25
	v_fmamk_f32 v130, v24, 0xbc800000, v4
	v_fmamk_f32 v137, v24, 0xbc800000, v2
	v_mul_f32_e32 v138, v138, v138
	v_mul_f32_e32 v136, v136, v136
	v_fmac_f32_e32 v138, v137, v137
	v_fmac_f32_e32 v136, v130, v130
	v_add_f32_e32 v130, v138, v136
	v_add_f32_e32 v25, v130, v25
	v_mov_b32_e32 v22, v25
	s_nop 1
	v_permlane16_swap_b32_e32 v25, v22
	s_nop 0
	s_waitcnt lgkmcnt(0)
	v_add_f32_e32 v22, v25, v22
	v_mov_b32_e32 v23, v22
	s_nop 1
	v_permlane32_swap_b32_e32 v22, v23
	s_nop 0
	s_and_saveexec_b64 s[18:19], vcc
	s_cbranch_execz .LBB0_1310
	s_lshl_b32 s0, s55, 11
	s_add_i32 s20, s20, s0
	v_mul_f32_e32 v24, 0x3c800000, v24
	s_waitcnt lgkmcnt(0)
	v_add_f32_e32 v25, v22, v23
	v_lshl_add_u32 v1, v1, 5, s20
	ds_write_b64 v1, v[24:25] offset:5632
